# all: EpiY hoist + peel + no setprio + saddr DMA + deferred dequeue wait + prologue batch + slim log
# speedup vs baseline: 1.0130x; 1.0036x over previous
.LBB0_80:
	s_add_u32 s2, s14, 0x100
	v_mov_b32_e32 v0, 0
	s_addc_u32 s8, s15, 0
	s_mov_b32 s9, -2
	v_mov_b32_e32 v1, v0
	v_mov_b32_e32 v2, v0
	v_mov_b32_e32 v3, v0
	v_mov_b32_e32 v6, v0
	s_waitcnt lgkmcnt(0)
	v_mov_b32_e32 v7, v0
	v_mov_b32_e32 v8, v0
	v_mov_b32_e32 v9, v0
	v_mov_b32_e32 v18, v0
	v_mov_b32_e32 v19, v0
	v_mov_b32_e32 v20, v0
	v_mov_b32_e32 v21, v0
	v_mov_b32_e32 v22, v0
	v_mov_b32_e32 v23, v0
	v_mov_b32_e32 v24, v0
	v_mov_b32_e32 v25, v0
	v_mov_b32_e32 v34, v0
	v_mov_b32_e32 v35, v0
	v_mov_b32_e32 v36, v0
	v_mov_b32_e32 v37, v0
	v_mov_b32_e32 v38, v0
	v_mov_b32_e32 v39, v0
	v_mov_b32_e32 v40, v0
	v_mov_b32_e32 v41, v0
	v_mov_b32_e32 v50, v0
	v_mov_b32_e32 v51, v0
	v_mov_b32_e32 v52, v0
	v_mov_b32_e32 v53, v0
	v_mov_b32_e32 v54, v0
	v_mov_b32_e32 v55, v0
	v_mov_b32_e32 v56, v0
	v_mov_b32_e32 v57, v0
	v_mov_b32_e32 v10, v0
	v_mov_b32_e32 v11, v0
	v_mov_b32_e32 v12, v0
	v_mov_b32_e32 v13, v0
	v_mov_b32_e32 v14, v0
	v_mov_b32_e32 v15, v0
	v_mov_b32_e32 v16, v0
	v_mov_b32_e32 v17, v0
	v_mov_b32_e32 v26, v0
	v_mov_b32_e32 v27, v0
	v_mov_b32_e32 v28, v0
	v_mov_b32_e32 v29, v0
	v_mov_b32_e32 v30, v0
	v_mov_b32_e32 v31, v0
	v_mov_b32_e32 v32, v0
	v_mov_b32_e32 v33, v0
	v_mov_b32_e32 v42, v0
	v_mov_b32_e32 v43, v0
	v_mov_b32_e32 v44, v0
	v_mov_b32_e32 v45, v0
	v_mov_b32_e32 v46, v0
	v_mov_b32_e32 v47, v0
	v_mov_b32_e32 v48, v0
	v_mov_b32_e32 v49, v0
	v_mov_b32_e32 v58, v0
	v_mov_b32_e32 v59, v0
	v_mov_b32_e32 v60, v0
	v_mov_b32_e32 v61, v0
	v_mov_b32_e32 v62, v0
	v_mov_b32_e32 v63, v0
	v_mov_b32_e32 v64, v0
	v_mov_b32_e32 v65, v0
	v_mov_b32_e32 v66, v0
	v_mov_b32_e32 v67, v0
	v_mov_b32_e32 v68, v0
	v_mov_b32_e32 v69, v0
	v_mov_b32_e32 v70, v0
	v_mov_b32_e32 v71, v0
	v_mov_b32_e32 v72, v0
	v_mov_b32_e32 v73, v0
	v_mov_b32_e32 v82, v0
	v_mov_b32_e32 v83, v0
	v_mov_b32_e32 v84, v0
	v_mov_b32_e32 v85, v0
	v_mov_b32_e32 v86, v0
	v_mov_b32_e32 v87, v0
	v_mov_b32_e32 v88, v0
	v_mov_b32_e32 v89, v0
	v_mov_b32_e32 v98, v0
	v_mov_b32_e32 v99, v0
	v_mov_b32_e32 v100, v0
	v_mov_b32_e32 v101, v0
	v_mov_b32_e32 v102, v0
	v_mov_b32_e32 v103, v0
	v_mov_b32_e32 v104, v0
	v_mov_b32_e32 v105, v0
	v_mov_b32_e32 v114, v0
	v_mov_b32_e32 v115, v0
	v_mov_b32_e32 v116, v0
	v_mov_b32_e32 v117, v0
	v_mov_b32_e32 v118, v0
	v_mov_b32_e32 v119, v0
	v_mov_b32_e32 v120, v0
	v_mov_b32_e32 v121, v0
	v_mov_b32_e32 v74, v0
	v_mov_b32_e32 v75, v0
	v_mov_b32_e32 v76, v0
	v_mov_b32_e32 v77, v0
	v_mov_b32_e32 v78, v0
	v_mov_b32_e32 v79, v0
	v_mov_b32_e32 v80, v0
	v_mov_b32_e32 v81, v0
	v_mov_b32_e32 v90, v0
	v_mov_b32_e32 v91, v0
	v_mov_b32_e32 v92, v0
	v_mov_b32_e32 v93, v0
	v_mov_b32_e32 v94, v0
	v_mov_b32_e32 v95, v0
	v_mov_b32_e32 v96, v0
	v_mov_b32_e32 v97, v0
	v_mov_b32_e32 v106, v0
	v_mov_b32_e32 v107, v0
	v_mov_b32_e32 v108, v0
	v_mov_b32_e32 v109, v0
	v_mov_b32_e32 v110, v0
	v_mov_b32_e32 v111, v0
	v_mov_b32_e32 v112, v0
	v_mov_b32_e32 v113, v0
	v_mov_b32_e32 v122, v0
	v_mov_b32_e32 v123, v0
	v_mov_b32_e32 v124, v0
	v_mov_b32_e32 v125, v0
	v_mov_b32_e32 v126, v0
	v_mov_b32_e32 v127, v0
	v_mov_b32_e32 v128, v0
	v_mov_b32_e32 v129, v0
	s_cmp_eq_u32 s36, 1
	s_cbranch_scc1 .LBB0_81
	s_add_u32 s14, s0, 0x100
	s_addc_u32 s15, s1, 0
	s_add_i32 s3, 0, 0x10000
	s_cmpk_eq_i32 s9, 0x7c
	s_cselect_b32 s27, s43, s15
	s_cselect_b32 s26, s42, s14
	v_add_u32_e32 v162, s3, v145
	s_cselect_b32 s23, s79, s8
	s_cselect_b32 s22, s78, s2
	s_add_i32 s4, 0, 0x14000
	ds_read_b128 v[140:143], v162
	ds_read_b128 v[148:151], v162 offset:1024
	ds_read_b128 v[172:175], v162 offset:2048
	ds_read_b128 v[190:193], v162 offset:3072
	v_add_u32_e32 v162, s4, v145
	ds_read_b128 v[194:197], v162
	ds_read_b128 v[198:201], v162 offset:1024
	ds_read_b128 v[202:205], v162 offset:2048
	ds_read_b128 v[206:209], v162 offset:3072
	s_add_i32 m0, s30, 0xc000
	ds_read_b128 v[210:213], v147
	ds_read_b128 v[214:217], v147 offset:1024
	ds_read_b128 v[218:221], v147 offset:2048
	ds_read_b128 v[222:225], v147 offset:3072
	ds_read_b128 v[226:229], v147 offset:4096
	ds_read_b128 v[230:233], v147 offset:5120
	ds_read_b128 v[234:237], v147 offset:6144
	ds_read_b128 v[238:241], v147 offset:7168
	global_load_lds_dwordx4 v136, s[0:1]
	s_add_i32 m0, s30, 0xe000
	s_nop 0
	global_load_lds_dwordx4 v138, s[0:1]
	s_waitcnt vmcnt(24)
	s_waitcnt lgkmcnt(0)
	s_barrier
	s_waitcnt lgkmcnt(0)
	v_mfma_f32_16x16x32_bf16 v[126:129], v[140:143], v[210:213], v[126:129]
	v_mfma_f32_16x16x32_bf16 v[122:125], v[172:175], v[210:213], v[122:125]
	v_mfma_f32_16x16x32_bf16 v[110:113], v[140:143], v[218:221], v[110:113]
	v_mfma_f32_16x16x32_bf16 v[106:109], v[172:175], v[218:221], v[106:109]
	v_mfma_f32_16x16x32_bf16 v[94:97], v[140:143], v[226:229], v[94:97]
	v_mfma_f32_16x16x32_bf16 v[90:93], v[172:175], v[226:229], v[90:93]
	v_mfma_f32_16x16x32_bf16 v[78:81], v[140:143], v[234:237], v[78:81]
	v_mfma_f32_16x16x32_bf16 v[74:77], v[172:175], v[234:237], v[74:77]
	v_mfma_f32_16x16x32_bf16 v[126:129], v[148:151], v[214:217], v[126:129]
	v_mfma_f32_16x16x32_bf16 v[122:125], v[190:193], v[214:217], v[122:125]
	v_mfma_f32_16x16x32_bf16 v[110:113], v[148:151], v[222:225], v[110:113]
	v_mfma_f32_16x16x32_bf16 v[106:109], v[190:193], v[222:225], v[106:109]
	v_mfma_f32_16x16x32_bf16 v[94:97], v[148:151], v[230:233], v[94:97]
	v_mfma_f32_16x16x32_bf16 v[90:93], v[190:193], v[230:233], v[90:93]
	v_mfma_f32_16x16x32_bf16 v[78:81], v[148:151], v[238:241], v[78:81]
	v_mfma_f32_16x16x32_bf16 v[74:77], v[190:193], v[238:241], v[74:77]
	v_mfma_f32_16x16x32_bf16 v[118:121], v[194:197], v[210:213], v[118:121]
	v_mfma_f32_16x16x32_bf16 v[114:117], v[202:205], v[210:213], v[114:117]
	v_mfma_f32_16x16x32_bf16 v[102:105], v[194:197], v[218:221], v[102:105]
	v_mfma_f32_16x16x32_bf16 v[98:101], v[202:205], v[218:221], v[98:101]
	v_mfma_f32_16x16x32_bf16 v[86:89], v[194:197], v[226:229], v[86:89]
	v_mfma_f32_16x16x32_bf16 v[82:85], v[202:205], v[226:229], v[82:85]
	v_mfma_f32_16x16x32_bf16 v[70:73], v[194:197], v[234:237], v[70:73]
	v_mfma_f32_16x16x32_bf16 v[66:69], v[202:205], v[234:237], v[66:69]
	v_mfma_f32_16x16x32_bf16 v[118:121], v[198:201], v[214:217], v[118:121]
	v_mfma_f32_16x16x32_bf16 v[114:117], v[206:209], v[214:217], v[114:117]
	v_mfma_f32_16x16x32_bf16 v[102:105], v[198:201], v[222:225], v[102:105]
	v_mfma_f32_16x16x32_bf16 v[98:101], v[206:209], v[222:225], v[98:101]
	v_mfma_f32_16x16x32_bf16 v[86:89], v[198:201], v[230:233], v[86:89]
	v_mfma_f32_16x16x32_bf16 v[82:85], v[206:209], v[230:233], v[82:85]
	v_mfma_f32_16x16x32_bf16 v[70:73], v[198:201], v[238:241], v[70:73]
	v_mfma_f32_16x16x32_bf16 v[66:69], v[206:209], v[238:241], v[66:69]
	s_barrier
	s_add_i32 s0, s3, s11
	v_lshl_add_u64 v[162:163], s[22:23], 0, v[4:5]
	s_mov_b32 m0, s0
	ds_read_b128 v[210:213], v147 offset:16384
	ds_read_b128 v[214:217], v147 offset:17408
	ds_read_b128 v[218:221], v147 offset:18432
	ds_read_b128 v[222:225], v147 offset:19456
	ds_read_b128 v[226:229], v147 offset:20480
	ds_read_b128 v[230:233], v147 offset:21504
	ds_read_b128 v[234:237], v147 offset:22528
	ds_read_b128 v[238:241], v147 offset:23552
	global_load_lds_dwordx4 v4, s[22:23]
	s_add_i32 m0, s0, 0x2000
	s_add_u32 s0, s22, 0x208000
	v_lshl_add_u64 v[166:167], s[22:23], 0, v[130:131]
	s_addc_u32 s1, s23, 0
	s_add_i32 s3, s4, s11
	global_load_lds_dwordx4 v130, s[22:23]
	s_mov_b32 m0, s3
	v_lshl_add_u64 v[180:181], s[26:27], 0, v[132:133]
	global_load_lds_dwordx4 v4, s[0:1]
	s_add_i32 m0, s3, 0x2000
	s_nop 0
	global_load_lds_dwordx4 v130, s[0:1]
	v_lshl_add_u64 v[176:177], s[26:27], 0, v[134:135]
	s_mov_b32 m0, s30
	s_nop 0
	global_load_lds_dwordx4 v134, s[26:27]
	s_mov_b32 m0, s31
	s_nop 0
	global_load_lds_dwordx4 v132, s[26:27]
	s_waitcnt vmcnt(24)
	s_waitcnt lgkmcnt(0)
	s_barrier
	s_waitcnt lgkmcnt(0)
	v_mfma_f32_16x16x32_bf16 v[62:65], v[140:143], v[210:213], v[62:65]
	v_mfma_f32_16x16x32_bf16 v[58:61], v[172:175], v[210:213], v[58:61]
	v_mfma_f32_16x16x32_bf16 v[46:49], v[140:143], v[218:221], v[46:49]
	v_mfma_f32_16x16x32_bf16 v[42:45], v[172:175], v[218:221], v[42:45]
	v_mfma_f32_16x16x32_bf16 v[30:33], v[140:143], v[226:229], v[30:33]
	v_mfma_f32_16x16x32_bf16 v[26:29], v[172:175], v[226:229], v[26:29]
	v_mfma_f32_16x16x32_bf16 v[14:17], v[140:143], v[234:237], v[14:17]
	v_mfma_f32_16x16x32_bf16 v[10:13], v[172:175], v[234:237], v[10:13]
	v_mfma_f32_16x16x32_bf16 v[62:65], v[148:151], v[214:217], v[62:65]
	v_mfma_f32_16x16x32_bf16 v[58:61], v[190:193], v[214:217], v[58:61]
	v_mfma_f32_16x16x32_bf16 v[46:49], v[148:151], v[222:225], v[46:49]
	v_mfma_f32_16x16x32_bf16 v[42:45], v[190:193], v[222:225], v[42:45]
	v_mfma_f32_16x16x32_bf16 v[30:33], v[148:151], v[230:233], v[30:33]
	v_mfma_f32_16x16x32_bf16 v[26:29], v[190:193], v[230:233], v[26:29]
	v_mfma_f32_16x16x32_bf16 v[14:17], v[148:151], v[238:241], v[14:17]
	v_mfma_f32_16x16x32_bf16 v[10:13], v[190:193], v[238:241], v[10:13]
	v_mfma_f32_16x16x32_bf16 v[54:57], v[194:197], v[210:213], v[54:57]
	v_mfma_f32_16x16x32_bf16 v[50:53], v[202:205], v[210:213], v[50:53]
	v_mfma_f32_16x16x32_bf16 v[38:41], v[194:197], v[218:221], v[38:41]
	v_mfma_f32_16x16x32_bf16 v[34:37], v[202:205], v[218:221], v[34:37]
	v_mfma_f32_16x16x32_bf16 v[22:25], v[194:197], v[226:229], v[22:25]
	v_mfma_f32_16x16x32_bf16 v[18:21], v[202:205], v[226:229], v[18:21]
	v_mfma_f32_16x16x32_bf16 v[6:9], v[194:197], v[234:237], v[6:9]
	v_mfma_f32_16x16x32_bf16 v[0:3], v[202:205], v[234:237], v[0:3]
	v_mfma_f32_16x16x32_bf16 v[54:57], v[198:201], v[214:217], v[54:57]
	v_mfma_f32_16x16x32_bf16 v[50:53], v[206:209], v[214:217], v[50:53]
	v_mfma_f32_16x16x32_bf16 v[38:41], v[198:201], v[222:225], v[38:41]
	v_mfma_f32_16x16x32_bf16 v[34:37], v[206:209], v[222:225], v[34:37]
	v_mfma_f32_16x16x32_bf16 v[22:25], v[198:201], v[230:233], v[22:25]
	v_mfma_f32_16x16x32_bf16 v[18:21], v[206:209], v[230:233], v[18:21]
	v_mfma_f32_16x16x32_bf16 v[6:9], v[198:201], v[238:241], v[6:9]
	v_mfma_f32_16x16x32_bf16 v[0:3], v[206:209], v[238:241], v[0:3]
	s_barrier
	s_branch .Lpeelmid_81
.LBB0_81:
	s_add_u32 s14, s0, 0x100
	s_addc_u32 s15, s1, 0
	s_add_i32 s3, 0, 0x10000
	s_cmpk_eq_i32 s9, 0x7c
	s_cselect_b32 s27, s43, s15
	s_cselect_b32 s26, s42, s14
	v_add_u32_e32 v162, s3, v145
	s_cselect_b32 s23, s79, s8
	s_cselect_b32 s22, s78, s2
	s_add_i32 s4, 0, 0x14000
	ds_read_b128 v[140:143], v162
	ds_read_b128 v[148:151], v162 offset:1024
	ds_read_b128 v[172:175], v162 offset:2048
	ds_read_b128 v[190:193], v162 offset:3072
	v_add_u32_e32 v162, s4, v145
	ds_read_b128 v[194:197], v162
	ds_read_b128 v[198:201], v162 offset:1024
	ds_read_b128 v[202:205], v162 offset:2048
	ds_read_b128 v[206:209], v162 offset:3072
	s_add_i32 m0, s30, 0xc000
	ds_read_b128 v[210:213], v147
	ds_read_b128 v[214:217], v147 offset:1024
	ds_read_b128 v[218:221], v147 offset:2048
	ds_read_b128 v[222:225], v147 offset:3072
	ds_read_b128 v[226:229], v147 offset:4096
	ds_read_b128 v[230:233], v147 offset:5120
	ds_read_b128 v[234:237], v147 offset:6144
	ds_read_b128 v[238:241], v147 offset:7168
	global_load_lds_dwordx4 v136, s[0:1]
	s_add_i32 m0, s30, 0xe000
	s_nop 0
	global_load_lds_dwordx4 v138, s[0:1]
	s_waitcnt vmcnt(8)
	s_waitcnt lgkmcnt(0)
	s_barrier
	s_waitcnt lgkmcnt(0)
	v_mfma_f32_16x16x32_bf16 v[126:129], v[140:143], v[210:213], v[126:129]
	v_mfma_f32_16x16x32_bf16 v[122:125], v[172:175], v[210:213], v[122:125]
	v_mfma_f32_16x16x32_bf16 v[110:113], v[140:143], v[218:221], v[110:113]
	v_mfma_f32_16x16x32_bf16 v[106:109], v[172:175], v[218:221], v[106:109]
	v_mfma_f32_16x16x32_bf16 v[94:97], v[140:143], v[226:229], v[94:97]
	v_mfma_f32_16x16x32_bf16 v[90:93], v[172:175], v[226:229], v[90:93]
	v_mfma_f32_16x16x32_bf16 v[78:81], v[140:143], v[234:237], v[78:81]
	v_mfma_f32_16x16x32_bf16 v[74:77], v[172:175], v[234:237], v[74:77]
	v_mfma_f32_16x16x32_bf16 v[126:129], v[148:151], v[214:217], v[126:129]
	v_mfma_f32_16x16x32_bf16 v[122:125], v[190:193], v[214:217], v[122:125]
	v_mfma_f32_16x16x32_bf16 v[110:113], v[148:151], v[222:225], v[110:113]
	v_mfma_f32_16x16x32_bf16 v[106:109], v[190:193], v[222:225], v[106:109]
	v_mfma_f32_16x16x32_bf16 v[94:97], v[148:151], v[230:233], v[94:97]
	v_mfma_f32_16x16x32_bf16 v[90:93], v[190:193], v[230:233], v[90:93]
	v_mfma_f32_16x16x32_bf16 v[78:81], v[148:151], v[238:241], v[78:81]
	v_mfma_f32_16x16x32_bf16 v[74:77], v[190:193], v[238:241], v[74:77]
	v_mfma_f32_16x16x32_bf16 v[118:121], v[194:197], v[210:213], v[118:121]
	v_mfma_f32_16x16x32_bf16 v[114:117], v[202:205], v[210:213], v[114:117]
	v_mfma_f32_16x16x32_bf16 v[102:105], v[194:197], v[218:221], v[102:105]
	v_mfma_f32_16x16x32_bf16 v[98:101], v[202:205], v[218:221], v[98:101]
	v_mfma_f32_16x16x32_bf16 v[86:89], v[194:197], v[226:229], v[86:89]
	v_mfma_f32_16x16x32_bf16 v[82:85], v[202:205], v[226:229], v[82:85]
	v_mfma_f32_16x16x32_bf16 v[70:73], v[194:197], v[234:237], v[70:73]
	v_mfma_f32_16x16x32_bf16 v[66:69], v[202:205], v[234:237], v[66:69]
	v_mfma_f32_16x16x32_bf16 v[118:121], v[198:201], v[214:217], v[118:121]
	v_mfma_f32_16x16x32_bf16 v[114:117], v[206:209], v[214:217], v[114:117]
	v_mfma_f32_16x16x32_bf16 v[102:105], v[198:201], v[222:225], v[102:105]
	v_mfma_f32_16x16x32_bf16 v[98:101], v[206:209], v[222:225], v[98:101]
	v_mfma_f32_16x16x32_bf16 v[86:89], v[198:201], v[230:233], v[86:89]
	v_mfma_f32_16x16x32_bf16 v[82:85], v[206:209], v[230:233], v[82:85]
	v_mfma_f32_16x16x32_bf16 v[70:73], v[198:201], v[238:241], v[70:73]
	v_mfma_f32_16x16x32_bf16 v[66:69], v[206:209], v[238:241], v[66:69]
	s_barrier
	s_add_i32 s0, s3, s11
	v_lshl_add_u64 v[162:163], s[22:23], 0, v[4:5]
	s_mov_b32 m0, s0
	ds_read_b128 v[210:213], v147 offset:16384
	ds_read_b128 v[214:217], v147 offset:17408
	ds_read_b128 v[218:221], v147 offset:18432
	ds_read_b128 v[222:225], v147 offset:19456
	ds_read_b128 v[226:229], v147 offset:20480
	ds_read_b128 v[230:233], v147 offset:21504
	ds_read_b128 v[234:237], v147 offset:22528
	ds_read_b128 v[238:241], v147 offset:23552
	global_load_lds_dwordx4 v4, s[22:23]
	s_add_i32 m0, s0, 0x2000
	s_add_u32 s0, s22, 0x208000
	v_lshl_add_u64 v[166:167], s[22:23], 0, v[130:131]
	s_addc_u32 s1, s23, 0
	s_add_i32 s3, s4, s11
	global_load_lds_dwordx4 v130, s[22:23]
	s_mov_b32 m0, s3
	v_lshl_add_u64 v[180:181], s[26:27], 0, v[132:133]
	global_load_lds_dwordx4 v4, s[0:1]
	s_add_i32 m0, s3, 0x2000
	s_nop 0
	global_load_lds_dwordx4 v130, s[0:1]
	v_lshl_add_u64 v[176:177], s[26:27], 0, v[134:135]
	s_mov_b32 m0, s30
	s_nop 0
	global_load_lds_dwordx4 v134, s[26:27]
	s_mov_b32 m0, s31
	s_nop 0
	global_load_lds_dwordx4 v132, s[26:27]
	s_waitcnt vmcnt(8)
	s_waitcnt lgkmcnt(0)
	s_barrier
	s_waitcnt lgkmcnt(0)
	v_mfma_f32_16x16x32_bf16 v[62:65], v[140:143], v[210:213], v[62:65]
	v_mfma_f32_16x16x32_bf16 v[58:61], v[172:175], v[210:213], v[58:61]
	v_mfma_f32_16x16x32_bf16 v[46:49], v[140:143], v[218:221], v[46:49]
	v_mfma_f32_16x16x32_bf16 v[42:45], v[172:175], v[218:221], v[42:45]
	v_mfma_f32_16x16x32_bf16 v[30:33], v[140:143], v[226:229], v[30:33]
	v_mfma_f32_16x16x32_bf16 v[26:29], v[172:175], v[226:229], v[26:29]
	v_mfma_f32_16x16x32_bf16 v[14:17], v[140:143], v[234:237], v[14:17]
	v_mfma_f32_16x16x32_bf16 v[10:13], v[172:175], v[234:237], v[10:13]
	v_mfma_f32_16x16x32_bf16 v[62:65], v[148:151], v[214:217], v[62:65]
	v_mfma_f32_16x16x32_bf16 v[58:61], v[190:193], v[214:217], v[58:61]
	v_mfma_f32_16x16x32_bf16 v[46:49], v[148:151], v[222:225], v[46:49]
	v_mfma_f32_16x16x32_bf16 v[42:45], v[190:193], v[222:225], v[42:45]
	v_mfma_f32_16x16x32_bf16 v[30:33], v[148:151], v[230:233], v[30:33]
	v_mfma_f32_16x16x32_bf16 v[26:29], v[190:193], v[230:233], v[26:29]
	v_mfma_f32_16x16x32_bf16 v[14:17], v[148:151], v[238:241], v[14:17]
	v_mfma_f32_16x16x32_bf16 v[10:13], v[190:193], v[238:241], v[10:13]
	v_mfma_f32_16x16x32_bf16 v[54:57], v[194:197], v[210:213], v[54:57]
	v_mfma_f32_16x16x32_bf16 v[50:53], v[202:205], v[210:213], v[50:53]
	v_mfma_f32_16x16x32_bf16 v[38:41], v[194:197], v[218:221], v[38:41]
	v_mfma_f32_16x16x32_bf16 v[34:37], v[202:205], v[218:221], v[34:37]
	v_mfma_f32_16x16x32_bf16 v[22:25], v[194:197], v[226:229], v[22:25]
	v_mfma_f32_16x16x32_bf16 v[18:21], v[202:205], v[226:229], v[18:21]
	v_mfma_f32_16x16x32_bf16 v[6:9], v[194:197], v[234:237], v[6:9]
	v_mfma_f32_16x16x32_bf16 v[0:3], v[202:205], v[234:237], v[0:3]
	v_mfma_f32_16x16x32_bf16 v[54:57], v[198:201], v[214:217], v[54:57]
	v_mfma_f32_16x16x32_bf16 v[50:53], v[206:209], v[214:217], v[50:53]
	v_mfma_f32_16x16x32_bf16 v[38:41], v[198:201], v[222:225], v[38:41]
	v_mfma_f32_16x16x32_bf16 v[34:37], v[206:209], v[222:225], v[34:37]
	v_mfma_f32_16x16x32_bf16 v[22:25], v[198:201], v[230:233], v[22:25]
	v_mfma_f32_16x16x32_bf16 v[18:21], v[206:209], v[230:233], v[18:21]
	v_mfma_f32_16x16x32_bf16 v[6:9], v[198:201], v[238:241], v[6:9]
	v_mfma_f32_16x16x32_bf16 v[0:3], v[206:209], v[238:241], v[0:3]
	s_barrier
.Lpeelmid_81:
	s_add_i32 s3, 0, 0x18000
	v_add_u32_e32 v164, s3, v145
	s_add_i32 s4, 0, 0x1c000
	ds_read_b128 v[140:143], v164
	ds_read_b128 v[148:151], v164 offset:1024
	ds_read_b128 v[172:175], v164 offset:2048
	ds_read_b128 v[190:193], v164 offset:3072
	v_add_u32_e32 v164, s4, v145
	ds_read_b128 v[194:197], v164
	ds_read_b128 v[198:201], v164 offset:1024
	ds_read_b128 v[202:205], v164 offset:2048
	ds_read_b128 v[206:209], v164 offset:3072
	s_add_u32 s0, s26, 0x208000
	s_addc_u32 s1, s27, 0
	s_mov_b32 m0, s34
	ds_read_b128 v[210:213], v147 offset:32768
	ds_read_b128 v[214:217], v147 offset:33792
	ds_read_b128 v[218:221], v147 offset:34816
	ds_read_b128 v[222:225], v147 offset:35840
	ds_read_b128 v[226:229], v147 offset:36864
	ds_read_b128 v[230:233], v147 offset:37888
	ds_read_b128 v[234:237], v147 offset:38912
	ds_read_b128 v[238:241], v147 offset:39936
	global_load_lds_dwordx4 v134, s[0:1]
	v_lshl_add_u64 v[242:243], s[0:1], 0, v[132:133]
	s_mov_b32 m0, s35
	s_nop 0
	global_load_lds_dwordx4 v132, s[0:1]
	s_waitcnt vmcnt(8)
	s_waitcnt lgkmcnt(0)
	s_barrier
	s_waitcnt lgkmcnt(0)
	v_mfma_f32_16x16x32_bf16 v[126:129], v[140:143], v[210:213], v[126:129]
	v_mfma_f32_16x16x32_bf16 v[122:125], v[172:175], v[210:213], v[122:125]
	v_mfma_f32_16x16x32_bf16 v[110:113], v[140:143], v[218:221], v[110:113]
	v_mfma_f32_16x16x32_bf16 v[106:109], v[172:175], v[218:221], v[106:109]
	v_mfma_f32_16x16x32_bf16 v[94:97], v[140:143], v[226:229], v[94:97]
	v_mfma_f32_16x16x32_bf16 v[90:93], v[172:175], v[226:229], v[90:93]
	v_mfma_f32_16x16x32_bf16 v[78:81], v[140:143], v[234:237], v[78:81]
	v_mfma_f32_16x16x32_bf16 v[74:77], v[172:175], v[234:237], v[74:77]
	v_mfma_f32_16x16x32_bf16 v[126:129], v[148:151], v[214:217], v[126:129]
	v_mfma_f32_16x16x32_bf16 v[122:125], v[190:193], v[214:217], v[122:125]
	v_mfma_f32_16x16x32_bf16 v[110:113], v[148:151], v[222:225], v[110:113]
	v_mfma_f32_16x16x32_bf16 v[106:109], v[190:193], v[222:225], v[106:109]
	v_mfma_f32_16x16x32_bf16 v[94:97], v[148:151], v[230:233], v[94:97]
	v_mfma_f32_16x16x32_bf16 v[90:93], v[190:193], v[230:233], v[90:93]
	v_mfma_f32_16x16x32_bf16 v[78:81], v[148:151], v[238:241], v[78:81]
	v_mfma_f32_16x16x32_bf16 v[74:77], v[190:193], v[238:241], v[74:77]
	v_mfma_f32_16x16x32_bf16 v[118:121], v[194:197], v[210:213], v[118:121]
	v_mfma_f32_16x16x32_bf16 v[114:117], v[202:205], v[210:213], v[114:117]
	v_mfma_f32_16x16x32_bf16 v[102:105], v[194:197], v[218:221], v[102:105]
	v_mfma_f32_16x16x32_bf16 v[98:101], v[202:205], v[218:221], v[98:101]
	v_mfma_f32_16x16x32_bf16 v[86:89], v[194:197], v[226:229], v[86:89]
	v_mfma_f32_16x16x32_bf16 v[82:85], v[202:205], v[226:229], v[82:85]
	v_mfma_f32_16x16x32_bf16 v[70:73], v[194:197], v[234:237], v[70:73]
	v_mfma_f32_16x16x32_bf16 v[66:69], v[202:205], v[234:237], v[66:69]
	v_mfma_f32_16x16x32_bf16 v[118:121], v[198:201], v[214:217], v[118:121]
	v_mfma_f32_16x16x32_bf16 v[114:117], v[206:209], v[214:217], v[114:117]
	v_mfma_f32_16x16x32_bf16 v[102:105], v[198:201], v[222:225], v[102:105]
	v_mfma_f32_16x16x32_bf16 v[98:101], v[206:209], v[222:225], v[98:101]
	v_mfma_f32_16x16x32_bf16 v[86:89], v[198:201], v[230:233], v[86:89]
	v_mfma_f32_16x16x32_bf16 v[82:85], v[206:209], v[230:233], v[82:85]
	v_mfma_f32_16x16x32_bf16 v[70:73], v[198:201], v[238:241], v[70:73]
	v_mfma_f32_16x16x32_bf16 v[66:69], v[206:209], v[238:241], v[66:69]
	s_barrier
	s_add_i32 s0, s3, s11
	v_lshl_add_u64 v[162:163], v[162:163], 0, s[70:71]
	s_mov_b32 m0, s0
	ds_read_b128 v[210:213], v147 offset:49152
	ds_read_b128 v[214:217], v147 offset:50176
	ds_read_b128 v[218:221], v147 offset:51200
	ds_read_b128 v[222:225], v147 offset:52224
	ds_read_b128 v[226:229], v147 offset:53248
	ds_read_b128 v[230:233], v147 offset:54272
	ds_read_b128 v[234:237], v147 offset:55296
	ds_read_b128 v[238:241], v147 offset:56320
	global_load_lds_dwordx4 v[162:163], off
	s_add_i32 m0, s0, 0x2000
	s_add_u32 s0, s22, 0x208080
	v_lshl_add_u64 v[162:163], v[166:167], 0, s[70:71]
	s_addc_u32 s1, s23, 0
	s_add_i32 s3, s4, s11
	global_load_lds_dwordx4 v[162:163], off
	s_mov_b32 m0, s3
	s_nop 0
	global_load_lds_dwordx4 v4, s[0:1]
	s_add_i32 m0, s3, 0x2000
	s_nop 0
	global_load_lds_dwordx4 v130, s[0:1]
	v_lshl_add_u64 v[162:163], v[176:177], 0, s[70:71]
	s_mov_b32 m0, s51
	s_nop 0
	global_load_lds_dwordx4 v[162:163], off
	v_lshl_add_u64 v[162:163], v[180:181], 0, s[70:71]
	s_mov_b32 m0, s52
	s_nop 0
	global_load_lds_dwordx4 v[162:163], off
	s_waitcnt vmcnt(8)
	s_waitcnt lgkmcnt(0)
	s_barrier
	s_waitcnt lgkmcnt(0)
	v_mfma_f32_16x16x32_bf16 v[62:65], v[140:143], v[210:213], v[62:65]
	v_mfma_f32_16x16x32_bf16 v[58:61], v[172:175], v[210:213], v[58:61]
	v_mfma_f32_16x16x32_bf16 v[46:49], v[140:143], v[218:221], v[46:49]
	v_mfma_f32_16x16x32_bf16 v[42:45], v[172:175], v[218:221], v[42:45]
	v_mfma_f32_16x16x32_bf16 v[30:33], v[140:143], v[226:229], v[30:33]
	v_mfma_f32_16x16x32_bf16 v[26:29], v[172:175], v[226:229], v[26:29]
	v_mfma_f32_16x16x32_bf16 v[14:17], v[140:143], v[234:237], v[14:17]
	v_mfma_f32_16x16x32_bf16 v[10:13], v[172:175], v[234:237], v[10:13]
	v_mfma_f32_16x16x32_bf16 v[62:65], v[148:151], v[214:217], v[62:65]
	v_mfma_f32_16x16x32_bf16 v[58:61], v[190:193], v[214:217], v[58:61]
	v_mfma_f32_16x16x32_bf16 v[46:49], v[148:151], v[222:225], v[46:49]
	v_mfma_f32_16x16x32_bf16 v[42:45], v[190:193], v[222:225], v[42:45]
	v_mfma_f32_16x16x32_bf16 v[30:33], v[148:151], v[230:233], v[30:33]
	v_mfma_f32_16x16x32_bf16 v[26:29], v[190:193], v[230:233], v[26:29]
	v_mfma_f32_16x16x32_bf16 v[14:17], v[148:151], v[238:241], v[14:17]
	v_mfma_f32_16x16x32_bf16 v[10:13], v[190:193], v[238:241], v[10:13]
	v_mfma_f32_16x16x32_bf16 v[54:57], v[194:197], v[210:213], v[54:57]
	v_mfma_f32_16x16x32_bf16 v[50:53], v[202:205], v[210:213], v[50:53]
	v_mfma_f32_16x16x32_bf16 v[38:41], v[194:197], v[218:221], v[38:41]
	v_mfma_f32_16x16x32_bf16 v[34:37], v[202:205], v[218:221], v[34:37]
	v_mfma_f32_16x16x32_bf16 v[22:25], v[194:197], v[226:229], v[22:25]
	v_mfma_f32_16x16x32_bf16 v[18:21], v[202:205], v[226:229], v[18:21]
	v_mfma_f32_16x16x32_bf16 v[6:9], v[194:197], v[234:237], v[6:9]
	v_mfma_f32_16x16x32_bf16 v[0:3], v[202:205], v[234:237], v[0:3]
	v_mfma_f32_16x16x32_bf16 v[54:57], v[198:201], v[214:217], v[54:57]
	v_mfma_f32_16x16x32_bf16 v[50:53], v[206:209], v[214:217], v[50:53]
	v_mfma_f32_16x16x32_bf16 v[38:41], v[198:201], v[222:225], v[38:41]
	v_mfma_f32_16x16x32_bf16 v[34:37], v[206:209], v[222:225], v[34:37]
	v_mfma_f32_16x16x32_bf16 v[22:25], v[198:201], v[230:233], v[22:25]
	v_mfma_f32_16x16x32_bf16 v[18:21], v[206:209], v[230:233], v[18:21]
	v_mfma_f32_16x16x32_bf16 v[6:9], v[198:201], v[238:241], v[6:9]
	v_mfma_f32_16x16x32_bf16 v[0:3], v[206:209], v[238:241], v[0:3]
	s_barrier
	s_add_i32 s9, s9, 2
	s_add_u32 s2, s2, 0x100
	s_addc_u32 s8, s8, 0
	s_cmpk_gt_u32 s9, 0x7d
	s_mov_b64 s[0:1], s[14:15]
	s_cbranch_scc0 .LBB0_81
	s_and_b64 vcc, exec, s[48:49]
	s_cbranch_vccz .LBB0_84
	s_barrier

.LBB0_123:
	s_ashr_i32 s3, s51, 24
	s_lshl_b32 s2, s51, 8
	s_andn2_b32 s3, s3, 63
	s_add_i32 s2, s3, s2
	s_ashr_i32 s3, s2, 31
	s_lshl_b64 s[2:3], s[2:3], 12
	s_add_u32 s48, s11, s2
	s_addc_u32 s49, s26, s3
	s_and_b64 s[2:3], s[38:39], exec
	s_cselect_b32 s2, s49, s1
	s_cselect_b32 s8, s48, s0
	s_ashr_i32 s47, s46, 31
	s_lshl_b64 s[4:5], s[46:47], 20
	v_readlane_b32 s6, v254, 1
	v_readlane_b32 s7, v254, 2
	s_add_u32 s78, s6, s4
	s_addc_u32 s79, s7, s5
	s_and_b64 s[4:5], s[38:39], exec
	s_cselect_b32 s10, s79, s15
	s_cselect_b32 s24, s78, s14
	s_add_u32 s22, s0, 0x80080
	s_addc_u32 s23, s1, 0
	s_add_u32 s9, s14, 0x100
	v_mov_b32_e32 v0, 0
	s_addc_u32 s25, s15, 0
	s_mov_b32 s28, -2
	v_mov_b32_e32 v1, v0
	v_mov_b32_e32 v2, v0
	v_mov_b32_e32 v3, v0
	v_mov_b32_e32 v6, v0
	v_mov_b32_e32 v7, v0
	v_mov_b32_e32 v8, v0
	v_mov_b32_e32 v9, v0
	v_mov_b32_e32 v10, v0
	v_mov_b32_e32 v11, v0
	v_mov_b32_e32 v12, v0
	v_mov_b32_e32 v13, v0
	v_mov_b32_e32 v14, v0
	v_mov_b32_e32 v15, v0
	v_mov_b32_e32 v16, v0
	v_mov_b32_e32 v17, v0
	v_mov_b32_e32 v18, v0
	v_mov_b32_e32 v19, v0
	v_mov_b32_e32 v20, v0
	v_mov_b32_e32 v21, v0
	v_mov_b32_e32 v22, v0
	v_mov_b32_e32 v23, v0
	v_mov_b32_e32 v24, v0
	v_mov_b32_e32 v25, v0
	v_mov_b32_e32 v26, v0
	v_mov_b32_e32 v27, v0
	v_mov_b32_e32 v28, v0
	v_mov_b32_e32 v29, v0
	v_mov_b32_e32 v30, v0
	v_mov_b32_e32 v31, v0
	v_mov_b32_e32 v32, v0
	v_mov_b32_e32 v33, v0
	v_mov_b32_e32 v58, v0
	v_mov_b32_e32 v59, v0
	v_mov_b32_e32 v60, v0
	v_mov_b32_e32 v61, v0
	v_mov_b32_e32 v62, v0
	v_mov_b32_e32 v63, v0
	v_mov_b32_e32 v64, v0
	v_mov_b32_e32 v65, v0
	v_mov_b32_e32 v74, v0
	v_mov_b32_e32 v75, v0
	v_mov_b32_e32 v76, v0
	v_mov_b32_e32 v77, v0
	v_mov_b32_e32 v78, v0
	v_mov_b32_e32 v79, v0
	v_mov_b32_e32 v80, v0
	v_mov_b32_e32 v81, v0
	v_mov_b32_e32 v82, v0
	v_mov_b32_e32 v83, v0
	v_mov_b32_e32 v84, v0
	v_mov_b32_e32 v85, v0
	v_mov_b32_e32 v86, v0
	v_mov_b32_e32 v87, v0
	v_mov_b32_e32 v88, v0
	v_mov_b32_e32 v89, v0
	v_mov_b32_e32 v90, v0
	v_mov_b32_e32 v91, v0
	v_mov_b32_e32 v92, v0
	v_mov_b32_e32 v93, v0
	v_mov_b32_e32 v94, v0
	v_mov_b32_e32 v95, v0
	v_mov_b32_e32 v96, v0
	v_mov_b32_e32 v97, v0
	v_mov_b32_e32 v34, v0
	v_mov_b32_e32 v35, v0
	v_mov_b32_e32 v36, v0
	v_mov_b32_e32 v37, v0
	v_mov_b32_e32 v38, v0
	v_mov_b32_e32 v39, v0
	v_mov_b32_e32 v40, v0
	v_mov_b32_e32 v41, v0
	v_mov_b32_e32 v42, v0
	v_mov_b32_e32 v43, v0
	v_mov_b32_e32 v44, v0
	v_mov_b32_e32 v45, v0
	v_mov_b32_e32 v46, v0
	v_mov_b32_e32 v47, v0
	v_mov_b32_e32 v48, v0
	v_mov_b32_e32 v49, v0
	v_mov_b32_e32 v50, v0
	v_mov_b32_e32 v51, v0
	v_mov_b32_e32 v52, v0
	v_mov_b32_e32 v53, v0
	v_mov_b32_e32 v54, v0
	v_mov_b32_e32 v55, v0
	v_mov_b32_e32 v56, v0
	v_mov_b32_e32 v57, v0
	v_mov_b32_e32 v66, v0
	v_mov_b32_e32 v67, v0
	v_mov_b32_e32 v68, v0
	v_mov_b32_e32 v69, v0
	v_mov_b32_e32 v70, v0
	v_mov_b32_e32 v71, v0
	v_mov_b32_e32 v72, v0
	v_mov_b32_e32 v73, v0
	v_mov_b32_e32 v98, v0
	v_mov_b32_e32 v99, v0
	v_mov_b32_e32 v100, v0
	v_mov_b32_e32 v101, v0
	v_mov_b32_e32 v102, v0
	v_mov_b32_e32 v103, v0
	v_mov_b32_e32 v104, v0
	v_mov_b32_e32 v105, v0
	v_mov_b32_e32 v106, v0
	v_mov_b32_e32 v107, v0
	v_mov_b32_e32 v108, v0
	v_mov_b32_e32 v109, v0
	v_mov_b32_e32 v110, v0
	v_mov_b32_e32 v111, v0
	v_mov_b32_e32 v112, v0
	v_mov_b32_e32 v113, v0
	v_mov_b32_e32 v114, v0
	v_mov_b32_e32 v115, v0
	v_mov_b32_e32 v116, v0
	v_mov_b32_e32 v117, v0
	v_mov_b32_e32 v118, v0
	v_mov_b32_e32 v119, v0
	v_mov_b32_e32 v120, v0
	v_mov_b32_e32 v121, v0
	v_mov_b32_e32 v122, v0
	v_mov_b32_e32 v123, v0
	v_mov_b32_e32 v124, v0
	v_mov_b32_e32 v125, v0
	v_mov_b32_e32 v126, v0
	v_mov_b32_e32 v127, v0
	v_mov_b32_e32 v128, v0
	v_mov_b32_e32 v129, v0
	s_cmp_eq_u32 s50, 1
	s_cbranch_scc1 .LBB0_124
	s_add_u32 s0, s22, 0xfff80080
	s_addc_u32 s1, s23, -1
	s_add_i32 s3, 0, 0x10000
	s_cmp_eq_u32 s28, 28
	s_cselect_b32 s15, s2, s1
	s_cselect_b32 s14, s8, s0
	v_add_u32_e32 v162, s3, v141
	s_cselect_b32 s1, s10, s25
	s_cselect_b32 s0, s24, s9
	s_add_i32 s6, 0, 0x14000
	ds_read_b128 v[144:147], v162
	ds_read_b128 v[148:151], v162 offset:1024
	ds_read_b128 v[172:175], v162 offset:2048
	ds_read_b128 v[190:193], v162 offset:3072
	v_add_u32_e32 v162, s6, v141
	ds_read_b128 v[194:197], v162
	ds_read_b128 v[198:201], v162 offset:1024
	ds_read_b128 v[202:205], v162 offset:2048
	ds_read_b128 v[206:209], v162 offset:3072
	s_add_i32 m0, s30, 0xc000
	ds_read_b128 v[210:213], v143
	ds_read_b128 v[214:217], v143 offset:1024
	ds_read_b128 v[218:221], v143 offset:2048
	ds_read_b128 v[222:225], v143 offset:3072
	ds_read_b128 v[226:229], v143 offset:4096
	ds_read_b128 v[230:233], v143 offset:5120
	ds_read_b128 v[234:237], v143 offset:6144
	ds_read_b128 v[238:241], v143 offset:7168
	global_load_lds_dwordx4 v136, s[22:23]
	s_add_i32 m0, s30, 0xe000
	s_nop 0
	global_load_lds_dwordx4 v138, s[22:23]
	s_waitcnt vmcnt(24)
	s_waitcnt lgkmcnt(0)
	s_barrier
	s_waitcnt lgkmcnt(0)
	v_mfma_f32_16x16x32_bf16 v[126:129], v[144:147], v[210:213], v[126:129]
	v_mfma_f32_16x16x32_bf16 v[122:125], v[172:175], v[210:213], v[122:125]
	v_mfma_f32_16x16x32_bf16 v[118:121], v[144:147], v[218:221], v[118:121]
	v_mfma_f32_16x16x32_bf16 v[114:117], v[172:175], v[218:221], v[114:117]
	v_mfma_f32_16x16x32_bf16 v[110:113], v[144:147], v[226:229], v[110:113]
	v_mfma_f32_16x16x32_bf16 v[106:109], v[172:175], v[226:229], v[106:109]
	v_mfma_f32_16x16x32_bf16 v[102:105], v[144:147], v[234:237], v[102:105]
	v_mfma_f32_16x16x32_bf16 v[98:101], v[172:175], v[234:237], v[98:101]
	v_mfma_f32_16x16x32_bf16 v[126:129], v[148:151], v[214:217], v[126:129]
	v_mfma_f32_16x16x32_bf16 v[122:125], v[190:193], v[214:217], v[122:125]
	v_mfma_f32_16x16x32_bf16 v[118:121], v[148:151], v[222:225], v[118:121]
	v_mfma_f32_16x16x32_bf16 v[114:117], v[190:193], v[222:225], v[114:117]
	v_mfma_f32_16x16x32_bf16 v[110:113], v[148:151], v[230:233], v[110:113]
	v_mfma_f32_16x16x32_bf16 v[106:109], v[190:193], v[230:233], v[106:109]
	v_mfma_f32_16x16x32_bf16 v[102:105], v[148:151], v[238:241], v[102:105]
	v_mfma_f32_16x16x32_bf16 v[98:101], v[190:193], v[238:241], v[98:101]
	v_mfma_f32_16x16x32_bf16 v[70:73], v[194:197], v[210:213], v[70:73]
	v_mfma_f32_16x16x32_bf16 v[66:69], v[202:205], v[210:213], v[66:69]
	v_mfma_f32_16x16x32_bf16 v[54:57], v[194:197], v[218:221], v[54:57]
	v_mfma_f32_16x16x32_bf16 v[50:53], v[202:205], v[218:221], v[50:53]
	v_mfma_f32_16x16x32_bf16 v[46:49], v[194:197], v[226:229], v[46:49]
	v_mfma_f32_16x16x32_bf16 v[42:45], v[202:205], v[226:229], v[42:45]
	v_mfma_f32_16x16x32_bf16 v[38:41], v[194:197], v[234:237], v[38:41]
	v_mfma_f32_16x16x32_bf16 v[34:37], v[202:205], v[234:237], v[34:37]
	v_mfma_f32_16x16x32_bf16 v[70:73], v[198:201], v[214:217], v[70:73]
	v_mfma_f32_16x16x32_bf16 v[66:69], v[206:209], v[214:217], v[66:69]
	v_mfma_f32_16x16x32_bf16 v[54:57], v[198:201], v[222:225], v[54:57]
	v_mfma_f32_16x16x32_bf16 v[50:53], v[206:209], v[222:225], v[50:53]
	v_mfma_f32_16x16x32_bf16 v[46:49], v[198:201], v[230:233], v[46:49]
	v_mfma_f32_16x16x32_bf16 v[42:45], v[206:209], v[230:233], v[42:45]
	v_mfma_f32_16x16x32_bf16 v[38:41], v[198:201], v[238:241], v[38:41]
	v_mfma_f32_16x16x32_bf16 v[34:37], v[206:209], v[238:241], v[34:37]
	s_barrier
	s_add_i32 s3, s3, s27
	v_lshl_add_u64 v[162:163], s[0:1], 0, v[4:5]
	s_mov_b32 m0, s3
	ds_read_b128 v[210:213], v143 offset:16384
	ds_read_b128 v[214:217], v143 offset:17408
	ds_read_b128 v[218:221], v143 offset:18432
	ds_read_b128 v[222:225], v143 offset:19456
	ds_read_b128 v[226:229], v143 offset:20480
	ds_read_b128 v[230:233], v143 offset:21504
	ds_read_b128 v[234:237], v143 offset:22528
	ds_read_b128 v[238:241], v143 offset:23552
	global_load_lds_dwordx4 v4, s[0:1]
	s_add_i32 m0, s3, 0x2000
	s_add_u32 s4, s0, 0x80000
	v_lshl_add_u64 v[166:167], s[0:1], 0, v[130:131]
	s_addc_u32 s5, s1, 0
	s_add_i32 s3, s6, s27
	global_load_lds_dwordx4 v130, s[0:1]
	s_mov_b32 m0, s3
	v_lshl_add_u64 v[180:181], s[14:15], 0, v[132:133]
	global_load_lds_dwordx4 v4, s[4:5]
	s_add_i32 m0, s3, 0x2000
	s_nop 0
	global_load_lds_dwordx4 v130, s[4:5]
	v_lshl_add_u64 v[176:177], s[14:15], 0, v[134:135]
	s_mov_b32 m0, s30
	s_nop 0
	global_load_lds_dwordx4 v134, s[14:15]
	s_mov_b32 m0, s31
	s_nop 0
	global_load_lds_dwordx4 v132, s[14:15]
	s_waitcnt vmcnt(24)
	s_waitcnt lgkmcnt(0)
	s_barrier
	s_waitcnt lgkmcnt(0)
	v_mfma_f32_16x16x32_bf16 v[94:97], v[144:147], v[210:213], v[94:97]
	v_mfma_f32_16x16x32_bf16 v[90:93], v[172:175], v[210:213], v[90:93]
	v_mfma_f32_16x16x32_bf16 v[86:89], v[144:147], v[218:221], v[86:89]
	v_mfma_f32_16x16x32_bf16 v[82:85], v[172:175], v[218:221], v[82:85]
	v_mfma_f32_16x16x32_bf16 v[78:81], v[144:147], v[226:229], v[78:81]
	v_mfma_f32_16x16x32_bf16 v[74:77], v[172:175], v[226:229], v[74:77]
	v_mfma_f32_16x16x32_bf16 v[62:65], v[144:147], v[234:237], v[62:65]
	v_mfma_f32_16x16x32_bf16 v[58:61], v[172:175], v[234:237], v[58:61]
	v_mfma_f32_16x16x32_bf16 v[94:97], v[148:151], v[214:217], v[94:97]
	v_mfma_f32_16x16x32_bf16 v[90:93], v[190:193], v[214:217], v[90:93]
	v_mfma_f32_16x16x32_bf16 v[86:89], v[148:151], v[222:225], v[86:89]
	v_mfma_f32_16x16x32_bf16 v[82:85], v[190:193], v[222:225], v[82:85]
	v_mfma_f32_16x16x32_bf16 v[78:81], v[148:151], v[230:233], v[78:81]
	v_mfma_f32_16x16x32_bf16 v[74:77], v[190:193], v[230:233], v[74:77]
	v_mfma_f32_16x16x32_bf16 v[62:65], v[148:151], v[238:241], v[62:65]
	v_mfma_f32_16x16x32_bf16 v[58:61], v[190:193], v[238:241], v[58:61]
	v_mfma_f32_16x16x32_bf16 v[30:33], v[194:197], v[210:213], v[30:33]
	v_mfma_f32_16x16x32_bf16 v[26:29], v[202:205], v[210:213], v[26:29]
	v_mfma_f32_16x16x32_bf16 v[22:25], v[194:197], v[218:221], v[22:25]
	v_mfma_f32_16x16x32_bf16 v[18:21], v[202:205], v[218:221], v[18:21]
	v_mfma_f32_16x16x32_bf16 v[14:17], v[194:197], v[226:229], v[14:17]
	v_mfma_f32_16x16x32_bf16 v[10:13], v[202:205], v[226:229], v[10:13]
	v_mfma_f32_16x16x32_bf16 v[6:9], v[194:197], v[234:237], v[6:9]
	v_mfma_f32_16x16x32_bf16 v[0:3], v[202:205], v[234:237], v[0:3]
	v_mfma_f32_16x16x32_bf16 v[30:33], v[198:201], v[214:217], v[30:33]
	v_mfma_f32_16x16x32_bf16 v[26:29], v[206:209], v[214:217], v[26:29]
	v_mfma_f32_16x16x32_bf16 v[22:25], v[198:201], v[222:225], v[22:25]
	v_mfma_f32_16x16x32_bf16 v[18:21], v[206:209], v[222:225], v[18:21]
	v_mfma_f32_16x16x32_bf16 v[14:17], v[198:201], v[230:233], v[14:17]
	v_mfma_f32_16x16x32_bf16 v[10:13], v[206:209], v[230:233], v[10:13]
	v_mfma_f32_16x16x32_bf16 v[6:9], v[198:201], v[238:241], v[6:9]
	v_mfma_f32_16x16x32_bf16 v[0:3], v[206:209], v[238:241], v[0:3]
	s_barrier
	s_branch .Lpeelmid_124
.LBB0_124:
	s_add_u32 s0, s22, 0xfff80080
	s_addc_u32 s1, s23, -1
	s_add_i32 s3, 0, 0x10000
	s_cmp_eq_u32 s28, 28
	s_cselect_b32 s15, s2, s1
	s_cselect_b32 s14, s8, s0
	v_add_u32_e32 v162, s3, v141
	s_cselect_b32 s1, s10, s25
	s_cselect_b32 s0, s24, s9
	s_add_i32 s6, 0, 0x14000
	ds_read_b128 v[144:147], v162
	ds_read_b128 v[148:151], v162 offset:1024
	ds_read_b128 v[172:175], v162 offset:2048
	ds_read_b128 v[190:193], v162 offset:3072
	v_add_u32_e32 v162, s6, v141
	ds_read_b128 v[194:197], v162
	ds_read_b128 v[198:201], v162 offset:1024
	ds_read_b128 v[202:205], v162 offset:2048
	ds_read_b128 v[206:209], v162 offset:3072
	s_add_i32 m0, s30, 0xc000
	ds_read_b128 v[210:213], v143
	ds_read_b128 v[214:217], v143 offset:1024
	ds_read_b128 v[218:221], v143 offset:2048
	ds_read_b128 v[222:225], v143 offset:3072
	ds_read_b128 v[226:229], v143 offset:4096
	ds_read_b128 v[230:233], v143 offset:5120
	ds_read_b128 v[234:237], v143 offset:6144
	ds_read_b128 v[238:241], v143 offset:7168
	global_load_lds_dwordx4 v136, s[22:23]
	s_add_i32 m0, s30, 0xe000
	s_nop 0
	global_load_lds_dwordx4 v138, s[22:23]
	s_waitcnt vmcnt(8)
	s_waitcnt lgkmcnt(0)
	s_barrier
	s_waitcnt lgkmcnt(0)
	v_mfma_f32_16x16x32_bf16 v[126:129], v[144:147], v[210:213], v[126:129]
	v_mfma_f32_16x16x32_bf16 v[122:125], v[172:175], v[210:213], v[122:125]
	v_mfma_f32_16x16x32_bf16 v[118:121], v[144:147], v[218:221], v[118:121]
	v_mfma_f32_16x16x32_bf16 v[114:117], v[172:175], v[218:221], v[114:117]
	v_mfma_f32_16x16x32_bf16 v[110:113], v[144:147], v[226:229], v[110:113]
	v_mfma_f32_16x16x32_bf16 v[106:109], v[172:175], v[226:229], v[106:109]
	v_mfma_f32_16x16x32_bf16 v[102:105], v[144:147], v[234:237], v[102:105]
	v_mfma_f32_16x16x32_bf16 v[98:101], v[172:175], v[234:237], v[98:101]
	v_mfma_f32_16x16x32_bf16 v[126:129], v[148:151], v[214:217], v[126:129]
	v_mfma_f32_16x16x32_bf16 v[122:125], v[190:193], v[214:217], v[122:125]
	v_mfma_f32_16x16x32_bf16 v[118:121], v[148:151], v[222:225], v[118:121]
	v_mfma_f32_16x16x32_bf16 v[114:117], v[190:193], v[222:225], v[114:117]
	v_mfma_f32_16x16x32_bf16 v[110:113], v[148:151], v[230:233], v[110:113]
	v_mfma_f32_16x16x32_bf16 v[106:109], v[190:193], v[230:233], v[106:109]
	v_mfma_f32_16x16x32_bf16 v[102:105], v[148:151], v[238:241], v[102:105]
	v_mfma_f32_16x16x32_bf16 v[98:101], v[190:193], v[238:241], v[98:101]
	v_mfma_f32_16x16x32_bf16 v[70:73], v[194:197], v[210:213], v[70:73]
	v_mfma_f32_16x16x32_bf16 v[66:69], v[202:205], v[210:213], v[66:69]
	v_mfma_f32_16x16x32_bf16 v[54:57], v[194:197], v[218:221], v[54:57]
	v_mfma_f32_16x16x32_bf16 v[50:53], v[202:205], v[218:221], v[50:53]
	v_mfma_f32_16x16x32_bf16 v[46:49], v[194:197], v[226:229], v[46:49]
	v_mfma_f32_16x16x32_bf16 v[42:45], v[202:205], v[226:229], v[42:45]
	v_mfma_f32_16x16x32_bf16 v[38:41], v[194:197], v[234:237], v[38:41]
	v_mfma_f32_16x16x32_bf16 v[34:37], v[202:205], v[234:237], v[34:37]
	v_mfma_f32_16x16x32_bf16 v[70:73], v[198:201], v[214:217], v[70:73]
	v_mfma_f32_16x16x32_bf16 v[66:69], v[206:209], v[214:217], v[66:69]
	v_mfma_f32_16x16x32_bf16 v[54:57], v[198:201], v[222:225], v[54:57]
	v_mfma_f32_16x16x32_bf16 v[50:53], v[206:209], v[222:225], v[50:53]
	v_mfma_f32_16x16x32_bf16 v[46:49], v[198:201], v[230:233], v[46:49]
	v_mfma_f32_16x16x32_bf16 v[42:45], v[206:209], v[230:233], v[42:45]
	v_mfma_f32_16x16x32_bf16 v[38:41], v[198:201], v[238:241], v[38:41]
	v_mfma_f32_16x16x32_bf16 v[34:37], v[206:209], v[238:241], v[34:37]
	s_barrier
	s_add_i32 s3, s3, s27
	v_lshl_add_u64 v[162:163], s[0:1], 0, v[4:5]
	s_mov_b32 m0, s3
	ds_read_b128 v[210:213], v143 offset:16384
	ds_read_b128 v[214:217], v143 offset:17408
	ds_read_b128 v[218:221], v143 offset:18432
	ds_read_b128 v[222:225], v143 offset:19456
	ds_read_b128 v[226:229], v143 offset:20480
	ds_read_b128 v[230:233], v143 offset:21504
	ds_read_b128 v[234:237], v143 offset:22528
	ds_read_b128 v[238:241], v143 offset:23552
	global_load_lds_dwordx4 v4, s[0:1]
	s_add_i32 m0, s3, 0x2000
	s_add_u32 s4, s0, 0x80000
	v_lshl_add_u64 v[166:167], s[0:1], 0, v[130:131]
	s_addc_u32 s5, s1, 0
	s_add_i32 s3, s6, s27
	global_load_lds_dwordx4 v130, s[0:1]
	s_mov_b32 m0, s3
	v_lshl_add_u64 v[180:181], s[14:15], 0, v[132:133]
	global_load_lds_dwordx4 v4, s[4:5]
	s_add_i32 m0, s3, 0x2000
	s_nop 0
	global_load_lds_dwordx4 v130, s[4:5]
	v_lshl_add_u64 v[176:177], s[14:15], 0, v[134:135]
	s_mov_b32 m0, s30
	s_nop 0
	global_load_lds_dwordx4 v134, s[14:15]
	s_mov_b32 m0, s31
	s_nop 0
	global_load_lds_dwordx4 v132, s[14:15]
	s_waitcnt vmcnt(8)
	s_waitcnt lgkmcnt(0)
	s_barrier
	s_waitcnt lgkmcnt(0)
	v_mfma_f32_16x16x32_bf16 v[94:97], v[144:147], v[210:213], v[94:97]
	v_mfma_f32_16x16x32_bf16 v[90:93], v[172:175], v[210:213], v[90:93]
	v_mfma_f32_16x16x32_bf16 v[86:89], v[144:147], v[218:221], v[86:89]
	v_mfma_f32_16x16x32_bf16 v[82:85], v[172:175], v[218:221], v[82:85]
	v_mfma_f32_16x16x32_bf16 v[78:81], v[144:147], v[226:229], v[78:81]
	v_mfma_f32_16x16x32_bf16 v[74:77], v[172:175], v[226:229], v[74:77]
	v_mfma_f32_16x16x32_bf16 v[62:65], v[144:147], v[234:237], v[62:65]
	v_mfma_f32_16x16x32_bf16 v[58:61], v[172:175], v[234:237], v[58:61]
	v_mfma_f32_16x16x32_bf16 v[94:97], v[148:151], v[214:217], v[94:97]
	v_mfma_f32_16x16x32_bf16 v[90:93], v[190:193], v[214:217], v[90:93]
	v_mfma_f32_16x16x32_bf16 v[86:89], v[148:151], v[222:225], v[86:89]
	v_mfma_f32_16x16x32_bf16 v[82:85], v[190:193], v[222:225], v[82:85]
	v_mfma_f32_16x16x32_bf16 v[78:81], v[148:151], v[230:233], v[78:81]
	v_mfma_f32_16x16x32_bf16 v[74:77], v[190:193], v[230:233], v[74:77]
	v_mfma_f32_16x16x32_bf16 v[62:65], v[148:151], v[238:241], v[62:65]
	v_mfma_f32_16x16x32_bf16 v[58:61], v[190:193], v[238:241], v[58:61]
	v_mfma_f32_16x16x32_bf16 v[30:33], v[194:197], v[210:213], v[30:33]
	v_mfma_f32_16x16x32_bf16 v[26:29], v[202:205], v[210:213], v[26:29]
	v_mfma_f32_16x16x32_bf16 v[22:25], v[194:197], v[218:221], v[22:25]
	v_mfma_f32_16x16x32_bf16 v[18:21], v[202:205], v[218:221], v[18:21]
	v_mfma_f32_16x16x32_bf16 v[14:17], v[194:197], v[226:229], v[14:17]
	v_mfma_f32_16x16x32_bf16 v[10:13], v[202:205], v[226:229], v[10:13]
	v_mfma_f32_16x16x32_bf16 v[6:9], v[194:197], v[234:237], v[6:9]
	v_mfma_f32_16x16x32_bf16 v[0:3], v[202:205], v[234:237], v[0:3]
	v_mfma_f32_16x16x32_bf16 v[30:33], v[198:201], v[214:217], v[30:33]
	v_mfma_f32_16x16x32_bf16 v[26:29], v[206:209], v[214:217], v[26:29]
	v_mfma_f32_16x16x32_bf16 v[22:25], v[198:201], v[222:225], v[22:25]
	v_mfma_f32_16x16x32_bf16 v[18:21], v[206:209], v[222:225], v[18:21]
	v_mfma_f32_16x16x32_bf16 v[14:17], v[198:201], v[230:233], v[14:17]
	v_mfma_f32_16x16x32_bf16 v[10:13], v[206:209], v[230:233], v[10:13]
	v_mfma_f32_16x16x32_bf16 v[6:9], v[198:201], v[238:241], v[6:9]
	v_mfma_f32_16x16x32_bf16 v[0:3], v[206:209], v[238:241], v[0:3]
	s_barrier
.Lpeelmid_124:
	s_add_i32 s3, 0, 0x18000
	v_add_u32_e32 v164, s3, v141
	s_add_i32 s6, 0, 0x1c000
	ds_read_b128 v[144:147], v164
	ds_read_b128 v[148:151], v164 offset:1024
	ds_read_b128 v[172:175], v164 offset:2048
	ds_read_b128 v[190:193], v164 offset:3072
	v_add_u32_e32 v164, s6, v141
	ds_read_b128 v[194:197], v164
	ds_read_b128 v[198:201], v164 offset:1024
	ds_read_b128 v[202:205], v164 offset:2048
	ds_read_b128 v[206:209], v164 offset:3072
	s_add_u32 s4, s14, 0x80000
	s_addc_u32 s5, s15, 0
	s_mov_b32 m0, s34
	ds_read_b128 v[210:213], v143 offset:32768
	ds_read_b128 v[214:217], v143 offset:33792
	ds_read_b128 v[218:221], v143 offset:34816
	ds_read_b128 v[222:225], v143 offset:35840
	ds_read_b128 v[226:229], v143 offset:36864
	ds_read_b128 v[230:233], v143 offset:37888
	ds_read_b128 v[234:237], v143 offset:38912
	ds_read_b128 v[238:241], v143 offset:39936
	global_load_lds_dwordx4 v134, s[4:5]
	v_lshl_add_u64 v[242:243], s[4:5], 0, v[132:133]
	s_mov_b32 m0, s35
	s_nop 0
	global_load_lds_dwordx4 v132, s[4:5]
	s_waitcnt vmcnt(8)
	s_waitcnt lgkmcnt(0)
	s_barrier
	s_waitcnt lgkmcnt(0)
	v_mfma_f32_16x16x32_bf16 v[126:129], v[144:147], v[210:213], v[126:129]
	v_mfma_f32_16x16x32_bf16 v[122:125], v[172:175], v[210:213], v[122:125]
	v_mfma_f32_16x16x32_bf16 v[118:121], v[144:147], v[218:221], v[118:121]
	v_mfma_f32_16x16x32_bf16 v[114:117], v[172:175], v[218:221], v[114:117]
	v_mfma_f32_16x16x32_bf16 v[110:113], v[144:147], v[226:229], v[110:113]
	v_mfma_f32_16x16x32_bf16 v[106:109], v[172:175], v[226:229], v[106:109]
	v_mfma_f32_16x16x32_bf16 v[102:105], v[144:147], v[234:237], v[102:105]
	v_mfma_f32_16x16x32_bf16 v[98:101], v[172:175], v[234:237], v[98:101]
	v_mfma_f32_16x16x32_bf16 v[126:129], v[148:151], v[214:217], v[126:129]
	v_mfma_f32_16x16x32_bf16 v[122:125], v[190:193], v[214:217], v[122:125]
	v_mfma_f32_16x16x32_bf16 v[118:121], v[148:151], v[222:225], v[118:121]
	v_mfma_f32_16x16x32_bf16 v[114:117], v[190:193], v[222:225], v[114:117]
	v_mfma_f32_16x16x32_bf16 v[110:113], v[148:151], v[230:233], v[110:113]
	v_mfma_f32_16x16x32_bf16 v[106:109], v[190:193], v[230:233], v[106:109]
	v_mfma_f32_16x16x32_bf16 v[102:105], v[148:151], v[238:241], v[102:105]
	v_mfma_f32_16x16x32_bf16 v[98:101], v[190:193], v[238:241], v[98:101]
	v_mfma_f32_16x16x32_bf16 v[70:73], v[194:197], v[210:213], v[70:73]
	v_mfma_f32_16x16x32_bf16 v[66:69], v[202:205], v[210:213], v[66:69]
	v_mfma_f32_16x16x32_bf16 v[54:57], v[194:197], v[218:221], v[54:57]
	v_mfma_f32_16x16x32_bf16 v[50:53], v[202:205], v[218:221], v[50:53]
	v_mfma_f32_16x16x32_bf16 v[46:49], v[194:197], v[226:229], v[46:49]
	v_mfma_f32_16x16x32_bf16 v[42:45], v[202:205], v[226:229], v[42:45]
	v_mfma_f32_16x16x32_bf16 v[38:41], v[194:197], v[234:237], v[38:41]
	v_mfma_f32_16x16x32_bf16 v[34:37], v[202:205], v[234:237], v[34:37]
	v_mfma_f32_16x16x32_bf16 v[70:73], v[198:201], v[214:217], v[70:73]
	v_mfma_f32_16x16x32_bf16 v[66:69], v[206:209], v[214:217], v[66:69]
	v_mfma_f32_16x16x32_bf16 v[54:57], v[198:201], v[222:225], v[54:57]
	v_mfma_f32_16x16x32_bf16 v[50:53], v[206:209], v[222:225], v[50:53]
	v_mfma_f32_16x16x32_bf16 v[46:49], v[198:201], v[230:233], v[46:49]
	v_mfma_f32_16x16x32_bf16 v[42:45], v[206:209], v[230:233], v[42:45]
	v_mfma_f32_16x16x32_bf16 v[38:41], v[198:201], v[238:241], v[38:41]
	v_mfma_f32_16x16x32_bf16 v[34:37], v[206:209], v[238:241], v[34:37]
	s_barrier
	s_add_i32 s3, s3, s27
	v_lshl_add_u64 v[162:163], v[162:163], 0, s[70:71]
	s_mov_b32 m0, s3
	ds_read_b128 v[210:213], v143 offset:49152
	ds_read_b128 v[214:217], v143 offset:50176
	ds_read_b128 v[218:221], v143 offset:51200
	ds_read_b128 v[222:225], v143 offset:52224
	ds_read_b128 v[226:229], v143 offset:53248
	ds_read_b128 v[230:233], v143 offset:54272
	ds_read_b128 v[234:237], v143 offset:55296
	ds_read_b128 v[238:241], v143 offset:56320
	global_load_lds_dwordx4 v[162:163], off
	s_add_i32 m0, s3, 0x2000
	s_add_u32 s0, s0, 0x80080
	v_lshl_add_u64 v[162:163], v[166:167], 0, s[70:71]
	s_addc_u32 s1, s1, 0
	s_add_i32 s3, s6, s27
	global_load_lds_dwordx4 v[162:163], off
	s_mov_b32 m0, s3
	s_nop 0
	global_load_lds_dwordx4 v4, s[0:1]
	s_add_i32 m0, s3, 0x2000
	s_nop 0
	global_load_lds_dwordx4 v130, s[0:1]
	v_lshl_add_u64 v[162:163], v[176:177], 0, s[70:71]
	s_mov_b32 m0, s36
	s_nop 0
	global_load_lds_dwordx4 v[162:163], off
	v_lshl_add_u64 v[162:163], v[180:181], 0, s[70:71]
	s_mov_b32 m0, s37
	s_nop 0
	global_load_lds_dwordx4 v[162:163], off
	s_waitcnt vmcnt(8)
	s_waitcnt lgkmcnt(0)
	s_barrier
	s_waitcnt lgkmcnt(0)
	v_mfma_f32_16x16x32_bf16 v[94:97], v[144:147], v[210:213], v[94:97]
	v_mfma_f32_16x16x32_bf16 v[90:93], v[172:175], v[210:213], v[90:93]
	v_mfma_f32_16x16x32_bf16 v[86:89], v[144:147], v[218:221], v[86:89]
	v_mfma_f32_16x16x32_bf16 v[82:85], v[172:175], v[218:221], v[82:85]
	v_mfma_f32_16x16x32_bf16 v[78:81], v[144:147], v[226:229], v[78:81]
	v_mfma_f32_16x16x32_bf16 v[74:77], v[172:175], v[226:229], v[74:77]
	v_mfma_f32_16x16x32_bf16 v[62:65], v[144:147], v[234:237], v[62:65]
	v_mfma_f32_16x16x32_bf16 v[58:61], v[172:175], v[234:237], v[58:61]
	v_mfma_f32_16x16x32_bf16 v[94:97], v[148:151], v[214:217], v[94:97]
	v_mfma_f32_16x16x32_bf16 v[90:93], v[190:193], v[214:217], v[90:93]
	v_mfma_f32_16x16x32_bf16 v[86:89], v[148:151], v[222:225], v[86:89]
	v_mfma_f32_16x16x32_bf16 v[82:85], v[190:193], v[222:225], v[82:85]
	v_mfma_f32_16x16x32_bf16 v[78:81], v[148:151], v[230:233], v[78:81]
	v_mfma_f32_16x16x32_bf16 v[74:77], v[190:193], v[230:233], v[74:77]
	v_mfma_f32_16x16x32_bf16 v[62:65], v[148:151], v[238:241], v[62:65]
	v_mfma_f32_16x16x32_bf16 v[58:61], v[190:193], v[238:241], v[58:61]
	v_mfma_f32_16x16x32_bf16 v[30:33], v[194:197], v[210:213], v[30:33]
	v_mfma_f32_16x16x32_bf16 v[26:29], v[202:205], v[210:213], v[26:29]
	v_mfma_f32_16x16x32_bf16 v[22:25], v[194:197], v[218:221], v[22:25]
	v_mfma_f32_16x16x32_bf16 v[18:21], v[202:205], v[218:221], v[18:21]
	v_mfma_f32_16x16x32_bf16 v[14:17], v[194:197], v[226:229], v[14:17]
	v_mfma_f32_16x16x32_bf16 v[10:13], v[202:205], v[226:229], v[10:13]
	v_mfma_f32_16x16x32_bf16 v[6:9], v[194:197], v[234:237], v[6:9]
	v_mfma_f32_16x16x32_bf16 v[0:3], v[202:205], v[234:237], v[0:3]
	v_mfma_f32_16x16x32_bf16 v[30:33], v[198:201], v[214:217], v[30:33]
	v_mfma_f32_16x16x32_bf16 v[26:29], v[206:209], v[214:217], v[26:29]
	v_mfma_f32_16x16x32_bf16 v[22:25], v[198:201], v[222:225], v[22:25]
	v_mfma_f32_16x16x32_bf16 v[18:21], v[206:209], v[222:225], v[18:21]
	v_mfma_f32_16x16x32_bf16 v[14:17], v[198:201], v[230:233], v[14:17]
	v_mfma_f32_16x16x32_bf16 v[10:13], v[206:209], v[230:233], v[10:13]
	v_mfma_f32_16x16x32_bf16 v[6:9], v[198:201], v[238:241], v[6:9]
	v_mfma_f32_16x16x32_bf16 v[0:3], v[206:209], v[238:241], v[0:3]
	s_barrier
	s_add_i32 s28, s28, 2
	s_add_u32 s22, s22, 0x100
	s_addc_u32 s23, s23, 0
	s_add_u32 s9, s9, 0x100
	s_addc_u32 s25, s25, 0
	s_cmp_gt_u32 s28, 29
	s_cbranch_scc0 .LBB0_124
	s_and_b64 vcc, exec, s[42:43]
	s_cbranch_vccz .LBB0_127
	s_barrier

.LBB0_162:
	s_ashr_i32 s49, s48, 31
	s_lshl_b64 s[2:3], s[48:49], 20
	v_readlane_b32 s4, v253, 61
	v_readlane_b32 s5, v253, 62
	s_add_u32 s82, s4, s2
	s_addc_u32 s83, s5, s3
	s_and_b64 s[2:3], s[42:43], exec
	s_cselect_b32 s2, s83, s1
	s_cselect_b32 s8, s82, s0
	s_add_u32 s22, s14, 0x80080
	s_addc_u32 s23, s15, 0
	s_add_u32 s9, s0, 0x100
	v_mov_b32_e32 v0, 0
	s_addc_u32 s10, s1, 0
	s_mov_b32 s24, -2
	v_mov_b32_e32 v1, v0
	v_mov_b32_e32 v2, v0
	v_mov_b32_e32 v3, v0
	v_mov_b32_e32 v6, v0
	s_waitcnt lgkmcnt(0)
	v_mov_b32_e32 v7, v0
	v_mov_b32_e32 v8, v0
	v_mov_b32_e32 v9, v0
	v_mov_b32_e32 v18, v0
	v_mov_b32_e32 v19, v0
	v_mov_b32_e32 v20, v0
	v_mov_b32_e32 v21, v0
	v_mov_b32_e32 v22, v0
	v_mov_b32_e32 v23, v0
	v_mov_b32_e32 v24, v0
	v_mov_b32_e32 v25, v0
	v_mov_b32_e32 v34, v0
	v_mov_b32_e32 v35, v0
	v_mov_b32_e32 v36, v0
	v_mov_b32_e32 v37, v0
	v_mov_b32_e32 v38, v0
	v_mov_b32_e32 v39, v0
	v_mov_b32_e32 v40, v0
	v_mov_b32_e32 v41, v0
	v_mov_b32_e32 v50, v0
	v_mov_b32_e32 v51, v0
	v_mov_b32_e32 v52, v0
	v_mov_b32_e32 v53, v0
	v_mov_b32_e32 v54, v0
	v_mov_b32_e32 v55, v0
	v_mov_b32_e32 v56, v0
	v_mov_b32_e32 v57, v0
	v_mov_b32_e32 v10, v0
	v_mov_b32_e32 v11, v0
	v_mov_b32_e32 v12, v0
	v_mov_b32_e32 v13, v0
	v_mov_b32_e32 v14, v0
	v_mov_b32_e32 v15, v0
	v_mov_b32_e32 v16, v0
	v_mov_b32_e32 v17, v0
	v_mov_b32_e32 v26, v0
	v_mov_b32_e32 v27, v0
	v_mov_b32_e32 v28, v0
	v_mov_b32_e32 v29, v0
	v_mov_b32_e32 v30, v0
	v_mov_b32_e32 v31, v0
	v_mov_b32_e32 v32, v0
	v_mov_b32_e32 v33, v0
	v_mov_b32_e32 v42, v0
	v_mov_b32_e32 v43, v0
	v_mov_b32_e32 v44, v0
	v_mov_b32_e32 v45, v0
	v_mov_b32_e32 v46, v0
	v_mov_b32_e32 v47, v0
	v_mov_b32_e32 v48, v0
	v_mov_b32_e32 v49, v0
	v_mov_b32_e32 v58, v0
	v_mov_b32_e32 v59, v0
	v_mov_b32_e32 v60, v0
	v_mov_b32_e32 v61, v0
	v_mov_b32_e32 v62, v0
	v_mov_b32_e32 v63, v0
	v_mov_b32_e32 v64, v0
	v_mov_b32_e32 v65, v0
	v_mov_b32_e32 v66, v0
	v_mov_b32_e32 v67, v0
	v_mov_b32_e32 v68, v0
	v_mov_b32_e32 v69, v0
	v_mov_b32_e32 v70, v0
	v_mov_b32_e32 v71, v0
	v_mov_b32_e32 v72, v0
	v_mov_b32_e32 v73, v0
	v_mov_b32_e32 v82, v0
	v_mov_b32_e32 v83, v0
	v_mov_b32_e32 v84, v0
	v_mov_b32_e32 v85, v0
	v_mov_b32_e32 v86, v0
	v_mov_b32_e32 v87, v0
	v_mov_b32_e32 v88, v0
	v_mov_b32_e32 v89, v0
	v_mov_b32_e32 v98, v0
	v_mov_b32_e32 v99, v0
	v_mov_b32_e32 v100, v0
	v_mov_b32_e32 v101, v0
	v_mov_b32_e32 v102, v0
	v_mov_b32_e32 v103, v0
	v_mov_b32_e32 v104, v0
	v_mov_b32_e32 v105, v0
	v_mov_b32_e32 v114, v0
	v_mov_b32_e32 v115, v0
	v_mov_b32_e32 v116, v0
	v_mov_b32_e32 v117, v0
	v_mov_b32_e32 v118, v0
	v_mov_b32_e32 v119, v0
	v_mov_b32_e32 v120, v0
	v_mov_b32_e32 v121, v0
	v_mov_b32_e32 v74, v0
	v_mov_b32_e32 v75, v0
	v_mov_b32_e32 v76, v0
	v_mov_b32_e32 v77, v0
	v_mov_b32_e32 v78, v0
	v_mov_b32_e32 v79, v0
	v_mov_b32_e32 v80, v0
	v_mov_b32_e32 v81, v0
	v_mov_b32_e32 v90, v0
	v_mov_b32_e32 v91, v0
	v_mov_b32_e32 v92, v0
	v_mov_b32_e32 v93, v0
	v_mov_b32_e32 v94, v0
	v_mov_b32_e32 v95, v0
	v_mov_b32_e32 v96, v0
	v_mov_b32_e32 v97, v0
	v_mov_b32_e32 v106, v0
	v_mov_b32_e32 v107, v0
	v_mov_b32_e32 v108, v0
	v_mov_b32_e32 v109, v0
	v_mov_b32_e32 v110, v0
	v_mov_b32_e32 v111, v0
	v_mov_b32_e32 v112, v0
	v_mov_b32_e32 v113, v0
	v_mov_b32_e32 v122, v0
	v_mov_b32_e32 v123, v0
	v_mov_b32_e32 v124, v0
	v_mov_b32_e32 v125, v0
	v_mov_b32_e32 v126, v0
	v_mov_b32_e32 v127, v0
	v_mov_b32_e32 v128, v0
	v_mov_b32_e32 v129, v0
	s_cmp_eq_u32 s37, 1
	s_cbranch_scc1 .LBB0_163
	s_add_u32 s0, s22, 0xfff80080
	s_addc_u32 s1, s23, -1
	s_add_i32 s3, 0, 0x10000
	s_cmp_eq_u32 s24, 28
	s_cselect_b32 s15, s79, s1
	s_cselect_b32 s14, s78, s0
	v_add_u32_e32 v162, s3, v145
	s_cselect_b32 s1, s2, s10
	s_cselect_b32 s0, s8, s9
	s_add_i32 s6, 0, 0x14000
	ds_read_b128 v[140:143], v162
	ds_read_b128 v[148:151], v162 offset:1024
	ds_read_b128 v[172:175], v162 offset:2048
	ds_read_b128 v[190:193], v162 offset:3072
	v_add_u32_e32 v162, s6, v145
	ds_read_b128 v[194:197], v162
	ds_read_b128 v[198:201], v162 offset:1024
	ds_read_b128 v[202:205], v162 offset:2048
	ds_read_b128 v[206:209], v162 offset:3072
	s_add_i32 m0, s26, 0xc000
	ds_read_b128 v[210:213], v147
	ds_read_b128 v[214:217], v147 offset:1024
	ds_read_b128 v[218:221], v147 offset:2048
	ds_read_b128 v[222:225], v147 offset:3072
	ds_read_b128 v[226:229], v147 offset:4096
	ds_read_b128 v[230:233], v147 offset:5120
	ds_read_b128 v[234:237], v147 offset:6144
	ds_read_b128 v[238:241], v147 offset:7168
	global_load_lds_dwordx4 v136, s[22:23]
	s_add_i32 m0, s26, 0xe000
	s_nop 0
	global_load_lds_dwordx4 v138, s[22:23]
	s_waitcnt vmcnt(24)
	s_waitcnt lgkmcnt(0)
	s_barrier
	s_waitcnt lgkmcnt(0)
	v_mfma_f32_16x16x32_bf16 v[126:129], v[140:143], v[210:213], v[126:129]
	v_mfma_f32_16x16x32_bf16 v[122:125], v[172:175], v[210:213], v[122:125]
	v_mfma_f32_16x16x32_bf16 v[110:113], v[140:143], v[218:221], v[110:113]
	v_mfma_f32_16x16x32_bf16 v[106:109], v[172:175], v[218:221], v[106:109]
	v_mfma_f32_16x16x32_bf16 v[94:97], v[140:143], v[226:229], v[94:97]
	v_mfma_f32_16x16x32_bf16 v[90:93], v[172:175], v[226:229], v[90:93]
	v_mfma_f32_16x16x32_bf16 v[78:81], v[140:143], v[234:237], v[78:81]
	v_mfma_f32_16x16x32_bf16 v[74:77], v[172:175], v[234:237], v[74:77]
	v_mfma_f32_16x16x32_bf16 v[126:129], v[148:151], v[214:217], v[126:129]
	v_mfma_f32_16x16x32_bf16 v[122:125], v[190:193], v[214:217], v[122:125]
	v_mfma_f32_16x16x32_bf16 v[110:113], v[148:151], v[222:225], v[110:113]
	v_mfma_f32_16x16x32_bf16 v[106:109], v[190:193], v[222:225], v[106:109]
	v_mfma_f32_16x16x32_bf16 v[94:97], v[148:151], v[230:233], v[94:97]
	v_mfma_f32_16x16x32_bf16 v[90:93], v[190:193], v[230:233], v[90:93]
	v_mfma_f32_16x16x32_bf16 v[78:81], v[148:151], v[238:241], v[78:81]
	v_mfma_f32_16x16x32_bf16 v[74:77], v[190:193], v[238:241], v[74:77]
	v_mfma_f32_16x16x32_bf16 v[118:121], v[194:197], v[210:213], v[118:121]
	v_mfma_f32_16x16x32_bf16 v[114:117], v[202:205], v[210:213], v[114:117]
	v_mfma_f32_16x16x32_bf16 v[102:105], v[194:197], v[218:221], v[102:105]
	v_mfma_f32_16x16x32_bf16 v[98:101], v[202:205], v[218:221], v[98:101]
	v_mfma_f32_16x16x32_bf16 v[86:89], v[194:197], v[226:229], v[86:89]
	v_mfma_f32_16x16x32_bf16 v[82:85], v[202:205], v[226:229], v[82:85]
	v_mfma_f32_16x16x32_bf16 v[70:73], v[194:197], v[234:237], v[70:73]
	v_mfma_f32_16x16x32_bf16 v[66:69], v[202:205], v[234:237], v[66:69]
	v_mfma_f32_16x16x32_bf16 v[118:121], v[198:201], v[214:217], v[118:121]
	v_mfma_f32_16x16x32_bf16 v[114:117], v[206:209], v[214:217], v[114:117]
	v_mfma_f32_16x16x32_bf16 v[102:105], v[198:201], v[222:225], v[102:105]
	v_mfma_f32_16x16x32_bf16 v[98:101], v[206:209], v[222:225], v[98:101]
	v_mfma_f32_16x16x32_bf16 v[86:89], v[198:201], v[230:233], v[86:89]
	v_mfma_f32_16x16x32_bf16 v[82:85], v[206:209], v[230:233], v[82:85]
	v_mfma_f32_16x16x32_bf16 v[70:73], v[198:201], v[238:241], v[70:73]
	v_mfma_f32_16x16x32_bf16 v[66:69], v[206:209], v[238:241], v[66:69]
	s_barrier
	s_add_i32 s3, s3, s11
	v_lshl_add_u64 v[162:163], s[0:1], 0, v[4:5]
	s_mov_b32 m0, s3
	ds_read_b128 v[210:213], v147 offset:16384
	ds_read_b128 v[214:217], v147 offset:17408
	ds_read_b128 v[218:221], v147 offset:18432
	ds_read_b128 v[222:225], v147 offset:19456
	ds_read_b128 v[226:229], v147 offset:20480
	ds_read_b128 v[230:233], v147 offset:21504
	ds_read_b128 v[234:237], v147 offset:22528
	ds_read_b128 v[238:241], v147 offset:23552
	global_load_lds_dwordx4 v4, s[0:1]
	s_add_i32 m0, s3, 0x2000
	s_add_u32 s4, s0, 0x80000
	v_lshl_add_u64 v[166:167], s[0:1], 0, v[130:131]
	s_addc_u32 s5, s1, 0
	s_add_i32 s3, s6, s11
	global_load_lds_dwordx4 v130, s[0:1]
	s_mov_b32 m0, s3
	v_lshl_add_u64 v[180:181], s[14:15], 0, v[132:133]
	global_load_lds_dwordx4 v4, s[4:5]
	s_add_i32 m0, s3, 0x2000
	s_nop 0
	global_load_lds_dwordx4 v130, s[4:5]
	v_lshl_add_u64 v[176:177], s[14:15], 0, v[134:135]
	s_mov_b32 m0, s26
	s_nop 0
	global_load_lds_dwordx4 v134, s[14:15]
	s_mov_b32 m0, s27
	s_nop 0
	global_load_lds_dwordx4 v132, s[14:15]
	s_waitcnt vmcnt(24)
	s_waitcnt lgkmcnt(0)
	s_barrier
	s_waitcnt lgkmcnt(0)
	v_mfma_f32_16x16x32_bf16 v[62:65], v[140:143], v[210:213], v[62:65]
	v_mfma_f32_16x16x32_bf16 v[58:61], v[172:175], v[210:213], v[58:61]
	v_mfma_f32_16x16x32_bf16 v[46:49], v[140:143], v[218:221], v[46:49]
	v_mfma_f32_16x16x32_bf16 v[42:45], v[172:175], v[218:221], v[42:45]
	v_mfma_f32_16x16x32_bf16 v[30:33], v[140:143], v[226:229], v[30:33]
	v_mfma_f32_16x16x32_bf16 v[26:29], v[172:175], v[226:229], v[26:29]
	v_mfma_f32_16x16x32_bf16 v[14:17], v[140:143], v[234:237], v[14:17]
	v_mfma_f32_16x16x32_bf16 v[10:13], v[172:175], v[234:237], v[10:13]
	v_mfma_f32_16x16x32_bf16 v[62:65], v[148:151], v[214:217], v[62:65]
	v_mfma_f32_16x16x32_bf16 v[58:61], v[190:193], v[214:217], v[58:61]
	v_mfma_f32_16x16x32_bf16 v[46:49], v[148:151], v[222:225], v[46:49]
	v_mfma_f32_16x16x32_bf16 v[42:45], v[190:193], v[222:225], v[42:45]
	v_mfma_f32_16x16x32_bf16 v[30:33], v[148:151], v[230:233], v[30:33]
	v_mfma_f32_16x16x32_bf16 v[26:29], v[190:193], v[230:233], v[26:29]
	v_mfma_f32_16x16x32_bf16 v[14:17], v[148:151], v[238:241], v[14:17]
	v_mfma_f32_16x16x32_bf16 v[10:13], v[190:193], v[238:241], v[10:13]
	v_mfma_f32_16x16x32_bf16 v[54:57], v[194:197], v[210:213], v[54:57]
	v_mfma_f32_16x16x32_bf16 v[50:53], v[202:205], v[210:213], v[50:53]
	v_mfma_f32_16x16x32_bf16 v[38:41], v[194:197], v[218:221], v[38:41]
	v_mfma_f32_16x16x32_bf16 v[34:37], v[202:205], v[218:221], v[34:37]
	v_mfma_f32_16x16x32_bf16 v[22:25], v[194:197], v[226:229], v[22:25]
	v_mfma_f32_16x16x32_bf16 v[18:21], v[202:205], v[226:229], v[18:21]
	v_mfma_f32_16x16x32_bf16 v[6:9], v[194:197], v[234:237], v[6:9]
	v_mfma_f32_16x16x32_bf16 v[0:3], v[202:205], v[234:237], v[0:3]
	v_mfma_f32_16x16x32_bf16 v[54:57], v[198:201], v[214:217], v[54:57]
	v_mfma_f32_16x16x32_bf16 v[50:53], v[206:209], v[214:217], v[50:53]
	v_mfma_f32_16x16x32_bf16 v[38:41], v[198:201], v[222:225], v[38:41]
	v_mfma_f32_16x16x32_bf16 v[34:37], v[206:209], v[222:225], v[34:37]
	v_mfma_f32_16x16x32_bf16 v[22:25], v[198:201], v[230:233], v[22:25]
	v_mfma_f32_16x16x32_bf16 v[18:21], v[206:209], v[230:233], v[18:21]
	v_mfma_f32_16x16x32_bf16 v[6:9], v[198:201], v[238:241], v[6:9]
	v_mfma_f32_16x16x32_bf16 v[0:3], v[206:209], v[238:241], v[0:3]
	s_barrier
	s_branch .Lpeelmid_163
.LBB0_163:
	s_add_u32 s0, s22, 0xfff80080
	s_addc_u32 s1, s23, -1
	s_add_i32 s3, 0, 0x10000
	s_cmp_eq_u32 s24, 28
	s_cselect_b32 s15, s79, s1
	s_cselect_b32 s14, s78, s0
	v_add_u32_e32 v162, s3, v145
	s_cselect_b32 s1, s2, s10
	s_cselect_b32 s0, s8, s9
	s_add_i32 s6, 0, 0x14000
	ds_read_b128 v[140:143], v162
	ds_read_b128 v[148:151], v162 offset:1024
	ds_read_b128 v[172:175], v162 offset:2048
	ds_read_b128 v[190:193], v162 offset:3072
	v_add_u32_e32 v162, s6, v145
	ds_read_b128 v[194:197], v162
	ds_read_b128 v[198:201], v162 offset:1024
	ds_read_b128 v[202:205], v162 offset:2048
	ds_read_b128 v[206:209], v162 offset:3072
	s_add_i32 m0, s26, 0xc000
	ds_read_b128 v[210:213], v147
	ds_read_b128 v[214:217], v147 offset:1024
	ds_read_b128 v[218:221], v147 offset:2048
	ds_read_b128 v[222:225], v147 offset:3072
	ds_read_b128 v[226:229], v147 offset:4096
	ds_read_b128 v[230:233], v147 offset:5120
	ds_read_b128 v[234:237], v147 offset:6144
	ds_read_b128 v[238:241], v147 offset:7168
	global_load_lds_dwordx4 v136, s[22:23]
	s_add_i32 m0, s26, 0xe000
	s_nop 0
	global_load_lds_dwordx4 v138, s[22:23]
	s_waitcnt vmcnt(8)
	s_waitcnt lgkmcnt(0)
	s_barrier
	s_waitcnt lgkmcnt(0)
	v_mfma_f32_16x16x32_bf16 v[126:129], v[140:143], v[210:213], v[126:129]
	v_mfma_f32_16x16x32_bf16 v[122:125], v[172:175], v[210:213], v[122:125]
	v_mfma_f32_16x16x32_bf16 v[110:113], v[140:143], v[218:221], v[110:113]
	v_mfma_f32_16x16x32_bf16 v[106:109], v[172:175], v[218:221], v[106:109]
	v_mfma_f32_16x16x32_bf16 v[94:97], v[140:143], v[226:229], v[94:97]
	v_mfma_f32_16x16x32_bf16 v[90:93], v[172:175], v[226:229], v[90:93]
	v_mfma_f32_16x16x32_bf16 v[78:81], v[140:143], v[234:237], v[78:81]
	v_mfma_f32_16x16x32_bf16 v[74:77], v[172:175], v[234:237], v[74:77]
	v_mfma_f32_16x16x32_bf16 v[126:129], v[148:151], v[214:217], v[126:129]
	v_mfma_f32_16x16x32_bf16 v[122:125], v[190:193], v[214:217], v[122:125]
	v_mfma_f32_16x16x32_bf16 v[110:113], v[148:151], v[222:225], v[110:113]
	v_mfma_f32_16x16x32_bf16 v[106:109], v[190:193], v[222:225], v[106:109]
	v_mfma_f32_16x16x32_bf16 v[94:97], v[148:151], v[230:233], v[94:97]
	v_mfma_f32_16x16x32_bf16 v[90:93], v[190:193], v[230:233], v[90:93]
	v_mfma_f32_16x16x32_bf16 v[78:81], v[148:151], v[238:241], v[78:81]
	v_mfma_f32_16x16x32_bf16 v[74:77], v[190:193], v[238:241], v[74:77]
	v_mfma_f32_16x16x32_bf16 v[118:121], v[194:197], v[210:213], v[118:121]
	v_mfma_f32_16x16x32_bf16 v[114:117], v[202:205], v[210:213], v[114:117]
	v_mfma_f32_16x16x32_bf16 v[102:105], v[194:197], v[218:221], v[102:105]
	v_mfma_f32_16x16x32_bf16 v[98:101], v[202:205], v[218:221], v[98:101]
	v_mfma_f32_16x16x32_bf16 v[86:89], v[194:197], v[226:229], v[86:89]
	v_mfma_f32_16x16x32_bf16 v[82:85], v[202:205], v[226:229], v[82:85]
	v_mfma_f32_16x16x32_bf16 v[70:73], v[194:197], v[234:237], v[70:73]
	v_mfma_f32_16x16x32_bf16 v[66:69], v[202:205], v[234:237], v[66:69]
	v_mfma_f32_16x16x32_bf16 v[118:121], v[198:201], v[214:217], v[118:121]
	v_mfma_f32_16x16x32_bf16 v[114:117], v[206:209], v[214:217], v[114:117]
	v_mfma_f32_16x16x32_bf16 v[102:105], v[198:201], v[222:225], v[102:105]
	v_mfma_f32_16x16x32_bf16 v[98:101], v[206:209], v[222:225], v[98:101]
	v_mfma_f32_16x16x32_bf16 v[86:89], v[198:201], v[230:233], v[86:89]
	v_mfma_f32_16x16x32_bf16 v[82:85], v[206:209], v[230:233], v[82:85]
	v_mfma_f32_16x16x32_bf16 v[70:73], v[198:201], v[238:241], v[70:73]
	v_mfma_f32_16x16x32_bf16 v[66:69], v[206:209], v[238:241], v[66:69]
	s_barrier
	s_add_i32 s3, s3, s11
	v_lshl_add_u64 v[162:163], s[0:1], 0, v[4:5]
	s_mov_b32 m0, s3
	ds_read_b128 v[210:213], v147 offset:16384
	ds_read_b128 v[214:217], v147 offset:17408
	ds_read_b128 v[218:221], v147 offset:18432
	ds_read_b128 v[222:225], v147 offset:19456
	ds_read_b128 v[226:229], v147 offset:20480
	ds_read_b128 v[230:233], v147 offset:21504
	ds_read_b128 v[234:237], v147 offset:22528
	ds_read_b128 v[238:241], v147 offset:23552
	global_load_lds_dwordx4 v4, s[0:1]
	s_add_i32 m0, s3, 0x2000
	s_add_u32 s4, s0, 0x80000
	v_lshl_add_u64 v[166:167], s[0:1], 0, v[130:131]
	s_addc_u32 s5, s1, 0
	s_add_i32 s3, s6, s11
	global_load_lds_dwordx4 v130, s[0:1]
	s_mov_b32 m0, s3
	v_lshl_add_u64 v[180:181], s[14:15], 0, v[132:133]
	global_load_lds_dwordx4 v4, s[4:5]
	s_add_i32 m0, s3, 0x2000
	s_nop 0
	global_load_lds_dwordx4 v130, s[4:5]
	v_lshl_add_u64 v[176:177], s[14:15], 0, v[134:135]
	s_mov_b32 m0, s26
	s_nop 0
	global_load_lds_dwordx4 v134, s[14:15]
	s_mov_b32 m0, s27
	s_nop 0
	global_load_lds_dwordx4 v132, s[14:15]
	s_waitcnt vmcnt(8)
	s_waitcnt lgkmcnt(0)
	s_barrier
	s_waitcnt lgkmcnt(0)
	v_mfma_f32_16x16x32_bf16 v[62:65], v[140:143], v[210:213], v[62:65]
	v_mfma_f32_16x16x32_bf16 v[58:61], v[172:175], v[210:213], v[58:61]
	v_mfma_f32_16x16x32_bf16 v[46:49], v[140:143], v[218:221], v[46:49]
	v_mfma_f32_16x16x32_bf16 v[42:45], v[172:175], v[218:221], v[42:45]
	v_mfma_f32_16x16x32_bf16 v[30:33], v[140:143], v[226:229], v[30:33]
	v_mfma_f32_16x16x32_bf16 v[26:29], v[172:175], v[226:229], v[26:29]
	v_mfma_f32_16x16x32_bf16 v[14:17], v[140:143], v[234:237], v[14:17]
	v_mfma_f32_16x16x32_bf16 v[10:13], v[172:175], v[234:237], v[10:13]
	v_mfma_f32_16x16x32_bf16 v[62:65], v[148:151], v[214:217], v[62:65]
	v_mfma_f32_16x16x32_bf16 v[58:61], v[190:193], v[214:217], v[58:61]
	v_mfma_f32_16x16x32_bf16 v[46:49], v[148:151], v[222:225], v[46:49]
	v_mfma_f32_16x16x32_bf16 v[42:45], v[190:193], v[222:225], v[42:45]
	v_mfma_f32_16x16x32_bf16 v[30:33], v[148:151], v[230:233], v[30:33]
	v_mfma_f32_16x16x32_bf16 v[26:29], v[190:193], v[230:233], v[26:29]
	v_mfma_f32_16x16x32_bf16 v[14:17], v[148:151], v[238:241], v[14:17]
	v_mfma_f32_16x16x32_bf16 v[10:13], v[190:193], v[238:241], v[10:13]
	v_mfma_f32_16x16x32_bf16 v[54:57], v[194:197], v[210:213], v[54:57]
	v_mfma_f32_16x16x32_bf16 v[50:53], v[202:205], v[210:213], v[50:53]
	v_mfma_f32_16x16x32_bf16 v[38:41], v[194:197], v[218:221], v[38:41]
	v_mfma_f32_16x16x32_bf16 v[34:37], v[202:205], v[218:221], v[34:37]
	v_mfma_f32_16x16x32_bf16 v[22:25], v[194:197], v[226:229], v[22:25]
	v_mfma_f32_16x16x32_bf16 v[18:21], v[202:205], v[226:229], v[18:21]
	v_mfma_f32_16x16x32_bf16 v[6:9], v[194:197], v[234:237], v[6:9]
	v_mfma_f32_16x16x32_bf16 v[0:3], v[202:205], v[234:237], v[0:3]
	v_mfma_f32_16x16x32_bf16 v[54:57], v[198:201], v[214:217], v[54:57]
	v_mfma_f32_16x16x32_bf16 v[50:53], v[206:209], v[214:217], v[50:53]
	v_mfma_f32_16x16x32_bf16 v[38:41], v[198:201], v[222:225], v[38:41]
	v_mfma_f32_16x16x32_bf16 v[34:37], v[206:209], v[222:225], v[34:37]
	v_mfma_f32_16x16x32_bf16 v[22:25], v[198:201], v[230:233], v[22:25]
	v_mfma_f32_16x16x32_bf16 v[18:21], v[206:209], v[230:233], v[18:21]
	v_mfma_f32_16x16x32_bf16 v[6:9], v[198:201], v[238:241], v[6:9]
	v_mfma_f32_16x16x32_bf16 v[0:3], v[206:209], v[238:241], v[0:3]
	s_barrier
.Lpeelmid_163:
	s_add_i32 s3, 0, 0x18000
	v_add_u32_e32 v164, s3, v145
	s_add_i32 s6, 0, 0x1c000
	ds_read_b128 v[140:143], v164
	ds_read_b128 v[148:151], v164 offset:1024
	ds_read_b128 v[172:175], v164 offset:2048
	ds_read_b128 v[190:193], v164 offset:3072
	v_add_u32_e32 v164, s6, v145
	ds_read_b128 v[194:197], v164
	ds_read_b128 v[198:201], v164 offset:1024
	ds_read_b128 v[202:205], v164 offset:2048
	ds_read_b128 v[206:209], v164 offset:3072
	s_add_u32 s4, s14, 0x80000
	s_addc_u32 s5, s15, 0
	s_mov_b32 m0, s30
	ds_read_b128 v[210:213], v147 offset:32768
	ds_read_b128 v[214:217], v147 offset:33792
	ds_read_b128 v[218:221], v147 offset:34816
	ds_read_b128 v[222:225], v147 offset:35840
	ds_read_b128 v[226:229], v147 offset:36864
	ds_read_b128 v[230:233], v147 offset:37888
	ds_read_b128 v[234:237], v147 offset:38912
	ds_read_b128 v[238:241], v147 offset:39936
	global_load_lds_dwordx4 v134, s[4:5]
	v_lshl_add_u64 v[242:243], s[4:5], 0, v[132:133]
	s_mov_b32 m0, s31
	s_nop 0
	global_load_lds_dwordx4 v132, s[4:5]
	s_waitcnt vmcnt(8)
	s_waitcnt lgkmcnt(0)
	s_barrier
	s_waitcnt lgkmcnt(0)
	v_mfma_f32_16x16x32_bf16 v[126:129], v[140:143], v[210:213], v[126:129]
	v_mfma_f32_16x16x32_bf16 v[122:125], v[172:175], v[210:213], v[122:125]
	v_mfma_f32_16x16x32_bf16 v[110:113], v[140:143], v[218:221], v[110:113]
	v_mfma_f32_16x16x32_bf16 v[106:109], v[172:175], v[218:221], v[106:109]
	v_mfma_f32_16x16x32_bf16 v[94:97], v[140:143], v[226:229], v[94:97]
	v_mfma_f32_16x16x32_bf16 v[90:93], v[172:175], v[226:229], v[90:93]
	v_mfma_f32_16x16x32_bf16 v[78:81], v[140:143], v[234:237], v[78:81]
	v_mfma_f32_16x16x32_bf16 v[74:77], v[172:175], v[234:237], v[74:77]
	v_mfma_f32_16x16x32_bf16 v[126:129], v[148:151], v[214:217], v[126:129]
	v_mfma_f32_16x16x32_bf16 v[122:125], v[190:193], v[214:217], v[122:125]
	v_mfma_f32_16x16x32_bf16 v[110:113], v[148:151], v[222:225], v[110:113]
	v_mfma_f32_16x16x32_bf16 v[106:109], v[190:193], v[222:225], v[106:109]
	v_mfma_f32_16x16x32_bf16 v[94:97], v[148:151], v[230:233], v[94:97]
	v_mfma_f32_16x16x32_bf16 v[90:93], v[190:193], v[230:233], v[90:93]
	v_mfma_f32_16x16x32_bf16 v[78:81], v[148:151], v[238:241], v[78:81]
	v_mfma_f32_16x16x32_bf16 v[74:77], v[190:193], v[238:241], v[74:77]
	v_mfma_f32_16x16x32_bf16 v[118:121], v[194:197], v[210:213], v[118:121]
	v_mfma_f32_16x16x32_bf16 v[114:117], v[202:205], v[210:213], v[114:117]
	v_mfma_f32_16x16x32_bf16 v[102:105], v[194:197], v[218:221], v[102:105]
	v_mfma_f32_16x16x32_bf16 v[98:101], v[202:205], v[218:221], v[98:101]
	v_mfma_f32_16x16x32_bf16 v[86:89], v[194:197], v[226:229], v[86:89]
	v_mfma_f32_16x16x32_bf16 v[82:85], v[202:205], v[226:229], v[82:85]
	v_mfma_f32_16x16x32_bf16 v[70:73], v[194:197], v[234:237], v[70:73]
	v_mfma_f32_16x16x32_bf16 v[66:69], v[202:205], v[234:237], v[66:69]
	v_mfma_f32_16x16x32_bf16 v[118:121], v[198:201], v[214:217], v[118:121]
	v_mfma_f32_16x16x32_bf16 v[114:117], v[206:209], v[214:217], v[114:117]
	v_mfma_f32_16x16x32_bf16 v[102:105], v[198:201], v[222:225], v[102:105]
	v_mfma_f32_16x16x32_bf16 v[98:101], v[206:209], v[222:225], v[98:101]
	v_mfma_f32_16x16x32_bf16 v[86:89], v[198:201], v[230:233], v[86:89]
	v_mfma_f32_16x16x32_bf16 v[82:85], v[206:209], v[230:233], v[82:85]
	v_mfma_f32_16x16x32_bf16 v[70:73], v[198:201], v[238:241], v[70:73]
	v_mfma_f32_16x16x32_bf16 v[66:69], v[206:209], v[238:241], v[66:69]
	s_barrier
	s_add_i32 s3, s3, s11
	v_lshl_add_u64 v[162:163], v[162:163], 0, s[70:71]
	s_mov_b32 m0, s3
	ds_read_b128 v[210:213], v147 offset:49152
	ds_read_b128 v[214:217], v147 offset:50176
	ds_read_b128 v[218:221], v147 offset:51200
	ds_read_b128 v[222:225], v147 offset:52224
	ds_read_b128 v[226:229], v147 offset:53248
	ds_read_b128 v[230:233], v147 offset:54272
	ds_read_b128 v[234:237], v147 offset:55296
	ds_read_b128 v[238:241], v147 offset:56320
	global_load_lds_dwordx4 v[162:163], off
	s_add_i32 m0, s3, 0x2000
	s_add_u32 s0, s0, 0x80080
	v_lshl_add_u64 v[162:163], v[166:167], 0, s[70:71]
	s_addc_u32 s1, s1, 0
	s_add_i32 s3, s6, s11
	global_load_lds_dwordx4 v[162:163], off
	s_mov_b32 m0, s3
	s_nop 0
	global_load_lds_dwordx4 v4, s[0:1]
	s_add_i32 m0, s3, 0x2000
	s_nop 0
	global_load_lds_dwordx4 v130, s[0:1]
	v_lshl_add_u64 v[162:163], v[176:177], 0, s[70:71]
	s_mov_b32 m0, s35
	s_nop 0
	global_load_lds_dwordx4 v[162:163], off
	v_lshl_add_u64 v[162:163], v[180:181], 0, s[70:71]
	s_mov_b32 m0, s36
	s_nop 0
	global_load_lds_dwordx4 v[162:163], off
	s_waitcnt vmcnt(8)
	s_waitcnt lgkmcnt(0)
	s_barrier
	s_waitcnt lgkmcnt(0)
	v_mfma_f32_16x16x32_bf16 v[62:65], v[140:143], v[210:213], v[62:65]
	v_mfma_f32_16x16x32_bf16 v[58:61], v[172:175], v[210:213], v[58:61]
	v_mfma_f32_16x16x32_bf16 v[46:49], v[140:143], v[218:221], v[46:49]
	v_mfma_f32_16x16x32_bf16 v[42:45], v[172:175], v[218:221], v[42:45]
	v_mfma_f32_16x16x32_bf16 v[30:33], v[140:143], v[226:229], v[30:33]
	v_mfma_f32_16x16x32_bf16 v[26:29], v[172:175], v[226:229], v[26:29]
	v_mfma_f32_16x16x32_bf16 v[14:17], v[140:143], v[234:237], v[14:17]
	v_mfma_f32_16x16x32_bf16 v[10:13], v[172:175], v[234:237], v[10:13]
	v_mfma_f32_16x16x32_bf16 v[62:65], v[148:151], v[214:217], v[62:65]
	v_mfma_f32_16x16x32_bf16 v[58:61], v[190:193], v[214:217], v[58:61]
	v_mfma_f32_16x16x32_bf16 v[46:49], v[148:151], v[222:225], v[46:49]
	v_mfma_f32_16x16x32_bf16 v[42:45], v[190:193], v[222:225], v[42:45]
	v_mfma_f32_16x16x32_bf16 v[30:33], v[148:151], v[230:233], v[30:33]
	v_mfma_f32_16x16x32_bf16 v[26:29], v[190:193], v[230:233], v[26:29]
	v_mfma_f32_16x16x32_bf16 v[14:17], v[148:151], v[238:241], v[14:17]
	v_mfma_f32_16x16x32_bf16 v[10:13], v[190:193], v[238:241], v[10:13]
	v_mfma_f32_16x16x32_bf16 v[54:57], v[194:197], v[210:213], v[54:57]
	v_mfma_f32_16x16x32_bf16 v[50:53], v[202:205], v[210:213], v[50:53]
	v_mfma_f32_16x16x32_bf16 v[38:41], v[194:197], v[218:221], v[38:41]
	v_mfma_f32_16x16x32_bf16 v[34:37], v[202:205], v[218:221], v[34:37]
	v_mfma_f32_16x16x32_bf16 v[22:25], v[194:197], v[226:229], v[22:25]
	v_mfma_f32_16x16x32_bf16 v[18:21], v[202:205], v[226:229], v[18:21]
	v_mfma_f32_16x16x32_bf16 v[6:9], v[194:197], v[234:237], v[6:9]
	v_mfma_f32_16x16x32_bf16 v[0:3], v[202:205], v[234:237], v[0:3]
	v_mfma_f32_16x16x32_bf16 v[54:57], v[198:201], v[214:217], v[54:57]
	v_mfma_f32_16x16x32_bf16 v[50:53], v[206:209], v[214:217], v[50:53]
	v_mfma_f32_16x16x32_bf16 v[38:41], v[198:201], v[222:225], v[38:41]
	v_mfma_f32_16x16x32_bf16 v[34:37], v[206:209], v[222:225], v[34:37]
	v_mfma_f32_16x16x32_bf16 v[22:25], v[198:201], v[230:233], v[22:25]
	v_mfma_f32_16x16x32_bf16 v[18:21], v[206:209], v[230:233], v[18:21]
	v_mfma_f32_16x16x32_bf16 v[6:9], v[198:201], v[238:241], v[6:9]
	v_mfma_f32_16x16x32_bf16 v[0:3], v[206:209], v[238:241], v[0:3]
	s_barrier
	s_add_i32 s24, s24, 2
	s_add_u32 s22, s22, 0x100
	s_addc_u32 s23, s23, 0
	s_add_u32 s9, s9, 0x100
	s_addc_u32 s10, s10, 0
	s_cmp_gt_u32 s24, 29
	s_cbranch_scc0 .LBB0_163
	s_and_b64 vcc, exec, s[46:47]
	s_cbranch_vccz .LBB0_166
	s_barrier

.LBB0_204:
	s_ashr_i32 s49, s48, 31
	s_lshl_b64 s[2:3], s[48:49], 19
	v_readlane_b32 s4, v253, 17
	v_readlane_b32 s5, v253, 18
	s_add_u32 s84, s4, s2
	s_addc_u32 s85, s5, s3
	s_and_b64 s[2:3], s[42:43], exec
	s_cselect_b32 s2, s85, s15
	s_cselect_b32 s8, s84, s14
	s_add_u32 s22, s0, 0x40080
	s_addc_u32 s23, s1, 0
	s_add_u32 s9, s14, 0x100
	v_mov_b32_e32 v0, 0
	s_addc_u32 s10, s15, 0
	s_mov_b32 s24, -2
	v_mov_b32_e32 v1, v0
	v_mov_b32_e32 v2, v0
	v_mov_b32_e32 v3, v0
	v_mov_b32_e32 v6, v0
	v_mov_b32_e32 v7, v0
	v_mov_b32_e32 v8, v0
	v_mov_b32_e32 v9, v0
	v_mov_b32_e32 v10, v0
	v_mov_b32_e32 v11, v0
	v_mov_b32_e32 v12, v0
	v_mov_b32_e32 v13, v0
	v_mov_b32_e32 v14, v0
	v_mov_b32_e32 v15, v0
	v_mov_b32_e32 v16, v0
	v_mov_b32_e32 v17, v0
	v_mov_b32_e32 v18, v0
	v_mov_b32_e32 v19, v0
	v_mov_b32_e32 v20, v0
	v_mov_b32_e32 v21, v0
	v_mov_b32_e32 v22, v0
	v_mov_b32_e32 v23, v0
	v_mov_b32_e32 v24, v0
	v_mov_b32_e32 v25, v0
	v_mov_b32_e32 v26, v0
	v_mov_b32_e32 v27, v0
	v_mov_b32_e32 v28, v0
	v_mov_b32_e32 v29, v0
	v_mov_b32_e32 v30, v0
	v_mov_b32_e32 v31, v0
	v_mov_b32_e32 v32, v0
	v_mov_b32_e32 v33, v0
	v_mov_b32_e32 v66, v0
	v_mov_b32_e32 v67, v0
	v_mov_b32_e32 v68, v0
	v_mov_b32_e32 v69, v0
	v_mov_b32_e32 v70, v0
	v_mov_b32_e32 v71, v0
	v_mov_b32_e32 v72, v0
	v_mov_b32_e32 v73, v0
	v_mov_b32_e32 v74, v0
	v_mov_b32_e32 v75, v0
	v_mov_b32_e32 v76, v0
	v_mov_b32_e32 v77, v0
	v_mov_b32_e32 v78, v0
	v_mov_b32_e32 v79, v0
	v_mov_b32_e32 v80, v0
	v_mov_b32_e32 v81, v0
	v_mov_b32_e32 v82, v0
	v_mov_b32_e32 v83, v0
	v_mov_b32_e32 v84, v0
	v_mov_b32_e32 v85, v0
	v_mov_b32_e32 v86, v0
	v_mov_b32_e32 v87, v0
	v_mov_b32_e32 v88, v0
	v_mov_b32_e32 v89, v0
	v_mov_b32_e32 v90, v0
	v_mov_b32_e32 v91, v0
	v_mov_b32_e32 v92, v0
	v_mov_b32_e32 v93, v0
	v_mov_b32_e32 v94, v0
	v_mov_b32_e32 v95, v0
	v_mov_b32_e32 v96, v0
	v_mov_b32_e32 v97, v0
	v_mov_b32_e32 v34, v0
	v_mov_b32_e32 v35, v0
	v_mov_b32_e32 v36, v0
	v_mov_b32_e32 v37, v0
	v_mov_b32_e32 v38, v0
	v_mov_b32_e32 v39, v0
	v_mov_b32_e32 v40, v0
	v_mov_b32_e32 v41, v0
	v_mov_b32_e32 v42, v0
	v_mov_b32_e32 v43, v0
	v_mov_b32_e32 v44, v0
	v_mov_b32_e32 v45, v0
	v_mov_b32_e32 v46, v0
	v_mov_b32_e32 v47, v0
	v_mov_b32_e32 v48, v0
	v_mov_b32_e32 v49, v0
	v_mov_b32_e32 v50, v0
	v_mov_b32_e32 v51, v0
	v_mov_b32_e32 v52, v0
	v_mov_b32_e32 v53, v0
	v_mov_b32_e32 v54, v0
	v_mov_b32_e32 v55, v0
	v_mov_b32_e32 v56, v0
	v_mov_b32_e32 v57, v0
	v_mov_b32_e32 v58, v0
	v_mov_b32_e32 v59, v0
	v_mov_b32_e32 v60, v0
	v_mov_b32_e32 v61, v0
	v_mov_b32_e32 v62, v0
	v_mov_b32_e32 v63, v0
	v_mov_b32_e32 v64, v0
	v_mov_b32_e32 v65, v0
	v_mov_b32_e32 v98, v0
	v_mov_b32_e32 v99, v0
	v_mov_b32_e32 v100, v0
	v_mov_b32_e32 v101, v0
	v_mov_b32_e32 v102, v0
	v_mov_b32_e32 v103, v0
	v_mov_b32_e32 v104, v0
	v_mov_b32_e32 v105, v0
	v_mov_b32_e32 v106, v0
	v_mov_b32_e32 v107, v0
	v_mov_b32_e32 v108, v0
	v_mov_b32_e32 v109, v0
	v_mov_b32_e32 v110, v0
	v_mov_b32_e32 v111, v0
	v_mov_b32_e32 v112, v0
	v_mov_b32_e32 v113, v0
	v_mov_b32_e32 v114, v0
	v_mov_b32_e32 v115, v0
	v_mov_b32_e32 v116, v0
	v_mov_b32_e32 v117, v0
	v_mov_b32_e32 v118, v0
	v_mov_b32_e32 v119, v0
	v_mov_b32_e32 v120, v0
	v_mov_b32_e32 v121, v0
	v_mov_b32_e32 v122, v0
	v_mov_b32_e32 v123, v0
	v_mov_b32_e32 v124, v0
	v_mov_b32_e32 v125, v0
	v_mov_b32_e32 v126, v0
	v_mov_b32_e32 v127, v0
	v_mov_b32_e32 v128, v0
	v_mov_b32_e32 v129, v0
	s_cmp_eq_u32 s37, 1
	s_cbranch_scc1 .LBB0_205
	s_add_u32 s0, s22, 0xfffc0080
	s_addc_u32 s1, s23, -1
	s_add_i32 s3, 0, 0x10000
	s_cmp_eq_u32 s24, 12
	s_cselect_b32 s15, s83, s1
	s_cselect_b32 s14, s82, s0
	v_add_u32_e32 v144, s3, v168
	s_cselect_b32 s1, s2, s10
	s_cselect_b32 s0, s8, s9
	s_add_i32 s6, 0, 0x14000
	ds_read_b128 v[140:143], v144
	ds_read_b128 v[174:177], v144 offset:1024
	ds_read_b128 v[190:193], v144 offset:2048
	ds_read_b128 v[194:197], v144 offset:3072
	v_add_u32_e32 v144, s6, v168
	ds_read_b128 v[198:201], v144
	ds_read_b128 v[202:205], v144 offset:1024
	ds_read_b128 v[206:209], v144 offset:2048
	ds_read_b128 v[210:213], v144 offset:3072
	s_add_i32 m0, s27, 0xc000
	ds_read_b128 v[214:217], v172
	ds_read_b128 v[218:221], v172 offset:1024
	ds_read_b128 v[222:225], v172 offset:2048
	ds_read_b128 v[226:229], v172 offset:3072
	ds_read_b128 v[230:233], v172 offset:4096
	ds_read_b128 v[234:237], v172 offset:5120
	ds_read_b128 v[238:241], v172 offset:6144
	ds_read_b128 v[242:245], v172 offset:7168
	global_load_lds_dwordx4 v136, s[22:23]
	s_add_i32 m0, s27, 0xe000
	s_nop 0
	global_load_lds_dwordx4 v138, s[22:23]
	s_waitcnt vmcnt(24)
	s_waitcnt lgkmcnt(0)
	s_barrier
	s_waitcnt lgkmcnt(0)
	v_mfma_f32_16x16x32_bf16 v[126:129], v[140:143], v[214:217], v[126:129]
	v_mfma_f32_16x16x32_bf16 v[122:125], v[190:193], v[214:217], v[122:125]
	v_mfma_f32_16x16x32_bf16 v[118:121], v[140:143], v[222:225], v[118:121]
	v_mfma_f32_16x16x32_bf16 v[114:117], v[190:193], v[222:225], v[114:117]
	v_mfma_f32_16x16x32_bf16 v[110:113], v[140:143], v[230:233], v[110:113]
	v_mfma_f32_16x16x32_bf16 v[106:109], v[190:193], v[230:233], v[106:109]
	v_mfma_f32_16x16x32_bf16 v[102:105], v[140:143], v[238:241], v[102:105]
	v_mfma_f32_16x16x32_bf16 v[98:101], v[190:193], v[238:241], v[98:101]
	v_mfma_f32_16x16x32_bf16 v[126:129], v[174:177], v[218:221], v[126:129]
	v_mfma_f32_16x16x32_bf16 v[122:125], v[194:197], v[218:221], v[122:125]
	v_mfma_f32_16x16x32_bf16 v[118:121], v[174:177], v[226:229], v[118:121]
	v_mfma_f32_16x16x32_bf16 v[114:117], v[194:197], v[226:229], v[114:117]
	v_mfma_f32_16x16x32_bf16 v[110:113], v[174:177], v[234:237], v[110:113]
	v_mfma_f32_16x16x32_bf16 v[106:109], v[194:197], v[234:237], v[106:109]
	v_mfma_f32_16x16x32_bf16 v[102:105], v[174:177], v[242:245], v[102:105]
	v_mfma_f32_16x16x32_bf16 v[98:101], v[194:197], v[242:245], v[98:101]
	v_mfma_f32_16x16x32_bf16 v[62:65], v[198:201], v[214:217], v[62:65]
	v_mfma_f32_16x16x32_bf16 v[58:61], v[206:209], v[214:217], v[58:61]
	v_mfma_f32_16x16x32_bf16 v[54:57], v[198:201], v[222:225], v[54:57]
	v_mfma_f32_16x16x32_bf16 v[50:53], v[206:209], v[222:225], v[50:53]
	v_mfma_f32_16x16x32_bf16 v[46:49], v[198:201], v[230:233], v[46:49]
	v_mfma_f32_16x16x32_bf16 v[42:45], v[206:209], v[230:233], v[42:45]
	v_mfma_f32_16x16x32_bf16 v[38:41], v[198:201], v[238:241], v[38:41]
	v_mfma_f32_16x16x32_bf16 v[34:37], v[206:209], v[238:241], v[34:37]
	v_mfma_f32_16x16x32_bf16 v[62:65], v[202:205], v[218:221], v[62:65]
	v_mfma_f32_16x16x32_bf16 v[58:61], v[210:213], v[218:221], v[58:61]
	v_mfma_f32_16x16x32_bf16 v[54:57], v[202:205], v[226:229], v[54:57]
	v_mfma_f32_16x16x32_bf16 v[50:53], v[210:213], v[226:229], v[50:53]
	v_mfma_f32_16x16x32_bf16 v[46:49], v[202:205], v[234:237], v[46:49]
	v_mfma_f32_16x16x32_bf16 v[42:45], v[210:213], v[234:237], v[42:45]
	v_mfma_f32_16x16x32_bf16 v[38:41], v[202:205], v[242:245], v[38:41]
	v_mfma_f32_16x16x32_bf16 v[34:37], v[210:213], v[242:245], v[34:37]
	s_barrier
	s_add_i32 s3, s3, s26
	v_lshl_add_u64 v[144:145], s[0:1], 0, v[4:5]
	s_mov_b32 m0, s3
	ds_read_b128 v[214:217], v172 offset:16384
	ds_read_b128 v[218:221], v172 offset:17408
	ds_read_b128 v[222:225], v172 offset:18432
	ds_read_b128 v[226:229], v172 offset:19456
	ds_read_b128 v[230:233], v172 offset:20480
	ds_read_b128 v[234:237], v172 offset:21504
	ds_read_b128 v[238:241], v172 offset:22528
	ds_read_b128 v[242:245], v172 offset:23552
	global_load_lds_dwordx4 v4, s[0:1]
	s_add_i32 m0, s3, 0x2000
	s_add_u32 s4, s0, 0x40000
	v_lshl_add_u64 v[246:247], s[0:1], 0, v[134:135]
	s_addc_u32 s5, s1, 0
	s_add_i32 s3, s6, s26
	global_load_lds_dwordx4 v134, s[0:1]
	s_mov_b32 m0, s3
	v_lshl_add_u64 v[250:251], s[14:15], 0, v[132:133]
	global_load_lds_dwordx4 v4, s[4:5]
	s_add_i32 m0, s3, 0x2000
	s_nop 0
	global_load_lds_dwordx4 v134, s[4:5]
	v_lshl_add_u64 v[248:249], s[14:15], 0, v[130:131]
	s_mov_b32 m0, s27
	s_nop 0
	global_load_lds_dwordx4 v130, s[14:15]
	s_mov_b32 m0, s30
	s_nop 0
	global_load_lds_dwordx4 v132, s[14:15]
	s_waitcnt vmcnt(24)
	s_waitcnt lgkmcnt(0)
	s_barrier
	s_waitcnt lgkmcnt(0)
	v_mfma_f32_16x16x32_bf16 v[94:97], v[140:143], v[214:217], v[94:97]
	v_mfma_f32_16x16x32_bf16 v[90:93], v[190:193], v[214:217], v[90:93]
	v_mfma_f32_16x16x32_bf16 v[86:89], v[140:143], v[222:225], v[86:89]
	v_mfma_f32_16x16x32_bf16 v[82:85], v[190:193], v[222:225], v[82:85]
	v_mfma_f32_16x16x32_bf16 v[78:81], v[140:143], v[230:233], v[78:81]
	v_mfma_f32_16x16x32_bf16 v[74:77], v[190:193], v[230:233], v[74:77]
	v_mfma_f32_16x16x32_bf16 v[70:73], v[140:143], v[238:241], v[70:73]
	v_mfma_f32_16x16x32_bf16 v[66:69], v[190:193], v[238:241], v[66:69]
	v_mfma_f32_16x16x32_bf16 v[94:97], v[174:177], v[218:221], v[94:97]
	v_mfma_f32_16x16x32_bf16 v[90:93], v[194:197], v[218:221], v[90:93]
	v_mfma_f32_16x16x32_bf16 v[86:89], v[174:177], v[226:229], v[86:89]
	v_mfma_f32_16x16x32_bf16 v[82:85], v[194:197], v[226:229], v[82:85]
	v_mfma_f32_16x16x32_bf16 v[78:81], v[174:177], v[234:237], v[78:81]
	v_mfma_f32_16x16x32_bf16 v[74:77], v[194:197], v[234:237], v[74:77]
	v_mfma_f32_16x16x32_bf16 v[70:73], v[174:177], v[242:245], v[70:73]
	v_mfma_f32_16x16x32_bf16 v[66:69], v[194:197], v[242:245], v[66:69]
	v_mfma_f32_16x16x32_bf16 v[30:33], v[198:201], v[214:217], v[30:33]
	v_mfma_f32_16x16x32_bf16 v[26:29], v[206:209], v[214:217], v[26:29]
	v_mfma_f32_16x16x32_bf16 v[22:25], v[198:201], v[222:225], v[22:25]
	v_mfma_f32_16x16x32_bf16 v[18:21], v[206:209], v[222:225], v[18:21]
	v_mfma_f32_16x16x32_bf16 v[14:17], v[198:201], v[230:233], v[14:17]
	v_mfma_f32_16x16x32_bf16 v[10:13], v[206:209], v[230:233], v[10:13]
	v_mfma_f32_16x16x32_bf16 v[6:9], v[198:201], v[238:241], v[6:9]
	v_mfma_f32_16x16x32_bf16 v[0:3], v[206:209], v[238:241], v[0:3]
	v_mfma_f32_16x16x32_bf16 v[30:33], v[202:205], v[218:221], v[30:33]
	v_mfma_f32_16x16x32_bf16 v[26:29], v[210:213], v[218:221], v[26:29]
	v_mfma_f32_16x16x32_bf16 v[22:25], v[202:205], v[226:229], v[22:25]
	v_mfma_f32_16x16x32_bf16 v[18:21], v[210:213], v[226:229], v[18:21]
	v_mfma_f32_16x16x32_bf16 v[14:17], v[202:205], v[234:237], v[14:17]
	v_mfma_f32_16x16x32_bf16 v[10:13], v[210:213], v[234:237], v[10:13]
	v_mfma_f32_16x16x32_bf16 v[6:9], v[202:205], v[242:245], v[6:9]
	v_mfma_f32_16x16x32_bf16 v[0:3], v[210:213], v[242:245], v[0:3]
	s_barrier
	s_branch .Lpeelmid_205
.LBB0_205:
	s_add_u32 s0, s22, 0xfffc0080
	s_addc_u32 s1, s23, -1
	s_add_i32 s3, 0, 0x10000
	s_cmp_eq_u32 s24, 12
	s_cselect_b32 s15, s83, s1
	s_cselect_b32 s14, s82, s0
	v_add_u32_e32 v144, s3, v168
	s_cselect_b32 s1, s2, s10
	s_cselect_b32 s0, s8, s9
	s_add_i32 s6, 0, 0x14000
	ds_read_b128 v[140:143], v144
	ds_read_b128 v[174:177], v144 offset:1024
	ds_read_b128 v[190:193], v144 offset:2048
	ds_read_b128 v[194:197], v144 offset:3072
	v_add_u32_e32 v144, s6, v168
	ds_read_b128 v[198:201], v144
	ds_read_b128 v[202:205], v144 offset:1024
	ds_read_b128 v[206:209], v144 offset:2048
	ds_read_b128 v[210:213], v144 offset:3072
	s_add_i32 m0, s27, 0xc000
	ds_read_b128 v[214:217], v172
	ds_read_b128 v[218:221], v172 offset:1024
	ds_read_b128 v[222:225], v172 offset:2048
	ds_read_b128 v[226:229], v172 offset:3072
	ds_read_b128 v[230:233], v172 offset:4096
	ds_read_b128 v[234:237], v172 offset:5120
	ds_read_b128 v[238:241], v172 offset:6144
	ds_read_b128 v[242:245], v172 offset:7168
	global_load_lds_dwordx4 v136, s[22:23]
	s_add_i32 m0, s27, 0xe000
	s_nop 0
	global_load_lds_dwordx4 v138, s[22:23]
	s_waitcnt vmcnt(8)
	s_waitcnt lgkmcnt(0)
	s_barrier
	s_waitcnt lgkmcnt(0)
	v_mfma_f32_16x16x32_bf16 v[126:129], v[140:143], v[214:217], v[126:129]
	v_mfma_f32_16x16x32_bf16 v[122:125], v[190:193], v[214:217], v[122:125]
	v_mfma_f32_16x16x32_bf16 v[118:121], v[140:143], v[222:225], v[118:121]
	v_mfma_f32_16x16x32_bf16 v[114:117], v[190:193], v[222:225], v[114:117]
	v_mfma_f32_16x16x32_bf16 v[110:113], v[140:143], v[230:233], v[110:113]
	v_mfma_f32_16x16x32_bf16 v[106:109], v[190:193], v[230:233], v[106:109]
	v_mfma_f32_16x16x32_bf16 v[102:105], v[140:143], v[238:241], v[102:105]
	v_mfma_f32_16x16x32_bf16 v[98:101], v[190:193], v[238:241], v[98:101]
	v_mfma_f32_16x16x32_bf16 v[126:129], v[174:177], v[218:221], v[126:129]
	v_mfma_f32_16x16x32_bf16 v[122:125], v[194:197], v[218:221], v[122:125]
	v_mfma_f32_16x16x32_bf16 v[118:121], v[174:177], v[226:229], v[118:121]
	v_mfma_f32_16x16x32_bf16 v[114:117], v[194:197], v[226:229], v[114:117]
	v_mfma_f32_16x16x32_bf16 v[110:113], v[174:177], v[234:237], v[110:113]
	v_mfma_f32_16x16x32_bf16 v[106:109], v[194:197], v[234:237], v[106:109]
	v_mfma_f32_16x16x32_bf16 v[102:105], v[174:177], v[242:245], v[102:105]
	v_mfma_f32_16x16x32_bf16 v[98:101], v[194:197], v[242:245], v[98:101]
	v_mfma_f32_16x16x32_bf16 v[62:65], v[198:201], v[214:217], v[62:65]
	v_mfma_f32_16x16x32_bf16 v[58:61], v[206:209], v[214:217], v[58:61]
	v_mfma_f32_16x16x32_bf16 v[54:57], v[198:201], v[222:225], v[54:57]
	v_mfma_f32_16x16x32_bf16 v[50:53], v[206:209], v[222:225], v[50:53]
	v_mfma_f32_16x16x32_bf16 v[46:49], v[198:201], v[230:233], v[46:49]
	v_mfma_f32_16x16x32_bf16 v[42:45], v[206:209], v[230:233], v[42:45]
	v_mfma_f32_16x16x32_bf16 v[38:41], v[198:201], v[238:241], v[38:41]
	v_mfma_f32_16x16x32_bf16 v[34:37], v[206:209], v[238:241], v[34:37]
	v_mfma_f32_16x16x32_bf16 v[62:65], v[202:205], v[218:221], v[62:65]
	v_mfma_f32_16x16x32_bf16 v[58:61], v[210:213], v[218:221], v[58:61]
	v_mfma_f32_16x16x32_bf16 v[54:57], v[202:205], v[226:229], v[54:57]
	v_mfma_f32_16x16x32_bf16 v[50:53], v[210:213], v[226:229], v[50:53]
	v_mfma_f32_16x16x32_bf16 v[46:49], v[202:205], v[234:237], v[46:49]
	v_mfma_f32_16x16x32_bf16 v[42:45], v[210:213], v[234:237], v[42:45]
	v_mfma_f32_16x16x32_bf16 v[38:41], v[202:205], v[242:245], v[38:41]
	v_mfma_f32_16x16x32_bf16 v[34:37], v[210:213], v[242:245], v[34:37]
	s_barrier
	s_add_i32 s3, s3, s26
	v_lshl_add_u64 v[144:145], s[0:1], 0, v[4:5]
	s_mov_b32 m0, s3
	ds_read_b128 v[214:217], v172 offset:16384
	ds_read_b128 v[218:221], v172 offset:17408
	ds_read_b128 v[222:225], v172 offset:18432
	ds_read_b128 v[226:229], v172 offset:19456
	ds_read_b128 v[230:233], v172 offset:20480
	ds_read_b128 v[234:237], v172 offset:21504
	ds_read_b128 v[238:241], v172 offset:22528
	ds_read_b128 v[242:245], v172 offset:23552
	global_load_lds_dwordx4 v4, s[0:1]
	s_add_i32 m0, s3, 0x2000
	s_add_u32 s4, s0, 0x40000
	v_lshl_add_u64 v[246:247], s[0:1], 0, v[134:135]
	s_addc_u32 s5, s1, 0
	s_add_i32 s3, s6, s26
	global_load_lds_dwordx4 v134, s[0:1]
	s_mov_b32 m0, s3
	v_lshl_add_u64 v[250:251], s[14:15], 0, v[132:133]
	global_load_lds_dwordx4 v4, s[4:5]
	s_add_i32 m0, s3, 0x2000
	s_nop 0
	global_load_lds_dwordx4 v134, s[4:5]
	v_lshl_add_u64 v[248:249], s[14:15], 0, v[130:131]
	s_mov_b32 m0, s27
	s_nop 0
	global_load_lds_dwordx4 v130, s[14:15]
	s_mov_b32 m0, s30
	s_nop 0
	global_load_lds_dwordx4 v132, s[14:15]
	s_waitcnt vmcnt(8)
	s_waitcnt lgkmcnt(0)
	s_barrier
	s_waitcnt lgkmcnt(0)
	v_mfma_f32_16x16x32_bf16 v[94:97], v[140:143], v[214:217], v[94:97]
	v_mfma_f32_16x16x32_bf16 v[90:93], v[190:193], v[214:217], v[90:93]
	v_mfma_f32_16x16x32_bf16 v[86:89], v[140:143], v[222:225], v[86:89]
	v_mfma_f32_16x16x32_bf16 v[82:85], v[190:193], v[222:225], v[82:85]
	v_mfma_f32_16x16x32_bf16 v[78:81], v[140:143], v[230:233], v[78:81]
	v_mfma_f32_16x16x32_bf16 v[74:77], v[190:193], v[230:233], v[74:77]
	v_mfma_f32_16x16x32_bf16 v[70:73], v[140:143], v[238:241], v[70:73]
	v_mfma_f32_16x16x32_bf16 v[66:69], v[190:193], v[238:241], v[66:69]
	v_mfma_f32_16x16x32_bf16 v[94:97], v[174:177], v[218:221], v[94:97]
	v_mfma_f32_16x16x32_bf16 v[90:93], v[194:197], v[218:221], v[90:93]
	v_mfma_f32_16x16x32_bf16 v[86:89], v[174:177], v[226:229], v[86:89]
	v_mfma_f32_16x16x32_bf16 v[82:85], v[194:197], v[226:229], v[82:85]
	v_mfma_f32_16x16x32_bf16 v[78:81], v[174:177], v[234:237], v[78:81]
	v_mfma_f32_16x16x32_bf16 v[74:77], v[194:197], v[234:237], v[74:77]
	v_mfma_f32_16x16x32_bf16 v[70:73], v[174:177], v[242:245], v[70:73]
	v_mfma_f32_16x16x32_bf16 v[66:69], v[194:197], v[242:245], v[66:69]
	v_mfma_f32_16x16x32_bf16 v[30:33], v[198:201], v[214:217], v[30:33]
	v_mfma_f32_16x16x32_bf16 v[26:29], v[206:209], v[214:217], v[26:29]
	v_mfma_f32_16x16x32_bf16 v[22:25], v[198:201], v[222:225], v[22:25]
	v_mfma_f32_16x16x32_bf16 v[18:21], v[206:209], v[222:225], v[18:21]
	v_mfma_f32_16x16x32_bf16 v[14:17], v[198:201], v[230:233], v[14:17]
	v_mfma_f32_16x16x32_bf16 v[10:13], v[206:209], v[230:233], v[10:13]
	v_mfma_f32_16x16x32_bf16 v[6:9], v[198:201], v[238:241], v[6:9]
	v_mfma_f32_16x16x32_bf16 v[0:3], v[206:209], v[238:241], v[0:3]
	v_mfma_f32_16x16x32_bf16 v[30:33], v[202:205], v[218:221], v[30:33]
	v_mfma_f32_16x16x32_bf16 v[26:29], v[210:213], v[218:221], v[26:29]
	v_mfma_f32_16x16x32_bf16 v[22:25], v[202:205], v[226:229], v[22:25]
	v_mfma_f32_16x16x32_bf16 v[18:21], v[210:213], v[226:229], v[18:21]
	v_mfma_f32_16x16x32_bf16 v[14:17], v[202:205], v[234:237], v[14:17]
	v_mfma_f32_16x16x32_bf16 v[10:13], v[210:213], v[234:237], v[10:13]
	v_mfma_f32_16x16x32_bf16 v[6:9], v[202:205], v[242:245], v[6:9]
	v_mfma_f32_16x16x32_bf16 v[0:3], v[210:213], v[242:245], v[0:3]
	s_barrier
.Lpeelmid_205:
	s_add_i32 s3, 0, 0x18000
	v_add_u32_e32 v173, s3, v168
	s_add_i32 s6, 0, 0x1c000
	ds_read_b128 v[140:143], v173
	ds_read_b128 v[174:177], v173 offset:1024
	ds_read_b128 v[190:193], v173 offset:2048
	ds_read_b128 v[194:197], v173 offset:3072
	v_add_u32_e32 v173, s6, v168
	ds_read_b128 v[198:201], v173
	ds_read_b128 v[202:205], v173 offset:1024
	ds_read_b128 v[206:209], v173 offset:2048
	ds_read_b128 v[210:213], v173 offset:3072
	s_add_u32 s4, s14, 0x40000
	s_addc_u32 s5, s15, 0
	s_mov_b32 m0, s31
	ds_read_b128 v[214:217], v172 offset:32768
	ds_read_b128 v[218:221], v172 offset:33792
	ds_read_b128 v[222:225], v172 offset:34816
	ds_read_b128 v[226:229], v172 offset:35840
	ds_read_b128 v[230:233], v172 offset:36864
	ds_read_b128 v[234:237], v172 offset:37888
	ds_read_b128 v[238:241], v172 offset:38912
	ds_read_b128 v[242:245], v172 offset:39936
	global_load_lds_dwordx4 v130, s[4:5]
	v_lshl_add_u64 v[180:181], s[4:5], 0, v[132:133]
	s_mov_b32 m0, s34
	s_nop 0
	global_load_lds_dwordx4 v132, s[4:5]
	s_waitcnt vmcnt(8)
	s_waitcnt lgkmcnt(0)
	s_barrier
	s_waitcnt lgkmcnt(0)
	v_mfma_f32_16x16x32_bf16 v[126:129], v[140:143], v[214:217], v[126:129]
	v_mfma_f32_16x16x32_bf16 v[122:125], v[190:193], v[214:217], v[122:125]
	v_mfma_f32_16x16x32_bf16 v[118:121], v[140:143], v[222:225], v[118:121]
	v_mfma_f32_16x16x32_bf16 v[114:117], v[190:193], v[222:225], v[114:117]
	v_mfma_f32_16x16x32_bf16 v[110:113], v[140:143], v[230:233], v[110:113]
	v_mfma_f32_16x16x32_bf16 v[106:109], v[190:193], v[230:233], v[106:109]
	v_mfma_f32_16x16x32_bf16 v[102:105], v[140:143], v[238:241], v[102:105]
	v_mfma_f32_16x16x32_bf16 v[98:101], v[190:193], v[238:241], v[98:101]
	v_mfma_f32_16x16x32_bf16 v[126:129], v[174:177], v[218:221], v[126:129]
	v_mfma_f32_16x16x32_bf16 v[122:125], v[194:197], v[218:221], v[122:125]
	v_mfma_f32_16x16x32_bf16 v[118:121], v[174:177], v[226:229], v[118:121]
	v_mfma_f32_16x16x32_bf16 v[114:117], v[194:197], v[226:229], v[114:117]
	v_mfma_f32_16x16x32_bf16 v[110:113], v[174:177], v[234:237], v[110:113]
	v_mfma_f32_16x16x32_bf16 v[106:109], v[194:197], v[234:237], v[106:109]
	v_mfma_f32_16x16x32_bf16 v[102:105], v[174:177], v[242:245], v[102:105]
	v_mfma_f32_16x16x32_bf16 v[98:101], v[194:197], v[242:245], v[98:101]
	v_mfma_f32_16x16x32_bf16 v[62:65], v[198:201], v[214:217], v[62:65]
	v_mfma_f32_16x16x32_bf16 v[58:61], v[206:209], v[214:217], v[58:61]
	v_mfma_f32_16x16x32_bf16 v[54:57], v[198:201], v[222:225], v[54:57]
	v_mfma_f32_16x16x32_bf16 v[50:53], v[206:209], v[222:225], v[50:53]
	v_mfma_f32_16x16x32_bf16 v[46:49], v[198:201], v[230:233], v[46:49]
	v_mfma_f32_16x16x32_bf16 v[42:45], v[206:209], v[230:233], v[42:45]
	v_mfma_f32_16x16x32_bf16 v[38:41], v[198:201], v[238:241], v[38:41]
	v_mfma_f32_16x16x32_bf16 v[34:37], v[206:209], v[238:241], v[34:37]
	v_mfma_f32_16x16x32_bf16 v[62:65], v[202:205], v[218:221], v[62:65]
	v_mfma_f32_16x16x32_bf16 v[58:61], v[210:213], v[218:221], v[58:61]
	v_mfma_f32_16x16x32_bf16 v[54:57], v[202:205], v[226:229], v[54:57]
	v_mfma_f32_16x16x32_bf16 v[50:53], v[210:213], v[226:229], v[50:53]
	v_mfma_f32_16x16x32_bf16 v[46:49], v[202:205], v[234:237], v[46:49]
	v_mfma_f32_16x16x32_bf16 v[42:45], v[210:213], v[234:237], v[42:45]
	v_mfma_f32_16x16x32_bf16 v[38:41], v[202:205], v[242:245], v[38:41]
	v_mfma_f32_16x16x32_bf16 v[34:37], v[210:213], v[242:245], v[34:37]
	s_barrier
	s_add_i32 s3, s3, s26
	v_lshl_add_u64 v[144:145], v[144:145], 0, s[70:71]
	s_mov_b32 m0, s3
	ds_read_b128 v[214:217], v172 offset:49152
	ds_read_b128 v[218:221], v172 offset:50176
	ds_read_b128 v[222:225], v172 offset:51200
	ds_read_b128 v[226:229], v172 offset:52224
	ds_read_b128 v[230:233], v172 offset:53248
	ds_read_b128 v[234:237], v172 offset:54272
	ds_read_b128 v[238:241], v172 offset:55296
	ds_read_b128 v[242:245], v172 offset:56320
	global_load_lds_dwordx4 v[144:145], off
	s_add_i32 m0, s3, 0x2000
	s_add_u32 s0, s0, 0x40080
	v_lshl_add_u64 v[144:145], v[246:247], 0, s[70:71]
	s_addc_u32 s1, s1, 0
	s_add_i32 s3, s6, s26
	global_load_lds_dwordx4 v[144:145], off
	s_mov_b32 m0, s3
	s_nop 0
	global_load_lds_dwordx4 v4, s[0:1]
	s_add_i32 m0, s3, 0x2000
	s_nop 0
	global_load_lds_dwordx4 v134, s[0:1]
	v_lshl_add_u64 v[144:145], v[248:249], 0, s[70:71]
	s_mov_b32 m0, s35
	s_nop 0
	global_load_lds_dwordx4 v[144:145], off
	v_lshl_add_u64 v[144:145], v[250:251], 0, s[70:71]
	s_mov_b32 m0, s36
	s_nop 0
	global_load_lds_dwordx4 v[144:145], off
	s_waitcnt vmcnt(8)
	s_waitcnt lgkmcnt(0)
	s_barrier
	s_waitcnt lgkmcnt(0)
	v_mfma_f32_16x16x32_bf16 v[94:97], v[140:143], v[214:217], v[94:97]
	v_mfma_f32_16x16x32_bf16 v[90:93], v[190:193], v[214:217], v[90:93]
	v_mfma_f32_16x16x32_bf16 v[86:89], v[140:143], v[222:225], v[86:89]
	v_mfma_f32_16x16x32_bf16 v[82:85], v[190:193], v[222:225], v[82:85]
	v_mfma_f32_16x16x32_bf16 v[78:81], v[140:143], v[230:233], v[78:81]
	v_mfma_f32_16x16x32_bf16 v[74:77], v[190:193], v[230:233], v[74:77]
	v_mfma_f32_16x16x32_bf16 v[70:73], v[140:143], v[238:241], v[70:73]
	v_mfma_f32_16x16x32_bf16 v[66:69], v[190:193], v[238:241], v[66:69]
	v_mfma_f32_16x16x32_bf16 v[94:97], v[174:177], v[218:221], v[94:97]
	v_mfma_f32_16x16x32_bf16 v[90:93], v[194:197], v[218:221], v[90:93]
	v_mfma_f32_16x16x32_bf16 v[86:89], v[174:177], v[226:229], v[86:89]
	v_mfma_f32_16x16x32_bf16 v[82:85], v[194:197], v[226:229], v[82:85]
	v_mfma_f32_16x16x32_bf16 v[78:81], v[174:177], v[234:237], v[78:81]
	v_mfma_f32_16x16x32_bf16 v[74:77], v[194:197], v[234:237], v[74:77]
	v_mfma_f32_16x16x32_bf16 v[70:73], v[174:177], v[242:245], v[70:73]
	v_mfma_f32_16x16x32_bf16 v[66:69], v[194:197], v[242:245], v[66:69]
	v_mfma_f32_16x16x32_bf16 v[30:33], v[198:201], v[214:217], v[30:33]
	v_mfma_f32_16x16x32_bf16 v[26:29], v[206:209], v[214:217], v[26:29]
	v_mfma_f32_16x16x32_bf16 v[22:25], v[198:201], v[222:225], v[22:25]
	v_mfma_f32_16x16x32_bf16 v[18:21], v[206:209], v[222:225], v[18:21]
	v_mfma_f32_16x16x32_bf16 v[14:17], v[198:201], v[230:233], v[14:17]
	v_mfma_f32_16x16x32_bf16 v[10:13], v[206:209], v[230:233], v[10:13]
	v_mfma_f32_16x16x32_bf16 v[6:9], v[198:201], v[238:241], v[6:9]
	v_mfma_f32_16x16x32_bf16 v[0:3], v[206:209], v[238:241], v[0:3]
	v_mfma_f32_16x16x32_bf16 v[30:33], v[202:205], v[218:221], v[30:33]
	v_mfma_f32_16x16x32_bf16 v[26:29], v[210:213], v[218:221], v[26:29]
	v_mfma_f32_16x16x32_bf16 v[22:25], v[202:205], v[226:229], v[22:25]
	v_mfma_f32_16x16x32_bf16 v[18:21], v[210:213], v[226:229], v[18:21]
	v_mfma_f32_16x16x32_bf16 v[14:17], v[202:205], v[234:237], v[14:17]
	v_mfma_f32_16x16x32_bf16 v[10:13], v[210:213], v[234:237], v[10:13]
	v_mfma_f32_16x16x32_bf16 v[6:9], v[202:205], v[242:245], v[6:9]
	v_mfma_f32_16x16x32_bf16 v[0:3], v[210:213], v[242:245], v[0:3]
	s_barrier
	s_add_i32 s24, s24, 2
	s_add_u32 s22, s22, 0x100
	s_addc_u32 s23, s23, 0
	s_add_u32 s9, s9, 0x100
	s_addc_u32 s10, s10, 0
	s_cmp_gt_u32 s24, 13
	s_cbranch_scc0 .LBB0_205
	s_and_b64 vcc, exec, s[46:47]
	s_cbranch_vccz .LBB0_208
	s_barrier

.LBB0_227:
	s_ashr_i32 s47, s46, 31
	s_lshl_b64 s[2:3], s[46:47], 19
	v_readlane_b32 s4, v253, 25
	v_readlane_b32 s5, v253, 26
	s_add_u32 s82, s4, s2
	s_addc_u32 s83, s5, s3
	s_and_b64 s[2:3], s[40:41], exec
	s_cselect_b32 s2, s83, s15
	s_cselect_b32 s8, s82, s14
	s_add_u32 s22, s0, 0x40080
	s_addc_u32 s23, s1, 0
	s_add_u32 s9, s14, 0x100
	v_mov_b32_e32 v0, 0
	s_addc_u32 s10, s15, 0
	s_mov_b32 s24, -2
	v_mov_b32_e32 v1, v0
	v_mov_b32_e32 v2, v0
	v_mov_b32_e32 v3, v0
	v_mov_b32_e32 v6, v0
	v_mov_b32_e32 v7, v0
	v_mov_b32_e32 v8, v0
	v_mov_b32_e32 v9, v0
	v_mov_b32_e32 v10, v0
	v_mov_b32_e32 v11, v0
	v_mov_b32_e32 v12, v0
	v_mov_b32_e32 v13, v0
	v_mov_b32_e32 v14, v0
	v_mov_b32_e32 v15, v0
	v_mov_b32_e32 v16, v0
	v_mov_b32_e32 v17, v0
	v_mov_b32_e32 v18, v0
	v_mov_b32_e32 v19, v0
	v_mov_b32_e32 v20, v0
	v_mov_b32_e32 v21, v0
	v_mov_b32_e32 v22, v0
	v_mov_b32_e32 v23, v0
	v_mov_b32_e32 v24, v0
	v_mov_b32_e32 v25, v0
	v_mov_b32_e32 v26, v0
	v_mov_b32_e32 v27, v0
	v_mov_b32_e32 v28, v0
	v_mov_b32_e32 v29, v0
	v_mov_b32_e32 v30, v0
	v_mov_b32_e32 v31, v0
	v_mov_b32_e32 v32, v0
	v_mov_b32_e32 v33, v0
	v_mov_b32_e32 v62, v0
	v_mov_b32_e32 v63, v0
	v_mov_b32_e32 v64, v0
	v_mov_b32_e32 v65, v0
	v_mov_b32_e32 v70, v0
	v_mov_b32_e32 v71, v0
	v_mov_b32_e32 v72, v0
	v_mov_b32_e32 v73, v0
	v_mov_b32_e32 v74, v0
	v_mov_b32_e32 v75, v0
	v_mov_b32_e32 v76, v0
	v_mov_b32_e32 v77, v0
	v_mov_b32_e32 v78, v0
	v_mov_b32_e32 v79, v0
	v_mov_b32_e32 v80, v0
	v_mov_b32_e32 v81, v0
	v_mov_b32_e32 v82, v0
	v_mov_b32_e32 v83, v0
	v_mov_b32_e32 v84, v0
	v_mov_b32_e32 v85, v0
	v_mov_b32_e32 v86, v0
	v_mov_b32_e32 v87, v0
	v_mov_b32_e32 v88, v0
	v_mov_b32_e32 v89, v0
	v_mov_b32_e32 v90, v0
	v_mov_b32_e32 v91, v0
	v_mov_b32_e32 v92, v0
	v_mov_b32_e32 v93, v0
	v_mov_b32_e32 v94, v0
	v_mov_b32_e32 v95, v0
	v_mov_b32_e32 v96, v0
	v_mov_b32_e32 v97, v0
	v_mov_b32_e32 v34, v0
	v_mov_b32_e32 v35, v0
	v_mov_b32_e32 v36, v0
	v_mov_b32_e32 v37, v0
	v_mov_b32_e32 v38, v0
	v_mov_b32_e32 v39, v0
	v_mov_b32_e32 v40, v0
	v_mov_b32_e32 v41, v0
	v_mov_b32_e32 v42, v0
	v_mov_b32_e32 v43, v0
	v_mov_b32_e32 v44, v0
	v_mov_b32_e32 v45, v0
	v_mov_b32_e32 v46, v0
	v_mov_b32_e32 v47, v0
	v_mov_b32_e32 v48, v0
	v_mov_b32_e32 v49, v0
	v_mov_b32_e32 v50, v0
	v_mov_b32_e32 v51, v0
	v_mov_b32_e32 v52, v0
	v_mov_b32_e32 v53, v0
	v_mov_b32_e32 v54, v0
	v_mov_b32_e32 v55, v0
	v_mov_b32_e32 v56, v0
	v_mov_b32_e32 v57, v0
	v_mov_b32_e32 v58, v0
	v_mov_b32_e32 v59, v0
	v_mov_b32_e32 v60, v0
	v_mov_b32_e32 v61, v0
	v_mov_b32_e32 v66, v0
	v_mov_b32_e32 v67, v0
	v_mov_b32_e32 v68, v0
	v_mov_b32_e32 v69, v0
	v_mov_b32_e32 v98, v0
	v_mov_b32_e32 v99, v0
	v_mov_b32_e32 v100, v0
	v_mov_b32_e32 v101, v0
	v_mov_b32_e32 v102, v0
	v_mov_b32_e32 v103, v0
	v_mov_b32_e32 v104, v0
	v_mov_b32_e32 v105, v0
	v_mov_b32_e32 v106, v0
	v_mov_b32_e32 v107, v0
	v_mov_b32_e32 v108, v0
	v_mov_b32_e32 v109, v0
	v_mov_b32_e32 v110, v0
	v_mov_b32_e32 v111, v0
	v_mov_b32_e32 v112, v0
	v_mov_b32_e32 v113, v0
	v_mov_b32_e32 v114, v0
	v_mov_b32_e32 v115, v0
	v_mov_b32_e32 v116, v0
	v_mov_b32_e32 v117, v0
	v_mov_b32_e32 v118, v0
	v_mov_b32_e32 v119, v0
	v_mov_b32_e32 v120, v0
	v_mov_b32_e32 v121, v0
	v_mov_b32_e32 v122, v0
	v_mov_b32_e32 v123, v0
	v_mov_b32_e32 v124, v0
	v_mov_b32_e32 v125, v0
	v_mov_b32_e32 v126, v0
	v_mov_b32_e32 v127, v0
	v_mov_b32_e32 v128, v0
	v_mov_b32_e32 v129, v0
	s_cmp_eq_u32 s37, 1
	s_cbranch_scc1 .LBB0_228
	s_add_u32 s0, s22, 0xfffc0080
	s_addc_u32 s1, s23, -1
	s_add_i32 s3, 0, 0x10000
	s_cmp_eq_u32 s24, 12
	s_cselect_b32 s15, s49, s1
	s_cselect_b32 s14, s48, s0
	v_add_u32_e32 v162, s3, v149
	s_cselect_b32 s1, s2, s10
	s_cselect_b32 s0, s8, s9
	s_add_i32 s6, 0, 0x14000
	ds_read_b128 v[140:143], v162
	ds_read_b128 v[144:147], v162 offset:1024
	ds_read_b128 v[172:175], v162 offset:2048
	ds_read_b128 v[190:193], v162 offset:3072
	v_add_u32_e32 v162, s6, v149
	ds_read_b128 v[194:197], v162
	ds_read_b128 v[198:201], v162 offset:1024
	ds_read_b128 v[202:205], v162 offset:2048
	ds_read_b128 v[206:209], v162 offset:3072
	s_add_i32 m0, s27, 0xc000
	ds_read_b128 v[210:213], v151
	ds_read_b128 v[214:217], v151 offset:1024
	ds_read_b128 v[218:221], v151 offset:2048
	ds_read_b128 v[222:225], v151 offset:3072
	ds_read_b128 v[226:229], v151 offset:4096
	ds_read_b128 v[230:233], v151 offset:5120
	ds_read_b128 v[234:237], v151 offset:6144
	ds_read_b128 v[238:241], v151 offset:7168
	global_load_lds_dwordx4 v136, s[22:23]
	s_add_i32 m0, s27, 0xe000
	s_nop 0
	global_load_lds_dwordx4 v138, s[22:23]
	s_waitcnt vmcnt(24)
	s_waitcnt lgkmcnt(0)
	s_barrier
	s_waitcnt lgkmcnt(0)
	v_mfma_f32_16x16x32_bf16 v[126:129], v[140:143], v[210:213], v[126:129]
	v_mfma_f32_16x16x32_bf16 v[122:125], v[172:175], v[210:213], v[122:125]
	v_mfma_f32_16x16x32_bf16 v[118:121], v[140:143], v[218:221], v[118:121]
	v_mfma_f32_16x16x32_bf16 v[114:117], v[172:175], v[218:221], v[114:117]
	v_mfma_f32_16x16x32_bf16 v[110:113], v[140:143], v[226:229], v[110:113]
	v_mfma_f32_16x16x32_bf16 v[106:109], v[172:175], v[226:229], v[106:109]
	v_mfma_f32_16x16x32_bf16 v[102:105], v[140:143], v[234:237], v[102:105]
	v_mfma_f32_16x16x32_bf16 v[98:101], v[172:175], v[234:237], v[98:101]
	v_mfma_f32_16x16x32_bf16 v[126:129], v[144:147], v[214:217], v[126:129]
	v_mfma_f32_16x16x32_bf16 v[122:125], v[190:193], v[214:217], v[122:125]
	v_mfma_f32_16x16x32_bf16 v[118:121], v[144:147], v[222:225], v[118:121]
	v_mfma_f32_16x16x32_bf16 v[114:117], v[190:193], v[222:225], v[114:117]
	v_mfma_f32_16x16x32_bf16 v[110:113], v[144:147], v[230:233], v[110:113]
	v_mfma_f32_16x16x32_bf16 v[106:109], v[190:193], v[230:233], v[106:109]
	v_mfma_f32_16x16x32_bf16 v[102:105], v[144:147], v[238:241], v[102:105]
	v_mfma_f32_16x16x32_bf16 v[98:101], v[190:193], v[238:241], v[98:101]
	v_mfma_f32_16x16x32_bf16 v[66:69], v[194:197], v[210:213], v[66:69]
	v_mfma_f32_16x16x32_bf16 v[58:61], v[202:205], v[210:213], v[58:61]
	v_mfma_f32_16x16x32_bf16 v[54:57], v[194:197], v[218:221], v[54:57]
	v_mfma_f32_16x16x32_bf16 v[50:53], v[202:205], v[218:221], v[50:53]
	v_mfma_f32_16x16x32_bf16 v[46:49], v[194:197], v[226:229], v[46:49]
	v_mfma_f32_16x16x32_bf16 v[42:45], v[202:205], v[226:229], v[42:45]
	v_mfma_f32_16x16x32_bf16 v[38:41], v[194:197], v[234:237], v[38:41]
	v_mfma_f32_16x16x32_bf16 v[34:37], v[202:205], v[234:237], v[34:37]
	v_mfma_f32_16x16x32_bf16 v[66:69], v[198:201], v[214:217], v[66:69]
	v_mfma_f32_16x16x32_bf16 v[58:61], v[206:209], v[214:217], v[58:61]
	v_mfma_f32_16x16x32_bf16 v[54:57], v[198:201], v[222:225], v[54:57]
	v_mfma_f32_16x16x32_bf16 v[50:53], v[206:209], v[222:225], v[50:53]
	v_mfma_f32_16x16x32_bf16 v[46:49], v[198:201], v[230:233], v[46:49]
	v_mfma_f32_16x16x32_bf16 v[42:45], v[206:209], v[230:233], v[42:45]
	v_mfma_f32_16x16x32_bf16 v[38:41], v[198:201], v[238:241], v[38:41]
	v_mfma_f32_16x16x32_bf16 v[34:37], v[206:209], v[238:241], v[34:37]
	s_barrier
	s_add_i32 s3, s3, s26
	v_lshl_add_u64 v[162:163], s[0:1], 0, v[4:5]
	s_mov_b32 m0, s3
	ds_read_b128 v[210:213], v151 offset:16384
	ds_read_b128 v[214:217], v151 offset:17408
	ds_read_b128 v[218:221], v151 offset:18432
	ds_read_b128 v[222:225], v151 offset:19456
	ds_read_b128 v[226:229], v151 offset:20480
	ds_read_b128 v[230:233], v151 offset:21504
	ds_read_b128 v[234:237], v151 offset:22528
	ds_read_b128 v[238:241], v151 offset:23552
	global_load_lds_dwordx4 v4, s[0:1]
	s_add_i32 m0, s3, 0x2000
	s_add_u32 s4, s0, 0x40000
	v_lshl_add_u64 v[166:167], s[0:1], 0, v[134:135]
	s_addc_u32 s5, s1, 0
	s_add_i32 s3, s6, s26
	global_load_lds_dwordx4 v134, s[0:1]
	s_mov_b32 m0, s3
	v_lshl_add_u64 v[180:181], s[14:15], 0, v[132:133]
	global_load_lds_dwordx4 v4, s[4:5]
	s_add_i32 m0, s3, 0x2000
	s_nop 0
	global_load_lds_dwordx4 v134, s[4:5]
	v_lshl_add_u64 v[176:177], s[14:15], 0, v[130:131]
	s_mov_b32 m0, s27
	s_nop 0
	global_load_lds_dwordx4 v130, s[14:15]
	s_mov_b32 m0, s30
	s_nop 0
	global_load_lds_dwordx4 v132, s[14:15]
	s_waitcnt vmcnt(24)
	s_waitcnt lgkmcnt(0)
	s_barrier
	s_waitcnt lgkmcnt(0)
	v_mfma_f32_16x16x32_bf16 v[94:97], v[140:143], v[210:213], v[94:97]
	v_mfma_f32_16x16x32_bf16 v[90:93], v[172:175], v[210:213], v[90:93]
	v_mfma_f32_16x16x32_bf16 v[86:89], v[140:143], v[218:221], v[86:89]
	v_mfma_f32_16x16x32_bf16 v[82:85], v[172:175], v[218:221], v[82:85]
	v_mfma_f32_16x16x32_bf16 v[78:81], v[140:143], v[226:229], v[78:81]
	v_mfma_f32_16x16x32_bf16 v[74:77], v[172:175], v[226:229], v[74:77]
	v_mfma_f32_16x16x32_bf16 v[70:73], v[140:143], v[234:237], v[70:73]
	v_mfma_f32_16x16x32_bf16 v[62:65], v[172:175], v[234:237], v[62:65]
	v_mfma_f32_16x16x32_bf16 v[94:97], v[144:147], v[214:217], v[94:97]
	v_mfma_f32_16x16x32_bf16 v[90:93], v[190:193], v[214:217], v[90:93]
	v_mfma_f32_16x16x32_bf16 v[86:89], v[144:147], v[222:225], v[86:89]
	v_mfma_f32_16x16x32_bf16 v[82:85], v[190:193], v[222:225], v[82:85]
	v_mfma_f32_16x16x32_bf16 v[78:81], v[144:147], v[230:233], v[78:81]
	v_mfma_f32_16x16x32_bf16 v[74:77], v[190:193], v[230:233], v[74:77]
	v_mfma_f32_16x16x32_bf16 v[70:73], v[144:147], v[238:241], v[70:73]
	v_mfma_f32_16x16x32_bf16 v[62:65], v[190:193], v[238:241], v[62:65]
	v_mfma_f32_16x16x32_bf16 v[30:33], v[194:197], v[210:213], v[30:33]
	v_mfma_f32_16x16x32_bf16 v[26:29], v[202:205], v[210:213], v[26:29]
	v_mfma_f32_16x16x32_bf16 v[22:25], v[194:197], v[218:221], v[22:25]
	v_mfma_f32_16x16x32_bf16 v[18:21], v[202:205], v[218:221], v[18:21]
	v_mfma_f32_16x16x32_bf16 v[14:17], v[194:197], v[226:229], v[14:17]
	v_mfma_f32_16x16x32_bf16 v[10:13], v[202:205], v[226:229], v[10:13]
	v_mfma_f32_16x16x32_bf16 v[6:9], v[194:197], v[234:237], v[6:9]
	v_mfma_f32_16x16x32_bf16 v[0:3], v[202:205], v[234:237], v[0:3]
	v_mfma_f32_16x16x32_bf16 v[30:33], v[198:201], v[214:217], v[30:33]
	v_mfma_f32_16x16x32_bf16 v[26:29], v[206:209], v[214:217], v[26:29]
	v_mfma_f32_16x16x32_bf16 v[22:25], v[198:201], v[222:225], v[22:25]
	v_mfma_f32_16x16x32_bf16 v[18:21], v[206:209], v[222:225], v[18:21]
	v_mfma_f32_16x16x32_bf16 v[14:17], v[198:201], v[230:233], v[14:17]
	v_mfma_f32_16x16x32_bf16 v[10:13], v[206:209], v[230:233], v[10:13]
	v_mfma_f32_16x16x32_bf16 v[6:9], v[198:201], v[238:241], v[6:9]
	v_mfma_f32_16x16x32_bf16 v[0:3], v[206:209], v[238:241], v[0:3]
	s_barrier
	s_branch .Lpeelmid_228
.LBB0_228:
	s_add_u32 s0, s22, 0xfffc0080
	s_addc_u32 s1, s23, -1
	s_add_i32 s3, 0, 0x10000
	s_cmp_eq_u32 s24, 12
	s_cselect_b32 s15, s49, s1
	s_cselect_b32 s14, s48, s0
	v_add_u32_e32 v162, s3, v149
	s_cselect_b32 s1, s2, s10
	s_cselect_b32 s0, s8, s9
	s_add_i32 s6, 0, 0x14000
	ds_read_b128 v[140:143], v162
	ds_read_b128 v[144:147], v162 offset:1024
	ds_read_b128 v[172:175], v162 offset:2048
	ds_read_b128 v[190:193], v162 offset:3072
	v_add_u32_e32 v162, s6, v149
	ds_read_b128 v[194:197], v162
	ds_read_b128 v[198:201], v162 offset:1024
	ds_read_b128 v[202:205], v162 offset:2048
	ds_read_b128 v[206:209], v162 offset:3072
	s_add_i32 m0, s27, 0xc000
	ds_read_b128 v[210:213], v151
	ds_read_b128 v[214:217], v151 offset:1024
	ds_read_b128 v[218:221], v151 offset:2048
	ds_read_b128 v[222:225], v151 offset:3072
	ds_read_b128 v[226:229], v151 offset:4096
	ds_read_b128 v[230:233], v151 offset:5120
	ds_read_b128 v[234:237], v151 offset:6144
	ds_read_b128 v[238:241], v151 offset:7168
	global_load_lds_dwordx4 v136, s[22:23]
	s_add_i32 m0, s27, 0xe000
	s_nop 0
	global_load_lds_dwordx4 v138, s[22:23]
	s_waitcnt vmcnt(8)
	s_waitcnt lgkmcnt(0)
	s_barrier
	s_waitcnt lgkmcnt(0)
	v_mfma_f32_16x16x32_bf16 v[126:129], v[140:143], v[210:213], v[126:129]
	v_mfma_f32_16x16x32_bf16 v[122:125], v[172:175], v[210:213], v[122:125]
	v_mfma_f32_16x16x32_bf16 v[118:121], v[140:143], v[218:221], v[118:121]
	v_mfma_f32_16x16x32_bf16 v[114:117], v[172:175], v[218:221], v[114:117]
	v_mfma_f32_16x16x32_bf16 v[110:113], v[140:143], v[226:229], v[110:113]
	v_mfma_f32_16x16x32_bf16 v[106:109], v[172:175], v[226:229], v[106:109]
	v_mfma_f32_16x16x32_bf16 v[102:105], v[140:143], v[234:237], v[102:105]
	v_mfma_f32_16x16x32_bf16 v[98:101], v[172:175], v[234:237], v[98:101]
	v_mfma_f32_16x16x32_bf16 v[126:129], v[144:147], v[214:217], v[126:129]
	v_mfma_f32_16x16x32_bf16 v[122:125], v[190:193], v[214:217], v[122:125]
	v_mfma_f32_16x16x32_bf16 v[118:121], v[144:147], v[222:225], v[118:121]
	v_mfma_f32_16x16x32_bf16 v[114:117], v[190:193], v[222:225], v[114:117]
	v_mfma_f32_16x16x32_bf16 v[110:113], v[144:147], v[230:233], v[110:113]
	v_mfma_f32_16x16x32_bf16 v[106:109], v[190:193], v[230:233], v[106:109]
	v_mfma_f32_16x16x32_bf16 v[102:105], v[144:147], v[238:241], v[102:105]
	v_mfma_f32_16x16x32_bf16 v[98:101], v[190:193], v[238:241], v[98:101]
	v_mfma_f32_16x16x32_bf16 v[66:69], v[194:197], v[210:213], v[66:69]
	v_mfma_f32_16x16x32_bf16 v[58:61], v[202:205], v[210:213], v[58:61]
	v_mfma_f32_16x16x32_bf16 v[54:57], v[194:197], v[218:221], v[54:57]
	v_mfma_f32_16x16x32_bf16 v[50:53], v[202:205], v[218:221], v[50:53]
	v_mfma_f32_16x16x32_bf16 v[46:49], v[194:197], v[226:229], v[46:49]
	v_mfma_f32_16x16x32_bf16 v[42:45], v[202:205], v[226:229], v[42:45]
	v_mfma_f32_16x16x32_bf16 v[38:41], v[194:197], v[234:237], v[38:41]
	v_mfma_f32_16x16x32_bf16 v[34:37], v[202:205], v[234:237], v[34:37]
	v_mfma_f32_16x16x32_bf16 v[66:69], v[198:201], v[214:217], v[66:69]
	v_mfma_f32_16x16x32_bf16 v[58:61], v[206:209], v[214:217], v[58:61]
	v_mfma_f32_16x16x32_bf16 v[54:57], v[198:201], v[222:225], v[54:57]
	v_mfma_f32_16x16x32_bf16 v[50:53], v[206:209], v[222:225], v[50:53]
	v_mfma_f32_16x16x32_bf16 v[46:49], v[198:201], v[230:233], v[46:49]
	v_mfma_f32_16x16x32_bf16 v[42:45], v[206:209], v[230:233], v[42:45]
	v_mfma_f32_16x16x32_bf16 v[38:41], v[198:201], v[238:241], v[38:41]
	v_mfma_f32_16x16x32_bf16 v[34:37], v[206:209], v[238:241], v[34:37]
	s_barrier
	s_add_i32 s3, s3, s26
	v_lshl_add_u64 v[162:163], s[0:1], 0, v[4:5]
	s_mov_b32 m0, s3
	ds_read_b128 v[210:213], v151 offset:16384
	ds_read_b128 v[214:217], v151 offset:17408
	ds_read_b128 v[218:221], v151 offset:18432
	ds_read_b128 v[222:225], v151 offset:19456
	ds_read_b128 v[226:229], v151 offset:20480
	ds_read_b128 v[230:233], v151 offset:21504
	ds_read_b128 v[234:237], v151 offset:22528
	ds_read_b128 v[238:241], v151 offset:23552
	global_load_lds_dwordx4 v4, s[0:1]
	s_add_i32 m0, s3, 0x2000
	s_add_u32 s4, s0, 0x40000
	v_lshl_add_u64 v[166:167], s[0:1], 0, v[134:135]
	s_addc_u32 s5, s1, 0
	s_add_i32 s3, s6, s26
	global_load_lds_dwordx4 v134, s[0:1]
	s_mov_b32 m0, s3
	v_lshl_add_u64 v[180:181], s[14:15], 0, v[132:133]
	global_load_lds_dwordx4 v4, s[4:5]
	s_add_i32 m0, s3, 0x2000
	s_nop 0
	global_load_lds_dwordx4 v134, s[4:5]
	v_lshl_add_u64 v[176:177], s[14:15], 0, v[130:131]
	s_mov_b32 m0, s27
	s_nop 0
	global_load_lds_dwordx4 v130, s[14:15]
	s_mov_b32 m0, s30
	s_nop 0
	global_load_lds_dwordx4 v132, s[14:15]
	s_waitcnt vmcnt(8)
	s_waitcnt lgkmcnt(0)
	s_barrier
	s_waitcnt lgkmcnt(0)
	v_mfma_f32_16x16x32_bf16 v[94:97], v[140:143], v[210:213], v[94:97]
	v_mfma_f32_16x16x32_bf16 v[90:93], v[172:175], v[210:213], v[90:93]
	v_mfma_f32_16x16x32_bf16 v[86:89], v[140:143], v[218:221], v[86:89]
	v_mfma_f32_16x16x32_bf16 v[82:85], v[172:175], v[218:221], v[82:85]
	v_mfma_f32_16x16x32_bf16 v[78:81], v[140:143], v[226:229], v[78:81]
	v_mfma_f32_16x16x32_bf16 v[74:77], v[172:175], v[226:229], v[74:77]
	v_mfma_f32_16x16x32_bf16 v[70:73], v[140:143], v[234:237], v[70:73]
	v_mfma_f32_16x16x32_bf16 v[62:65], v[172:175], v[234:237], v[62:65]
	v_mfma_f32_16x16x32_bf16 v[94:97], v[144:147], v[214:217], v[94:97]
	v_mfma_f32_16x16x32_bf16 v[90:93], v[190:193], v[214:217], v[90:93]
	v_mfma_f32_16x16x32_bf16 v[86:89], v[144:147], v[222:225], v[86:89]
	v_mfma_f32_16x16x32_bf16 v[82:85], v[190:193], v[222:225], v[82:85]
	v_mfma_f32_16x16x32_bf16 v[78:81], v[144:147], v[230:233], v[78:81]
	v_mfma_f32_16x16x32_bf16 v[74:77], v[190:193], v[230:233], v[74:77]
	v_mfma_f32_16x16x32_bf16 v[70:73], v[144:147], v[238:241], v[70:73]
	v_mfma_f32_16x16x32_bf16 v[62:65], v[190:193], v[238:241], v[62:65]
	v_mfma_f32_16x16x32_bf16 v[30:33], v[194:197], v[210:213], v[30:33]
	v_mfma_f32_16x16x32_bf16 v[26:29], v[202:205], v[210:213], v[26:29]
	v_mfma_f32_16x16x32_bf16 v[22:25], v[194:197], v[218:221], v[22:25]
	v_mfma_f32_16x16x32_bf16 v[18:21], v[202:205], v[218:221], v[18:21]
	v_mfma_f32_16x16x32_bf16 v[14:17], v[194:197], v[226:229], v[14:17]
	v_mfma_f32_16x16x32_bf16 v[10:13], v[202:205], v[226:229], v[10:13]
	v_mfma_f32_16x16x32_bf16 v[6:9], v[194:197], v[234:237], v[6:9]
	v_mfma_f32_16x16x32_bf16 v[0:3], v[202:205], v[234:237], v[0:3]
	v_mfma_f32_16x16x32_bf16 v[30:33], v[198:201], v[214:217], v[30:33]
	v_mfma_f32_16x16x32_bf16 v[26:29], v[206:209], v[214:217], v[26:29]
	v_mfma_f32_16x16x32_bf16 v[22:25], v[198:201], v[222:225], v[22:25]
	v_mfma_f32_16x16x32_bf16 v[18:21], v[206:209], v[222:225], v[18:21]
	v_mfma_f32_16x16x32_bf16 v[14:17], v[198:201], v[230:233], v[14:17]
	v_mfma_f32_16x16x32_bf16 v[10:13], v[206:209], v[230:233], v[10:13]
	v_mfma_f32_16x16x32_bf16 v[6:9], v[198:201], v[238:241], v[6:9]
	v_mfma_f32_16x16x32_bf16 v[0:3], v[206:209], v[238:241], v[0:3]
	s_barrier
.Lpeelmid_228:
	s_add_i32 s3, 0, 0x18000
	v_add_u32_e32 v164, s3, v149
	s_add_i32 s6, 0, 0x1c000
	ds_read_b128 v[140:143], v164
	ds_read_b128 v[144:147], v164 offset:1024
	ds_read_b128 v[172:175], v164 offset:2048
	ds_read_b128 v[190:193], v164 offset:3072
	v_add_u32_e32 v164, s6, v149
	ds_read_b128 v[194:197], v164
	ds_read_b128 v[198:201], v164 offset:1024
	ds_read_b128 v[202:205], v164 offset:2048
	ds_read_b128 v[206:209], v164 offset:3072
	s_add_u32 s4, s14, 0x40000
	s_addc_u32 s5, s15, 0
	s_mov_b32 m0, s31
	ds_read_b128 v[210:213], v151 offset:32768
	ds_read_b128 v[214:217], v151 offset:33792
	ds_read_b128 v[218:221], v151 offset:34816
	ds_read_b128 v[222:225], v151 offset:35840
	ds_read_b128 v[226:229], v151 offset:36864
	ds_read_b128 v[230:233], v151 offset:37888
	ds_read_b128 v[234:237], v151 offset:38912
	ds_read_b128 v[238:241], v151 offset:39936
	global_load_lds_dwordx4 v130, s[4:5]
	v_lshl_add_u64 v[242:243], s[4:5], 0, v[132:133]
	s_mov_b32 m0, s34
	s_nop 0
	global_load_lds_dwordx4 v132, s[4:5]
	s_waitcnt vmcnt(8)
	s_waitcnt lgkmcnt(0)
	s_barrier
	s_waitcnt lgkmcnt(0)
	v_mfma_f32_16x16x32_bf16 v[126:129], v[140:143], v[210:213], v[126:129]
	v_mfma_f32_16x16x32_bf16 v[122:125], v[172:175], v[210:213], v[122:125]
	v_mfma_f32_16x16x32_bf16 v[118:121], v[140:143], v[218:221], v[118:121]
	v_mfma_f32_16x16x32_bf16 v[114:117], v[172:175], v[218:221], v[114:117]
	v_mfma_f32_16x16x32_bf16 v[110:113], v[140:143], v[226:229], v[110:113]
	v_mfma_f32_16x16x32_bf16 v[106:109], v[172:175], v[226:229], v[106:109]
	v_mfma_f32_16x16x32_bf16 v[102:105], v[140:143], v[234:237], v[102:105]
	v_mfma_f32_16x16x32_bf16 v[98:101], v[172:175], v[234:237], v[98:101]
	v_mfma_f32_16x16x32_bf16 v[126:129], v[144:147], v[214:217], v[126:129]
	v_mfma_f32_16x16x32_bf16 v[122:125], v[190:193], v[214:217], v[122:125]
	v_mfma_f32_16x16x32_bf16 v[118:121], v[144:147], v[222:225], v[118:121]
	v_mfma_f32_16x16x32_bf16 v[114:117], v[190:193], v[222:225], v[114:117]
	v_mfma_f32_16x16x32_bf16 v[110:113], v[144:147], v[230:233], v[110:113]
	v_mfma_f32_16x16x32_bf16 v[106:109], v[190:193], v[230:233], v[106:109]
	v_mfma_f32_16x16x32_bf16 v[102:105], v[144:147], v[238:241], v[102:105]
	v_mfma_f32_16x16x32_bf16 v[98:101], v[190:193], v[238:241], v[98:101]
	v_mfma_f32_16x16x32_bf16 v[66:69], v[194:197], v[210:213], v[66:69]
	v_mfma_f32_16x16x32_bf16 v[58:61], v[202:205], v[210:213], v[58:61]
	v_mfma_f32_16x16x32_bf16 v[54:57], v[194:197], v[218:221], v[54:57]
	v_mfma_f32_16x16x32_bf16 v[50:53], v[202:205], v[218:221], v[50:53]
	v_mfma_f32_16x16x32_bf16 v[46:49], v[194:197], v[226:229], v[46:49]
	v_mfma_f32_16x16x32_bf16 v[42:45], v[202:205], v[226:229], v[42:45]
	v_mfma_f32_16x16x32_bf16 v[38:41], v[194:197], v[234:237], v[38:41]
	v_mfma_f32_16x16x32_bf16 v[34:37], v[202:205], v[234:237], v[34:37]
	v_mfma_f32_16x16x32_bf16 v[66:69], v[198:201], v[214:217], v[66:69]
	v_mfma_f32_16x16x32_bf16 v[58:61], v[206:209], v[214:217], v[58:61]
	v_mfma_f32_16x16x32_bf16 v[54:57], v[198:201], v[222:225], v[54:57]
	v_mfma_f32_16x16x32_bf16 v[50:53], v[206:209], v[222:225], v[50:53]
	v_mfma_f32_16x16x32_bf16 v[46:49], v[198:201], v[230:233], v[46:49]
	v_mfma_f32_16x16x32_bf16 v[42:45], v[206:209], v[230:233], v[42:45]
	v_mfma_f32_16x16x32_bf16 v[38:41], v[198:201], v[238:241], v[38:41]
	v_mfma_f32_16x16x32_bf16 v[34:37], v[206:209], v[238:241], v[34:37]
	s_barrier
	s_add_i32 s3, s3, s26
	v_lshl_add_u64 v[162:163], v[162:163], 0, s[70:71]
	s_mov_b32 m0, s3
	ds_read_b128 v[210:213], v151 offset:49152
	ds_read_b128 v[214:217], v151 offset:50176
	ds_read_b128 v[218:221], v151 offset:51200
	ds_read_b128 v[222:225], v151 offset:52224
	ds_read_b128 v[226:229], v151 offset:53248
	ds_read_b128 v[230:233], v151 offset:54272
	ds_read_b128 v[234:237], v151 offset:55296
	ds_read_b128 v[238:241], v151 offset:56320
	global_load_lds_dwordx4 v[162:163], off
	s_add_i32 m0, s3, 0x2000
	s_add_u32 s0, s0, 0x40080
	v_lshl_add_u64 v[162:163], v[166:167], 0, s[70:71]
	s_addc_u32 s1, s1, 0
	s_add_i32 s3, s6, s26
	global_load_lds_dwordx4 v[162:163], off
	s_mov_b32 m0, s3
	s_nop 0
	global_load_lds_dwordx4 v4, s[0:1]
	s_add_i32 m0, s3, 0x2000
	s_nop 0
	global_load_lds_dwordx4 v134, s[0:1]
	v_lshl_add_u64 v[162:163], v[176:177], 0, s[70:71]
	s_mov_b32 m0, s35
	s_nop 0
	global_load_lds_dwordx4 v[162:163], off
	v_lshl_add_u64 v[162:163], v[180:181], 0, s[70:71]
	s_mov_b32 m0, s36
	s_nop 0
	global_load_lds_dwordx4 v[162:163], off
	s_waitcnt vmcnt(8)
	s_waitcnt lgkmcnt(0)
	s_barrier
	s_waitcnt lgkmcnt(0)
	v_mfma_f32_16x16x32_bf16 v[94:97], v[140:143], v[210:213], v[94:97]
	v_mfma_f32_16x16x32_bf16 v[90:93], v[172:175], v[210:213], v[90:93]
	v_mfma_f32_16x16x32_bf16 v[86:89], v[140:143], v[218:221], v[86:89]
	v_mfma_f32_16x16x32_bf16 v[82:85], v[172:175], v[218:221], v[82:85]
	v_mfma_f32_16x16x32_bf16 v[78:81], v[140:143], v[226:229], v[78:81]
	v_mfma_f32_16x16x32_bf16 v[74:77], v[172:175], v[226:229], v[74:77]
	v_mfma_f32_16x16x32_bf16 v[70:73], v[140:143], v[234:237], v[70:73]
	v_mfma_f32_16x16x32_bf16 v[62:65], v[172:175], v[234:237], v[62:65]
	v_mfma_f32_16x16x32_bf16 v[94:97], v[144:147], v[214:217], v[94:97]
	v_mfma_f32_16x16x32_bf16 v[90:93], v[190:193], v[214:217], v[90:93]
	v_mfma_f32_16x16x32_bf16 v[86:89], v[144:147], v[222:225], v[86:89]
	v_mfma_f32_16x16x32_bf16 v[82:85], v[190:193], v[222:225], v[82:85]
	v_mfma_f32_16x16x32_bf16 v[78:81], v[144:147], v[230:233], v[78:81]
	v_mfma_f32_16x16x32_bf16 v[74:77], v[190:193], v[230:233], v[74:77]
	v_mfma_f32_16x16x32_bf16 v[70:73], v[144:147], v[238:241], v[70:73]
	v_mfma_f32_16x16x32_bf16 v[62:65], v[190:193], v[238:241], v[62:65]
	v_mfma_f32_16x16x32_bf16 v[30:33], v[194:197], v[210:213], v[30:33]
	v_mfma_f32_16x16x32_bf16 v[26:29], v[202:205], v[210:213], v[26:29]
	v_mfma_f32_16x16x32_bf16 v[22:25], v[194:197], v[218:221], v[22:25]
	v_mfma_f32_16x16x32_bf16 v[18:21], v[202:205], v[218:221], v[18:21]
	v_mfma_f32_16x16x32_bf16 v[14:17], v[194:197], v[226:229], v[14:17]
	v_mfma_f32_16x16x32_bf16 v[10:13], v[202:205], v[226:229], v[10:13]
	v_mfma_f32_16x16x32_bf16 v[6:9], v[194:197], v[234:237], v[6:9]
	v_mfma_f32_16x16x32_bf16 v[0:3], v[202:205], v[234:237], v[0:3]
	v_mfma_f32_16x16x32_bf16 v[30:33], v[198:201], v[214:217], v[30:33]
	v_mfma_f32_16x16x32_bf16 v[26:29], v[206:209], v[214:217], v[26:29]
	v_mfma_f32_16x16x32_bf16 v[22:25], v[198:201], v[222:225], v[22:25]
	v_mfma_f32_16x16x32_bf16 v[18:21], v[206:209], v[222:225], v[18:21]
	v_mfma_f32_16x16x32_bf16 v[14:17], v[198:201], v[230:233], v[14:17]
	v_mfma_f32_16x16x32_bf16 v[10:13], v[206:209], v[230:233], v[10:13]
	v_mfma_f32_16x16x32_bf16 v[6:9], v[198:201], v[238:241], v[6:9]
	v_mfma_f32_16x16x32_bf16 v[0:3], v[206:209], v[238:241], v[0:3]
	s_barrier
	s_add_i32 s24, s24, 2
	s_add_u32 s22, s22, 0x100
	s_addc_u32 s23, s23, 0
	s_add_u32 s9, s9, 0x100
	s_addc_u32 s10, s10, 0
	s_cmp_gt_u32 s24, 13
	s_cbranch_scc0 .LBB0_228
	s_and_b64 vcc, exec, s[44:45]
	s_cbranch_vccz .LBB0_231
	s_barrier

.LBB0_251:
	s_ashr_i32 s47, s46, 31
	s_lshl_b64 s[2:3], s[46:47], 20
	v_readlane_b32 s4, v253, 36
	s_add_u32 s82, s4, s2
	v_readlane_b32 s2, v253, 37
	s_addc_u32 s83, s2, s3
	s_and_b64 s[2:3], s[40:41], exec
	s_cselect_b32 s2, s83, s15
	s_cselect_b32 s8, s82, s14
	s_add_u32 s22, s0, 0x80080
	s_addc_u32 s23, s1, 0
	s_add_u32 s9, s14, 0x100
	v_mov_b32_e32 v0, 0
	s_addc_u32 s10, s15, 0
	s_mov_b32 s24, -2
	v_mov_b32_e32 v1, v0
	v_mov_b32_e32 v2, v0
	v_mov_b32_e32 v3, v0
	v_mov_b32_e32 v6, v0
	v_mov_b32_e32 v7, v0
	v_mov_b32_e32 v8, v0
	v_mov_b32_e32 v9, v0
	v_mov_b32_e32 v10, v0
	v_mov_b32_e32 v11, v0
	v_mov_b32_e32 v12, v0
	v_mov_b32_e32 v13, v0
	v_mov_b32_e32 v14, v0
	v_mov_b32_e32 v15, v0
	v_mov_b32_e32 v16, v0
	v_mov_b32_e32 v17, v0
	v_mov_b32_e32 v18, v0
	v_mov_b32_e32 v19, v0
	v_mov_b32_e32 v20, v0
	v_mov_b32_e32 v21, v0
	v_mov_b32_e32 v22, v0
	v_mov_b32_e32 v23, v0
	v_mov_b32_e32 v24, v0
	v_mov_b32_e32 v25, v0
	v_mov_b32_e32 v26, v0
	v_mov_b32_e32 v27, v0
	v_mov_b32_e32 v28, v0
	v_mov_b32_e32 v29, v0
	v_mov_b32_e32 v30, v0
	v_mov_b32_e32 v31, v0
	v_mov_b32_e32 v32, v0
	v_mov_b32_e32 v33, v0
	v_mov_b32_e32 v62, v0
	v_mov_b32_e32 v63, v0
	v_mov_b32_e32 v64, v0
	v_mov_b32_e32 v65, v0
	v_mov_b32_e32 v70, v0
	v_mov_b32_e32 v71, v0
	v_mov_b32_e32 v72, v0
	v_mov_b32_e32 v73, v0
	v_mov_b32_e32 v74, v0
	v_mov_b32_e32 v75, v0
	v_mov_b32_e32 v76, v0
	v_mov_b32_e32 v77, v0
	v_mov_b32_e32 v78, v0
	v_mov_b32_e32 v79, v0
	v_mov_b32_e32 v80, v0
	v_mov_b32_e32 v81, v0
	v_mov_b32_e32 v82, v0
	v_mov_b32_e32 v83, v0
	v_mov_b32_e32 v84, v0
	v_mov_b32_e32 v85, v0
	v_mov_b32_e32 v86, v0
	v_mov_b32_e32 v87, v0
	v_mov_b32_e32 v88, v0
	v_mov_b32_e32 v89, v0
	v_mov_b32_e32 v90, v0
	v_mov_b32_e32 v91, v0
	v_mov_b32_e32 v92, v0
	v_mov_b32_e32 v93, v0
	v_mov_b32_e32 v94, v0
	v_mov_b32_e32 v95, v0
	v_mov_b32_e32 v96, v0
	v_mov_b32_e32 v97, v0
	v_mov_b32_e32 v34, v0
	v_mov_b32_e32 v35, v0
	v_mov_b32_e32 v36, v0
	v_mov_b32_e32 v37, v0
	v_mov_b32_e32 v38, v0
	v_mov_b32_e32 v39, v0
	v_mov_b32_e32 v40, v0
	v_mov_b32_e32 v41, v0
	v_mov_b32_e32 v42, v0
	v_mov_b32_e32 v43, v0
	v_mov_b32_e32 v44, v0
	v_mov_b32_e32 v45, v0
	v_mov_b32_e32 v46, v0
	v_mov_b32_e32 v47, v0
	v_mov_b32_e32 v48, v0
	v_mov_b32_e32 v49, v0
	v_mov_b32_e32 v50, v0
	v_mov_b32_e32 v51, v0
	v_mov_b32_e32 v52, v0
	v_mov_b32_e32 v53, v0
	v_mov_b32_e32 v54, v0
	v_mov_b32_e32 v55, v0
	v_mov_b32_e32 v56, v0
	v_mov_b32_e32 v57, v0
	v_mov_b32_e32 v58, v0
	v_mov_b32_e32 v59, v0
	v_mov_b32_e32 v60, v0
	v_mov_b32_e32 v61, v0
	v_mov_b32_e32 v66, v0
	v_mov_b32_e32 v67, v0
	v_mov_b32_e32 v68, v0
	v_mov_b32_e32 v69, v0
	v_mov_b32_e32 v98, v0
	v_mov_b32_e32 v99, v0
	v_mov_b32_e32 v100, v0
	v_mov_b32_e32 v101, v0
	v_mov_b32_e32 v102, v0
	v_mov_b32_e32 v103, v0
	v_mov_b32_e32 v104, v0
	v_mov_b32_e32 v105, v0
	v_mov_b32_e32 v106, v0
	v_mov_b32_e32 v107, v0
	v_mov_b32_e32 v108, v0
	v_mov_b32_e32 v109, v0
	v_mov_b32_e32 v110, v0
	v_mov_b32_e32 v111, v0
	v_mov_b32_e32 v112, v0
	v_mov_b32_e32 v113, v0
	v_mov_b32_e32 v114, v0
	v_mov_b32_e32 v115, v0
	v_mov_b32_e32 v116, v0
	v_mov_b32_e32 v117, v0
	v_mov_b32_e32 v118, v0
	v_mov_b32_e32 v119, v0
	v_mov_b32_e32 v120, v0
	v_mov_b32_e32 v121, v0
	v_mov_b32_e32 v122, v0
	v_mov_b32_e32 v123, v0
	v_mov_b32_e32 v124, v0
	v_mov_b32_e32 v125, v0
	v_mov_b32_e32 v126, v0
	v_mov_b32_e32 v127, v0
	v_mov_b32_e32 v128, v0
	v_mov_b32_e32 v129, v0
	s_cmp_eq_u32 s37, 1
	s_cbranch_scc1 .LBB0_252
	s_add_u32 s0, s22, 0xfff80080
	s_addc_u32 s1, s23, -1
	s_add_i32 s3, 0, 0x10000
	s_cmp_eq_u32 s24, 28
	s_cselect_b32 s15, s49, s1
	s_cselect_b32 s14, s48, s0
	v_add_u32_e32 v162, s3, v141
	s_cselect_b32 s1, s2, s10
	s_cselect_b32 s0, s8, s9
	s_add_i32 s6, 0, 0x14000
	ds_read_b128 v[144:147], v162
	ds_read_b128 v[148:151], v162 offset:1024
	ds_read_b128 v[172:175], v162 offset:2048
	ds_read_b128 v[190:193], v162 offset:3072
	v_add_u32_e32 v162, s6, v141
	ds_read_b128 v[194:197], v162
	ds_read_b128 v[198:201], v162 offset:1024
	ds_read_b128 v[202:205], v162 offset:2048
	ds_read_b128 v[206:209], v162 offset:3072
	s_add_i32 m0, s27, 0xc000
	ds_read_b128 v[210:213], v143
	ds_read_b128 v[214:217], v143 offset:1024
	ds_read_b128 v[218:221], v143 offset:2048
	ds_read_b128 v[222:225], v143 offset:3072
	ds_read_b128 v[226:229], v143 offset:4096
	ds_read_b128 v[230:233], v143 offset:5120
	ds_read_b128 v[234:237], v143 offset:6144
	ds_read_b128 v[238:241], v143 offset:7168
	global_load_lds_dwordx4 v136, s[22:23]
	s_add_i32 m0, s27, 0xe000
	s_nop 0
	global_load_lds_dwordx4 v138, s[22:23]
	s_waitcnt vmcnt(24)
	s_waitcnt lgkmcnt(0)
	s_barrier
	s_waitcnt lgkmcnt(0)
	v_mfma_f32_16x16x32_bf16 v[126:129], v[144:147], v[210:213], v[126:129]
	v_mfma_f32_16x16x32_bf16 v[122:125], v[172:175], v[210:213], v[122:125]
	v_mfma_f32_16x16x32_bf16 v[118:121], v[144:147], v[218:221], v[118:121]
	v_mfma_f32_16x16x32_bf16 v[114:117], v[172:175], v[218:221], v[114:117]
	v_mfma_f32_16x16x32_bf16 v[110:113], v[144:147], v[226:229], v[110:113]
	v_mfma_f32_16x16x32_bf16 v[106:109], v[172:175], v[226:229], v[106:109]
	v_mfma_f32_16x16x32_bf16 v[102:105], v[144:147], v[234:237], v[102:105]
	v_mfma_f32_16x16x32_bf16 v[98:101], v[172:175], v[234:237], v[98:101]
	v_mfma_f32_16x16x32_bf16 v[126:129], v[148:151], v[214:217], v[126:129]
	v_mfma_f32_16x16x32_bf16 v[122:125], v[190:193], v[214:217], v[122:125]
	v_mfma_f32_16x16x32_bf16 v[118:121], v[148:151], v[222:225], v[118:121]
	v_mfma_f32_16x16x32_bf16 v[114:117], v[190:193], v[222:225], v[114:117]
	v_mfma_f32_16x16x32_bf16 v[110:113], v[148:151], v[230:233], v[110:113]
	v_mfma_f32_16x16x32_bf16 v[106:109], v[190:193], v[230:233], v[106:109]
	v_mfma_f32_16x16x32_bf16 v[102:105], v[148:151], v[238:241], v[102:105]
	v_mfma_f32_16x16x32_bf16 v[98:101], v[190:193], v[238:241], v[98:101]
	v_mfma_f32_16x16x32_bf16 v[66:69], v[194:197], v[210:213], v[66:69]
	v_mfma_f32_16x16x32_bf16 v[58:61], v[202:205], v[210:213], v[58:61]
	v_mfma_f32_16x16x32_bf16 v[54:57], v[194:197], v[218:221], v[54:57]
	v_mfma_f32_16x16x32_bf16 v[50:53], v[202:205], v[218:221], v[50:53]
	v_mfma_f32_16x16x32_bf16 v[46:49], v[194:197], v[226:229], v[46:49]
	v_mfma_f32_16x16x32_bf16 v[42:45], v[202:205], v[226:229], v[42:45]
	v_mfma_f32_16x16x32_bf16 v[38:41], v[194:197], v[234:237], v[38:41]
	v_mfma_f32_16x16x32_bf16 v[34:37], v[202:205], v[234:237], v[34:37]
	v_mfma_f32_16x16x32_bf16 v[66:69], v[198:201], v[214:217], v[66:69]
	v_mfma_f32_16x16x32_bf16 v[58:61], v[206:209], v[214:217], v[58:61]
	v_mfma_f32_16x16x32_bf16 v[54:57], v[198:201], v[222:225], v[54:57]
	v_mfma_f32_16x16x32_bf16 v[50:53], v[206:209], v[222:225], v[50:53]
	v_mfma_f32_16x16x32_bf16 v[46:49], v[198:201], v[230:233], v[46:49]
	v_mfma_f32_16x16x32_bf16 v[42:45], v[206:209], v[230:233], v[42:45]
	v_mfma_f32_16x16x32_bf16 v[38:41], v[198:201], v[238:241], v[38:41]
	v_mfma_f32_16x16x32_bf16 v[34:37], v[206:209], v[238:241], v[34:37]
	s_barrier
	s_add_i32 s3, s3, s26
	v_lshl_add_u64 v[162:163], s[0:1], 0, v[4:5]
	s_mov_b32 m0, s3
	ds_read_b128 v[210:213], v143 offset:16384
	ds_read_b128 v[214:217], v143 offset:17408
	ds_read_b128 v[218:221], v143 offset:18432
	ds_read_b128 v[222:225], v143 offset:19456
	ds_read_b128 v[226:229], v143 offset:20480
	ds_read_b128 v[230:233], v143 offset:21504
	ds_read_b128 v[234:237], v143 offset:22528
	ds_read_b128 v[238:241], v143 offset:23552
	global_load_lds_dwordx4 v4, s[0:1]
	s_add_i32 m0, s3, 0x2000
	s_add_u32 s4, s0, 0x80000
	v_lshl_add_u64 v[166:167], s[0:1], 0, v[130:131]
	s_addc_u32 s5, s1, 0
	s_add_i32 s3, s6, s26
	global_load_lds_dwordx4 v130, s[0:1]
	s_mov_b32 m0, s3
	v_lshl_add_u64 v[242:243], s[14:15], 0, v[132:133]
	global_load_lds_dwordx4 v4, s[4:5]
	s_add_i32 m0, s3, 0x2000
	s_nop 0
	global_load_lds_dwordx4 v130, s[4:5]
	v_lshl_add_u64 v[176:177], s[14:15], 0, v[134:135]
	s_mov_b32 m0, s27
	s_nop 0
	global_load_lds_dwordx4 v134, s[14:15]
	s_mov_b32 m0, s30
	s_nop 0
	global_load_lds_dwordx4 v132, s[14:15]
	s_waitcnt vmcnt(24)
	s_waitcnt lgkmcnt(0)
	s_barrier
	s_waitcnt lgkmcnt(0)
	v_mfma_f32_16x16x32_bf16 v[94:97], v[144:147], v[210:213], v[94:97]
	v_mfma_f32_16x16x32_bf16 v[90:93], v[172:175], v[210:213], v[90:93]
	v_mfma_f32_16x16x32_bf16 v[86:89], v[144:147], v[218:221], v[86:89]
	v_mfma_f32_16x16x32_bf16 v[82:85], v[172:175], v[218:221], v[82:85]
	v_mfma_f32_16x16x32_bf16 v[78:81], v[144:147], v[226:229], v[78:81]
	v_mfma_f32_16x16x32_bf16 v[74:77], v[172:175], v[226:229], v[74:77]
	v_mfma_f32_16x16x32_bf16 v[70:73], v[144:147], v[234:237], v[70:73]
	v_mfma_f32_16x16x32_bf16 v[62:65], v[172:175], v[234:237], v[62:65]
	v_mfma_f32_16x16x32_bf16 v[94:97], v[148:151], v[214:217], v[94:97]
	v_mfma_f32_16x16x32_bf16 v[90:93], v[190:193], v[214:217], v[90:93]
	v_mfma_f32_16x16x32_bf16 v[86:89], v[148:151], v[222:225], v[86:89]
	v_mfma_f32_16x16x32_bf16 v[82:85], v[190:193], v[222:225], v[82:85]
	v_mfma_f32_16x16x32_bf16 v[78:81], v[148:151], v[230:233], v[78:81]
	v_mfma_f32_16x16x32_bf16 v[74:77], v[190:193], v[230:233], v[74:77]
	v_mfma_f32_16x16x32_bf16 v[70:73], v[148:151], v[238:241], v[70:73]
	v_mfma_f32_16x16x32_bf16 v[62:65], v[190:193], v[238:241], v[62:65]
	v_mfma_f32_16x16x32_bf16 v[30:33], v[194:197], v[210:213], v[30:33]
	v_mfma_f32_16x16x32_bf16 v[26:29], v[202:205], v[210:213], v[26:29]
	v_mfma_f32_16x16x32_bf16 v[22:25], v[194:197], v[218:221], v[22:25]
	v_mfma_f32_16x16x32_bf16 v[18:21], v[202:205], v[218:221], v[18:21]
	v_mfma_f32_16x16x32_bf16 v[14:17], v[194:197], v[226:229], v[14:17]
	v_mfma_f32_16x16x32_bf16 v[10:13], v[202:205], v[226:229], v[10:13]
	v_mfma_f32_16x16x32_bf16 v[6:9], v[194:197], v[234:237], v[6:9]
	v_mfma_f32_16x16x32_bf16 v[0:3], v[202:205], v[234:237], v[0:3]
	v_mfma_f32_16x16x32_bf16 v[30:33], v[198:201], v[214:217], v[30:33]
	v_mfma_f32_16x16x32_bf16 v[26:29], v[206:209], v[214:217], v[26:29]
	v_mfma_f32_16x16x32_bf16 v[22:25], v[198:201], v[222:225], v[22:25]
	v_mfma_f32_16x16x32_bf16 v[18:21], v[206:209], v[222:225], v[18:21]
	v_mfma_f32_16x16x32_bf16 v[14:17], v[198:201], v[230:233], v[14:17]
	v_mfma_f32_16x16x32_bf16 v[10:13], v[206:209], v[230:233], v[10:13]
	v_mfma_f32_16x16x32_bf16 v[6:9], v[198:201], v[238:241], v[6:9]
	v_mfma_f32_16x16x32_bf16 v[0:3], v[206:209], v[238:241], v[0:3]
	s_barrier
	s_branch .Lpeelmid_252
.LBB0_252:
	s_add_u32 s0, s22, 0xfff80080
	s_addc_u32 s1, s23, -1
	s_add_i32 s3, 0, 0x10000
	s_cmp_eq_u32 s24, 28
	s_cselect_b32 s15, s49, s1
	s_cselect_b32 s14, s48, s0
	v_add_u32_e32 v162, s3, v141
	s_cselect_b32 s1, s2, s10
	s_cselect_b32 s0, s8, s9
	s_add_i32 s6, 0, 0x14000
	ds_read_b128 v[144:147], v162
	ds_read_b128 v[148:151], v162 offset:1024
	ds_read_b128 v[172:175], v162 offset:2048
	ds_read_b128 v[190:193], v162 offset:3072
	v_add_u32_e32 v162, s6, v141
	ds_read_b128 v[194:197], v162
	ds_read_b128 v[198:201], v162 offset:1024
	ds_read_b128 v[202:205], v162 offset:2048
	ds_read_b128 v[206:209], v162 offset:3072
	s_add_i32 m0, s27, 0xc000
	ds_read_b128 v[210:213], v143
	ds_read_b128 v[214:217], v143 offset:1024
	ds_read_b128 v[218:221], v143 offset:2048
	ds_read_b128 v[222:225], v143 offset:3072
	ds_read_b128 v[226:229], v143 offset:4096
	ds_read_b128 v[230:233], v143 offset:5120
	ds_read_b128 v[234:237], v143 offset:6144
	ds_read_b128 v[238:241], v143 offset:7168
	global_load_lds_dwordx4 v136, s[22:23]
	s_add_i32 m0, s27, 0xe000
	s_nop 0
	global_load_lds_dwordx4 v138, s[22:23]
	s_waitcnt vmcnt(8)
	s_waitcnt lgkmcnt(0)
	s_barrier
	s_waitcnt lgkmcnt(0)
	v_mfma_f32_16x16x32_bf16 v[126:129], v[144:147], v[210:213], v[126:129]
	v_mfma_f32_16x16x32_bf16 v[122:125], v[172:175], v[210:213], v[122:125]
	v_mfma_f32_16x16x32_bf16 v[118:121], v[144:147], v[218:221], v[118:121]
	v_mfma_f32_16x16x32_bf16 v[114:117], v[172:175], v[218:221], v[114:117]
	v_mfma_f32_16x16x32_bf16 v[110:113], v[144:147], v[226:229], v[110:113]
	v_mfma_f32_16x16x32_bf16 v[106:109], v[172:175], v[226:229], v[106:109]
	v_mfma_f32_16x16x32_bf16 v[102:105], v[144:147], v[234:237], v[102:105]
	v_mfma_f32_16x16x32_bf16 v[98:101], v[172:175], v[234:237], v[98:101]
	v_mfma_f32_16x16x32_bf16 v[126:129], v[148:151], v[214:217], v[126:129]
	v_mfma_f32_16x16x32_bf16 v[122:125], v[190:193], v[214:217], v[122:125]
	v_mfma_f32_16x16x32_bf16 v[118:121], v[148:151], v[222:225], v[118:121]
	v_mfma_f32_16x16x32_bf16 v[114:117], v[190:193], v[222:225], v[114:117]
	v_mfma_f32_16x16x32_bf16 v[110:113], v[148:151], v[230:233], v[110:113]
	v_mfma_f32_16x16x32_bf16 v[106:109], v[190:193], v[230:233], v[106:109]
	v_mfma_f32_16x16x32_bf16 v[102:105], v[148:151], v[238:241], v[102:105]
	v_mfma_f32_16x16x32_bf16 v[98:101], v[190:193], v[238:241], v[98:101]
	v_mfma_f32_16x16x32_bf16 v[66:69], v[194:197], v[210:213], v[66:69]
	v_mfma_f32_16x16x32_bf16 v[58:61], v[202:205], v[210:213], v[58:61]
	v_mfma_f32_16x16x32_bf16 v[54:57], v[194:197], v[218:221], v[54:57]
	v_mfma_f32_16x16x32_bf16 v[50:53], v[202:205], v[218:221], v[50:53]
	v_mfma_f32_16x16x32_bf16 v[46:49], v[194:197], v[226:229], v[46:49]
	v_mfma_f32_16x16x32_bf16 v[42:45], v[202:205], v[226:229], v[42:45]
	v_mfma_f32_16x16x32_bf16 v[38:41], v[194:197], v[234:237], v[38:41]
	v_mfma_f32_16x16x32_bf16 v[34:37], v[202:205], v[234:237], v[34:37]
	v_mfma_f32_16x16x32_bf16 v[66:69], v[198:201], v[214:217], v[66:69]
	v_mfma_f32_16x16x32_bf16 v[58:61], v[206:209], v[214:217], v[58:61]
	v_mfma_f32_16x16x32_bf16 v[54:57], v[198:201], v[222:225], v[54:57]
	v_mfma_f32_16x16x32_bf16 v[50:53], v[206:209], v[222:225], v[50:53]
	v_mfma_f32_16x16x32_bf16 v[46:49], v[198:201], v[230:233], v[46:49]
	v_mfma_f32_16x16x32_bf16 v[42:45], v[206:209], v[230:233], v[42:45]
	v_mfma_f32_16x16x32_bf16 v[38:41], v[198:201], v[238:241], v[38:41]
	v_mfma_f32_16x16x32_bf16 v[34:37], v[206:209], v[238:241], v[34:37]
	s_barrier
	s_add_i32 s3, s3, s26
	v_lshl_add_u64 v[162:163], s[0:1], 0, v[4:5]
	s_mov_b32 m0, s3
	ds_read_b128 v[210:213], v143 offset:16384
	ds_read_b128 v[214:217], v143 offset:17408
	ds_read_b128 v[218:221], v143 offset:18432
	ds_read_b128 v[222:225], v143 offset:19456
	ds_read_b128 v[226:229], v143 offset:20480
	ds_read_b128 v[230:233], v143 offset:21504
	ds_read_b128 v[234:237], v143 offset:22528
	ds_read_b128 v[238:241], v143 offset:23552
	global_load_lds_dwordx4 v4, s[0:1]
	s_add_i32 m0, s3, 0x2000
	s_add_u32 s4, s0, 0x80000
	v_lshl_add_u64 v[166:167], s[0:1], 0, v[130:131]
	s_addc_u32 s5, s1, 0
	s_add_i32 s3, s6, s26
	global_load_lds_dwordx4 v130, s[0:1]
	s_mov_b32 m0, s3
	v_lshl_add_u64 v[242:243], s[14:15], 0, v[132:133]
	global_load_lds_dwordx4 v4, s[4:5]
	s_add_i32 m0, s3, 0x2000
	s_nop 0
	global_load_lds_dwordx4 v130, s[4:5]
	v_lshl_add_u64 v[176:177], s[14:15], 0, v[134:135]
	s_mov_b32 m0, s27
	s_nop 0
	global_load_lds_dwordx4 v134, s[14:15]
	s_mov_b32 m0, s30
	s_nop 0
	global_load_lds_dwordx4 v132, s[14:15]
	s_waitcnt vmcnt(8)
	s_waitcnt lgkmcnt(0)
	s_barrier
	s_waitcnt lgkmcnt(0)
	v_mfma_f32_16x16x32_bf16 v[94:97], v[144:147], v[210:213], v[94:97]
	v_mfma_f32_16x16x32_bf16 v[90:93], v[172:175], v[210:213], v[90:93]
	v_mfma_f32_16x16x32_bf16 v[86:89], v[144:147], v[218:221], v[86:89]
	v_mfma_f32_16x16x32_bf16 v[82:85], v[172:175], v[218:221], v[82:85]
	v_mfma_f32_16x16x32_bf16 v[78:81], v[144:147], v[226:229], v[78:81]
	v_mfma_f32_16x16x32_bf16 v[74:77], v[172:175], v[226:229], v[74:77]
	v_mfma_f32_16x16x32_bf16 v[70:73], v[144:147], v[234:237], v[70:73]
	v_mfma_f32_16x16x32_bf16 v[62:65], v[172:175], v[234:237], v[62:65]
	v_mfma_f32_16x16x32_bf16 v[94:97], v[148:151], v[214:217], v[94:97]
	v_mfma_f32_16x16x32_bf16 v[90:93], v[190:193], v[214:217], v[90:93]
	v_mfma_f32_16x16x32_bf16 v[86:89], v[148:151], v[222:225], v[86:89]
	v_mfma_f32_16x16x32_bf16 v[82:85], v[190:193], v[222:225], v[82:85]
	v_mfma_f32_16x16x32_bf16 v[78:81], v[148:151], v[230:233], v[78:81]
	v_mfma_f32_16x16x32_bf16 v[74:77], v[190:193], v[230:233], v[74:77]
	v_mfma_f32_16x16x32_bf16 v[70:73], v[148:151], v[238:241], v[70:73]
	v_mfma_f32_16x16x32_bf16 v[62:65], v[190:193], v[238:241], v[62:65]
	v_mfma_f32_16x16x32_bf16 v[30:33], v[194:197], v[210:213], v[30:33]
	v_mfma_f32_16x16x32_bf16 v[26:29], v[202:205], v[210:213], v[26:29]
	v_mfma_f32_16x16x32_bf16 v[22:25], v[194:197], v[218:221], v[22:25]
	v_mfma_f32_16x16x32_bf16 v[18:21], v[202:205], v[218:221], v[18:21]
	v_mfma_f32_16x16x32_bf16 v[14:17], v[194:197], v[226:229], v[14:17]
	v_mfma_f32_16x16x32_bf16 v[10:13], v[202:205], v[226:229], v[10:13]
	v_mfma_f32_16x16x32_bf16 v[6:9], v[194:197], v[234:237], v[6:9]
	v_mfma_f32_16x16x32_bf16 v[0:3], v[202:205], v[234:237], v[0:3]
	v_mfma_f32_16x16x32_bf16 v[30:33], v[198:201], v[214:217], v[30:33]
	v_mfma_f32_16x16x32_bf16 v[26:29], v[206:209], v[214:217], v[26:29]
	v_mfma_f32_16x16x32_bf16 v[22:25], v[198:201], v[222:225], v[22:25]
	v_mfma_f32_16x16x32_bf16 v[18:21], v[206:209], v[222:225], v[18:21]
	v_mfma_f32_16x16x32_bf16 v[14:17], v[198:201], v[230:233], v[14:17]
	v_mfma_f32_16x16x32_bf16 v[10:13], v[206:209], v[230:233], v[10:13]
	v_mfma_f32_16x16x32_bf16 v[6:9], v[198:201], v[238:241], v[6:9]
	v_mfma_f32_16x16x32_bf16 v[0:3], v[206:209], v[238:241], v[0:3]
	s_barrier
.Lpeelmid_252:
	s_add_i32 s3, 0, 0x18000
	v_add_u32_e32 v164, s3, v141
	s_add_i32 s6, 0, 0x1c000
	ds_read_b128 v[144:147], v164
	ds_read_b128 v[148:151], v164 offset:1024
	ds_read_b128 v[172:175], v164 offset:2048
	ds_read_b128 v[190:193], v164 offset:3072
	v_add_u32_e32 v164, s6, v141
	ds_read_b128 v[194:197], v164
	ds_read_b128 v[198:201], v164 offset:1024
	ds_read_b128 v[202:205], v164 offset:2048
	ds_read_b128 v[206:209], v164 offset:3072
	s_add_u32 s4, s14, 0x80000
	s_addc_u32 s5, s15, 0
	s_mov_b32 m0, s31
	ds_read_b128 v[210:213], v143 offset:32768
	ds_read_b128 v[214:217], v143 offset:33792
	ds_read_b128 v[218:221], v143 offset:34816
	ds_read_b128 v[222:225], v143 offset:35840
	ds_read_b128 v[226:229], v143 offset:36864
	ds_read_b128 v[230:233], v143 offset:37888
	ds_read_b128 v[234:237], v143 offset:38912
	ds_read_b128 v[238:241], v143 offset:39936
	global_load_lds_dwordx4 v134, s[4:5]
	v_lshl_add_u64 v[244:245], s[4:5], 0, v[132:133]
	s_mov_b32 m0, s34
	s_nop 0
	global_load_lds_dwordx4 v132, s[4:5]
	s_waitcnt vmcnt(8)
	s_waitcnt lgkmcnt(0)
	s_barrier
	s_waitcnt lgkmcnt(0)
	v_mfma_f32_16x16x32_bf16 v[126:129], v[144:147], v[210:213], v[126:129]
	v_mfma_f32_16x16x32_bf16 v[122:125], v[172:175], v[210:213], v[122:125]
	v_mfma_f32_16x16x32_bf16 v[118:121], v[144:147], v[218:221], v[118:121]
	v_mfma_f32_16x16x32_bf16 v[114:117], v[172:175], v[218:221], v[114:117]
	v_mfma_f32_16x16x32_bf16 v[110:113], v[144:147], v[226:229], v[110:113]
	v_mfma_f32_16x16x32_bf16 v[106:109], v[172:175], v[226:229], v[106:109]
	v_mfma_f32_16x16x32_bf16 v[102:105], v[144:147], v[234:237], v[102:105]
	v_mfma_f32_16x16x32_bf16 v[98:101], v[172:175], v[234:237], v[98:101]
	v_mfma_f32_16x16x32_bf16 v[126:129], v[148:151], v[214:217], v[126:129]
	v_mfma_f32_16x16x32_bf16 v[122:125], v[190:193], v[214:217], v[122:125]
	v_mfma_f32_16x16x32_bf16 v[118:121], v[148:151], v[222:225], v[118:121]
	v_mfma_f32_16x16x32_bf16 v[114:117], v[190:193], v[222:225], v[114:117]
	v_mfma_f32_16x16x32_bf16 v[110:113], v[148:151], v[230:233], v[110:113]
	v_mfma_f32_16x16x32_bf16 v[106:109], v[190:193], v[230:233], v[106:109]
	v_mfma_f32_16x16x32_bf16 v[102:105], v[148:151], v[238:241], v[102:105]
	v_mfma_f32_16x16x32_bf16 v[98:101], v[190:193], v[238:241], v[98:101]
	v_mfma_f32_16x16x32_bf16 v[66:69], v[194:197], v[210:213], v[66:69]
	v_mfma_f32_16x16x32_bf16 v[58:61], v[202:205], v[210:213], v[58:61]
	v_mfma_f32_16x16x32_bf16 v[54:57], v[194:197], v[218:221], v[54:57]
	v_mfma_f32_16x16x32_bf16 v[50:53], v[202:205], v[218:221], v[50:53]
	v_mfma_f32_16x16x32_bf16 v[46:49], v[194:197], v[226:229], v[46:49]
	v_mfma_f32_16x16x32_bf16 v[42:45], v[202:205], v[226:229], v[42:45]
	v_mfma_f32_16x16x32_bf16 v[38:41], v[194:197], v[234:237], v[38:41]
	v_mfma_f32_16x16x32_bf16 v[34:37], v[202:205], v[234:237], v[34:37]
	v_mfma_f32_16x16x32_bf16 v[66:69], v[198:201], v[214:217], v[66:69]
	v_mfma_f32_16x16x32_bf16 v[58:61], v[206:209], v[214:217], v[58:61]
	v_mfma_f32_16x16x32_bf16 v[54:57], v[198:201], v[222:225], v[54:57]
	v_mfma_f32_16x16x32_bf16 v[50:53], v[206:209], v[222:225], v[50:53]
	v_mfma_f32_16x16x32_bf16 v[46:49], v[198:201], v[230:233], v[46:49]
	v_mfma_f32_16x16x32_bf16 v[42:45], v[206:209], v[230:233], v[42:45]
	v_mfma_f32_16x16x32_bf16 v[38:41], v[198:201], v[238:241], v[38:41]
	v_mfma_f32_16x16x32_bf16 v[34:37], v[206:209], v[238:241], v[34:37]
	s_barrier
	s_add_i32 s3, s3, s26
	v_lshl_add_u64 v[162:163], v[162:163], 0, s[70:71]
	s_mov_b32 m0, s3
	ds_read_b128 v[210:213], v143 offset:49152
	ds_read_b128 v[214:217], v143 offset:50176
	ds_read_b128 v[218:221], v143 offset:51200
	ds_read_b128 v[222:225], v143 offset:52224
	ds_read_b128 v[226:229], v143 offset:53248
	ds_read_b128 v[230:233], v143 offset:54272
	ds_read_b128 v[234:237], v143 offset:55296
	ds_read_b128 v[238:241], v143 offset:56320
	global_load_lds_dwordx4 v[162:163], off
	s_add_i32 m0, s3, 0x2000
	s_add_u32 s0, s0, 0x80080
	v_lshl_add_u64 v[162:163], v[166:167], 0, s[70:71]
	s_addc_u32 s1, s1, 0
	s_add_i32 s3, s6, s26
	global_load_lds_dwordx4 v[162:163], off
	s_mov_b32 m0, s3
	s_nop 0
	global_load_lds_dwordx4 v4, s[0:1]
	s_add_i32 m0, s3, 0x2000
	s_nop 0
	global_load_lds_dwordx4 v130, s[0:1]
	v_lshl_add_u64 v[162:163], v[176:177], 0, s[70:71]
	s_mov_b32 m0, s35
	s_nop 0
	global_load_lds_dwordx4 v[162:163], off
	v_lshl_add_u64 v[162:163], v[242:243], 0, s[70:71]
	s_mov_b32 m0, s36
	s_nop 0
	global_load_lds_dwordx4 v[162:163], off
	s_waitcnt vmcnt(8)
	s_waitcnt lgkmcnt(0)
	s_barrier
	s_waitcnt lgkmcnt(0)
	v_mfma_f32_16x16x32_bf16 v[94:97], v[144:147], v[210:213], v[94:97]
	v_mfma_f32_16x16x32_bf16 v[90:93], v[172:175], v[210:213], v[90:93]
	v_mfma_f32_16x16x32_bf16 v[86:89], v[144:147], v[218:221], v[86:89]
	v_mfma_f32_16x16x32_bf16 v[82:85], v[172:175], v[218:221], v[82:85]
	v_mfma_f32_16x16x32_bf16 v[78:81], v[144:147], v[226:229], v[78:81]
	v_mfma_f32_16x16x32_bf16 v[74:77], v[172:175], v[226:229], v[74:77]
	v_mfma_f32_16x16x32_bf16 v[70:73], v[144:147], v[234:237], v[70:73]
	v_mfma_f32_16x16x32_bf16 v[62:65], v[172:175], v[234:237], v[62:65]
	v_mfma_f32_16x16x32_bf16 v[94:97], v[148:151], v[214:217], v[94:97]
	v_mfma_f32_16x16x32_bf16 v[90:93], v[190:193], v[214:217], v[90:93]
	v_mfma_f32_16x16x32_bf16 v[86:89], v[148:151], v[222:225], v[86:89]
	v_mfma_f32_16x16x32_bf16 v[82:85], v[190:193], v[222:225], v[82:85]
	v_mfma_f32_16x16x32_bf16 v[78:81], v[148:151], v[230:233], v[78:81]
	v_mfma_f32_16x16x32_bf16 v[74:77], v[190:193], v[230:233], v[74:77]
	v_mfma_f32_16x16x32_bf16 v[70:73], v[148:151], v[238:241], v[70:73]
	v_mfma_f32_16x16x32_bf16 v[62:65], v[190:193], v[238:241], v[62:65]
	v_mfma_f32_16x16x32_bf16 v[30:33], v[194:197], v[210:213], v[30:33]
	v_mfma_f32_16x16x32_bf16 v[26:29], v[202:205], v[210:213], v[26:29]
	v_mfma_f32_16x16x32_bf16 v[22:25], v[194:197], v[218:221], v[22:25]
	v_mfma_f32_16x16x32_bf16 v[18:21], v[202:205], v[218:221], v[18:21]
	v_mfma_f32_16x16x32_bf16 v[14:17], v[194:197], v[226:229], v[14:17]
	v_mfma_f32_16x16x32_bf16 v[10:13], v[202:205], v[226:229], v[10:13]
	v_mfma_f32_16x16x32_bf16 v[6:9], v[194:197], v[234:237], v[6:9]
	v_mfma_f32_16x16x32_bf16 v[0:3], v[202:205], v[234:237], v[0:3]
	v_mfma_f32_16x16x32_bf16 v[30:33], v[198:201], v[214:217], v[30:33]
	v_mfma_f32_16x16x32_bf16 v[26:29], v[206:209], v[214:217], v[26:29]
	v_mfma_f32_16x16x32_bf16 v[22:25], v[198:201], v[222:225], v[22:25]
	v_mfma_f32_16x16x32_bf16 v[18:21], v[206:209], v[222:225], v[18:21]
	v_mfma_f32_16x16x32_bf16 v[14:17], v[198:201], v[230:233], v[14:17]
	v_mfma_f32_16x16x32_bf16 v[10:13], v[206:209], v[230:233], v[10:13]
	v_mfma_f32_16x16x32_bf16 v[6:9], v[198:201], v[238:241], v[6:9]
	v_mfma_f32_16x16x32_bf16 v[0:3], v[206:209], v[238:241], v[0:3]
	s_barrier
	s_add_i32 s24, s24, 2
	s_add_u32 s22, s22, 0x100
	s_addc_u32 s23, s23, 0
	s_add_u32 s9, s9, 0x100
	s_addc_u32 s10, s10, 0
	s_cmp_gt_u32 s24, 29
	s_cbranch_scc0 .LBB0_252
	s_and_b64 vcc, exec, s[44:45]
	s_cbranch_vccz .LBB0_255
	s_barrier

.LBB0_851:
	s_ashr_i32 s3, s37, 24
	s_lshl_b32 s2, s37, 8
	s_andn2_b32 s3, s3, 63
	s_add_i32 s2, s3, s2
	s_ashr_i32 s3, s2, 31
	s_lshl_b64 s[2:3], s[2:3], 12
	v_readlane_b32 s4, v252, 6
	v_readlane_b32 s5, v252, 7
	s_add_u32 s76, s4, s2
	s_addc_u32 s77, s5, s3
	s_and_b64 s[2:3], s[38:39], exec
	s_cselect_b32 s2, s77, s15
	s_cselect_b32 s8, s76, s14
	s_ashr_i32 s59, s58, 31
	s_lshl_b64 s[4:5], s[58:59], 20
	v_readlane_b32 s6, v252, 4
	v_readlane_b32 s7, v252, 5
	s_add_u32 s78, s6, s4
	s_addc_u32 s79, s7, s5
	s_and_b64 s[4:5], s[38:39], exec
	s_cselect_b32 s10, s79, s1
	s_cselect_b32 s24, s78, s0
	s_add_u32 s22, s14, 0x80080
	s_addc_u32 s23, s15, 0
	s_add_u32 s9, s0, 0x100
	v_mov_b32_e32 v0, 0
	s_addc_u32 s25, s1, 0
	s_mov_b32 s28, -2
	v_mov_b32_e32 v1, v0
	v_mov_b32_e32 v2, v0
	v_mov_b32_e32 v3, v0
	v_mov_b32_e32 v6, v0
	v_mov_b32_e32 v7, v0
	v_mov_b32_e32 v8, v0
	v_mov_b32_e32 v9, v0
	v_mov_b32_e32 v10, v0
	v_mov_b32_e32 v11, v0
	v_mov_b32_e32 v12, v0
	v_mov_b32_e32 v13, v0
	v_mov_b32_e32 v14, v0
	v_mov_b32_e32 v15, v0
	v_mov_b32_e32 v16, v0
	v_mov_b32_e32 v17, v0
	v_mov_b32_e32 v18, v0
	v_mov_b32_e32 v19, v0
	v_mov_b32_e32 v20, v0
	v_mov_b32_e32 v21, v0
	v_mov_b32_e32 v22, v0
	v_mov_b32_e32 v23, v0
	v_mov_b32_e32 v24, v0
	v_mov_b32_e32 v25, v0
	v_mov_b32_e32 v26, v0
	v_mov_b32_e32 v27, v0
	v_mov_b32_e32 v28, v0
	v_mov_b32_e32 v29, v0
	v_mov_b32_e32 v30, v0
	v_mov_b32_e32 v31, v0
	v_mov_b32_e32 v32, v0
	v_mov_b32_e32 v33, v0
	v_mov_b32_e32 v66, v0
	v_mov_b32_e32 v67, v0
	v_mov_b32_e32 v68, v0
	v_mov_b32_e32 v69, v0
	v_mov_b32_e32 v70, v0
	v_mov_b32_e32 v71, v0
	v_mov_b32_e32 v72, v0
	v_mov_b32_e32 v73, v0
	v_mov_b32_e32 v74, v0
	v_mov_b32_e32 v75, v0
	v_mov_b32_e32 v76, v0
	v_mov_b32_e32 v77, v0
	v_mov_b32_e32 v78, v0
	v_mov_b32_e32 v79, v0
	v_mov_b32_e32 v80, v0
	v_mov_b32_e32 v81, v0
	v_mov_b32_e32 v82, v0
	v_mov_b32_e32 v83, v0
	v_mov_b32_e32 v84, v0
	v_mov_b32_e32 v85, v0
	v_mov_b32_e32 v86, v0
	v_mov_b32_e32 v87, v0
	v_mov_b32_e32 v88, v0
	v_mov_b32_e32 v89, v0
	v_mov_b32_e32 v90, v0
	v_mov_b32_e32 v91, v0
	v_mov_b32_e32 v92, v0
	v_mov_b32_e32 v93, v0
	v_mov_b32_e32 v94, v0
	v_mov_b32_e32 v95, v0
	v_mov_b32_e32 v96, v0
	v_mov_b32_e32 v97, v0
	v_mov_b32_e32 v34, v0
	v_mov_b32_e32 v35, v0
	v_mov_b32_e32 v36, v0
	v_mov_b32_e32 v37, v0
	v_mov_b32_e32 v38, v0
	v_mov_b32_e32 v39, v0
	v_mov_b32_e32 v40, v0
	v_mov_b32_e32 v41, v0
	v_mov_b32_e32 v42, v0
	v_mov_b32_e32 v43, v0
	v_mov_b32_e32 v44, v0
	v_mov_b32_e32 v45, v0
	v_mov_b32_e32 v46, v0
	v_mov_b32_e32 v47, v0
	v_mov_b32_e32 v48, v0
	v_mov_b32_e32 v49, v0
	v_mov_b32_e32 v50, v0
	v_mov_b32_e32 v51, v0
	v_mov_b32_e32 v52, v0
	v_mov_b32_e32 v53, v0
	v_mov_b32_e32 v54, v0
	v_mov_b32_e32 v55, v0
	v_mov_b32_e32 v56, v0
	v_mov_b32_e32 v57, v0
	v_mov_b32_e32 v58, v0
	v_mov_b32_e32 v59, v0
	v_mov_b32_e32 v60, v0
	v_mov_b32_e32 v61, v0
	v_mov_b32_e32 v62, v0
	v_mov_b32_e32 v63, v0
	v_mov_b32_e32 v64, v0
	v_mov_b32_e32 v65, v0
	v_mov_b32_e32 v98, v0
	v_mov_b32_e32 v99, v0
	v_mov_b32_e32 v100, v0
	v_mov_b32_e32 v101, v0
	v_mov_b32_e32 v102, v0
	v_mov_b32_e32 v103, v0
	v_mov_b32_e32 v104, v0
	v_mov_b32_e32 v105, v0
	v_mov_b32_e32 v106, v0
	v_mov_b32_e32 v107, v0
	v_mov_b32_e32 v108, v0
	v_mov_b32_e32 v109, v0
	v_mov_b32_e32 v110, v0
	v_mov_b32_e32 v111, v0
	v_mov_b32_e32 v112, v0
	v_mov_b32_e32 v113, v0
	v_mov_b32_e32 v114, v0
	v_mov_b32_e32 v115, v0
	v_mov_b32_e32 v116, v0
	v_mov_b32_e32 v117, v0
	v_mov_b32_e32 v118, v0
	v_mov_b32_e32 v119, v0
	v_mov_b32_e32 v120, v0
	v_mov_b32_e32 v121, v0
	v_mov_b32_e32 v122, v0
	v_mov_b32_e32 v123, v0
	v_mov_b32_e32 v124, v0
	v_mov_b32_e32 v125, v0
	v_mov_b32_e32 v126, v0
	v_mov_b32_e32 v127, v0
	v_mov_b32_e32 v128, v0
	v_mov_b32_e32 v129, v0
	s_cmp_eq_u32 s36, 1
	s_cbranch_scc1 .LBB0_852
	s_add_u32 s0, s22, 0xfff80080
	s_addc_u32 s1, s23, -1
	s_add_i32 s3, 0, 0x10000
	s_cmp_eq_u32 s28, 28
	s_cselect_b32 s15, s2, s1
	s_cselect_b32 s14, s8, s0
	v_add_u32_e32 v167, s3, v163
	s_cselect_b32 s1, s10, s25
	s_cselect_b32 s0, s24, s9
	s_add_i32 s6, 0, 0x14000
	ds_read_b128 v[140:143], v167
	ds_read_b128 v[144:147], v167 offset:1024
	ds_read_b128 v[148:151], v167 offset:2048
	ds_read_b128 v[172:175], v167 offset:3072
	v_add_u32_e32 v167, s6, v163
	ds_read_b128 v[190:193], v167
	ds_read_b128 v[194:197], v167 offset:1024
	ds_read_b128 v[198:201], v167 offset:2048
	ds_read_b128 v[202:205], v167 offset:3072
	s_add_i32 m0, s26, 0xc000
	ds_read_b128 v[206:209], v166
	ds_read_b128 v[210:213], v166 offset:1024
	ds_read_b128 v[214:217], v166 offset:2048
	ds_read_b128 v[218:221], v166 offset:3072
	ds_read_b128 v[222:225], v166 offset:4096
	ds_read_b128 v[226:229], v166 offset:5120
	ds_read_b128 v[230:233], v166 offset:6144
	ds_read_b128 v[234:237], v166 offset:7168
	global_load_lds_dwordx4 v136, s[22:23]
	s_add_i32 m0, s26, 0xe000
	s_nop 0
	global_load_lds_dwordx4 v138, s[22:23]
	s_waitcnt vmcnt(24)
	s_waitcnt lgkmcnt(0)
	s_barrier
	s_waitcnt lgkmcnt(0)
	v_mfma_f32_16x16x32_bf16 v[126:129], v[140:143], v[206:209], v[126:129]
	v_mfma_f32_16x16x32_bf16 v[122:125], v[148:151], v[206:209], v[122:125]
	v_mfma_f32_16x16x32_bf16 v[118:121], v[140:143], v[214:217], v[118:121]
	v_mfma_f32_16x16x32_bf16 v[114:117], v[148:151], v[214:217], v[114:117]
	v_mfma_f32_16x16x32_bf16 v[110:113], v[140:143], v[222:225], v[110:113]
	v_mfma_f32_16x16x32_bf16 v[106:109], v[148:151], v[222:225], v[106:109]
	v_mfma_f32_16x16x32_bf16 v[102:105], v[140:143], v[230:233], v[102:105]
	v_mfma_f32_16x16x32_bf16 v[98:101], v[148:151], v[230:233], v[98:101]
	v_mfma_f32_16x16x32_bf16 v[126:129], v[144:147], v[210:213], v[126:129]
	v_mfma_f32_16x16x32_bf16 v[122:125], v[172:175], v[210:213], v[122:125]
	v_mfma_f32_16x16x32_bf16 v[118:121], v[144:147], v[218:221], v[118:121]
	v_mfma_f32_16x16x32_bf16 v[114:117], v[172:175], v[218:221], v[114:117]
	v_mfma_f32_16x16x32_bf16 v[110:113], v[144:147], v[226:229], v[110:113]
	v_mfma_f32_16x16x32_bf16 v[106:109], v[172:175], v[226:229], v[106:109]
	v_mfma_f32_16x16x32_bf16 v[102:105], v[144:147], v[234:237], v[102:105]
	v_mfma_f32_16x16x32_bf16 v[98:101], v[172:175], v[234:237], v[98:101]
	v_mfma_f32_16x16x32_bf16 v[62:65], v[190:193], v[206:209], v[62:65]
	v_mfma_f32_16x16x32_bf16 v[58:61], v[198:201], v[206:209], v[58:61]
	v_mfma_f32_16x16x32_bf16 v[54:57], v[190:193], v[214:217], v[54:57]
	v_mfma_f32_16x16x32_bf16 v[50:53], v[198:201], v[214:217], v[50:53]
	v_mfma_f32_16x16x32_bf16 v[46:49], v[190:193], v[222:225], v[46:49]
	v_mfma_f32_16x16x32_bf16 v[42:45], v[198:201], v[222:225], v[42:45]
	v_mfma_f32_16x16x32_bf16 v[38:41], v[190:193], v[230:233], v[38:41]
	v_mfma_f32_16x16x32_bf16 v[34:37], v[198:201], v[230:233], v[34:37]
	v_mfma_f32_16x16x32_bf16 v[62:65], v[194:197], v[210:213], v[62:65]
	v_mfma_f32_16x16x32_bf16 v[58:61], v[202:205], v[210:213], v[58:61]
	v_mfma_f32_16x16x32_bf16 v[54:57], v[194:197], v[218:221], v[54:57]
	v_mfma_f32_16x16x32_bf16 v[50:53], v[202:205], v[218:221], v[50:53]
	v_mfma_f32_16x16x32_bf16 v[46:49], v[194:197], v[226:229], v[46:49]
	v_mfma_f32_16x16x32_bf16 v[42:45], v[202:205], v[226:229], v[42:45]
	v_mfma_f32_16x16x32_bf16 v[38:41], v[194:197], v[234:237], v[38:41]
	v_mfma_f32_16x16x32_bf16 v[34:37], v[202:205], v[234:237], v[34:37]
	s_barrier
	s_add_i32 s3, s3, s11
	v_lshl_add_u64 v[176:177], s[0:1], 0, v[4:5]
	s_mov_b32 m0, s3
	ds_read_b128 v[206:209], v166 offset:16384
	ds_read_b128 v[210:213], v166 offset:17408
	ds_read_b128 v[214:217], v166 offset:18432
	ds_read_b128 v[218:221], v166 offset:19456
	ds_read_b128 v[222:225], v166 offset:20480
	ds_read_b128 v[226:229], v166 offset:21504
	ds_read_b128 v[230:233], v166 offset:22528
	ds_read_b128 v[234:237], v166 offset:23552
	global_load_lds_dwordx4 v4, s[0:1]
	s_add_i32 m0, s3, 0x2000
	s_add_u32 s4, s0, 0x80000
	v_lshl_add_u64 v[238:239], s[0:1], 0, v[134:135]
	s_addc_u32 s5, s1, 0
	s_add_i32 s3, s6, s11
	global_load_lds_dwordx4 v134, s[0:1]
	s_mov_b32 m0, s3
	v_lshl_add_u64 v[242:243], s[14:15], 0, v[132:133]
	global_load_lds_dwordx4 v4, s[4:5]
	s_add_i32 m0, s3, 0x2000
	s_nop 0
	global_load_lds_dwordx4 v134, s[4:5]
	v_lshl_add_u64 v[240:241], s[14:15], 0, v[130:131]
	s_mov_b32 m0, s26
	s_nop 0
	global_load_lds_dwordx4 v130, s[14:15]
	s_mov_b32 m0, s27
	s_nop 0
	global_load_lds_dwordx4 v132, s[14:15]
	s_waitcnt vmcnt(24)
	s_waitcnt lgkmcnt(0)
	s_barrier
	s_waitcnt lgkmcnt(0)
	v_mfma_f32_16x16x32_bf16 v[94:97], v[140:143], v[206:209], v[94:97]
	v_mfma_f32_16x16x32_bf16 v[90:93], v[148:151], v[206:209], v[90:93]
	v_mfma_f32_16x16x32_bf16 v[86:89], v[140:143], v[214:217], v[86:89]
	v_mfma_f32_16x16x32_bf16 v[82:85], v[148:151], v[214:217], v[82:85]
	v_mfma_f32_16x16x32_bf16 v[78:81], v[140:143], v[222:225], v[78:81]
	v_mfma_f32_16x16x32_bf16 v[74:77], v[148:151], v[222:225], v[74:77]
	v_mfma_f32_16x16x32_bf16 v[70:73], v[140:143], v[230:233], v[70:73]
	v_mfma_f32_16x16x32_bf16 v[66:69], v[148:151], v[230:233], v[66:69]
	v_mfma_f32_16x16x32_bf16 v[94:97], v[144:147], v[210:213], v[94:97]
	v_mfma_f32_16x16x32_bf16 v[90:93], v[172:175], v[210:213], v[90:93]
	v_mfma_f32_16x16x32_bf16 v[86:89], v[144:147], v[218:221], v[86:89]
	v_mfma_f32_16x16x32_bf16 v[82:85], v[172:175], v[218:221], v[82:85]
	v_mfma_f32_16x16x32_bf16 v[78:81], v[144:147], v[226:229], v[78:81]
	v_mfma_f32_16x16x32_bf16 v[74:77], v[172:175], v[226:229], v[74:77]
	v_mfma_f32_16x16x32_bf16 v[70:73], v[144:147], v[234:237], v[70:73]
	v_mfma_f32_16x16x32_bf16 v[66:69], v[172:175], v[234:237], v[66:69]
	v_mfma_f32_16x16x32_bf16 v[30:33], v[190:193], v[206:209], v[30:33]
	v_mfma_f32_16x16x32_bf16 v[26:29], v[198:201], v[206:209], v[26:29]
	v_mfma_f32_16x16x32_bf16 v[22:25], v[190:193], v[214:217], v[22:25]
	v_mfma_f32_16x16x32_bf16 v[18:21], v[198:201], v[214:217], v[18:21]
	v_mfma_f32_16x16x32_bf16 v[14:17], v[190:193], v[222:225], v[14:17]
	v_mfma_f32_16x16x32_bf16 v[10:13], v[198:201], v[222:225], v[10:13]
	v_mfma_f32_16x16x32_bf16 v[6:9], v[190:193], v[230:233], v[6:9]
	v_mfma_f32_16x16x32_bf16 v[0:3], v[198:201], v[230:233], v[0:3]
	v_mfma_f32_16x16x32_bf16 v[30:33], v[194:197], v[210:213], v[30:33]
	v_mfma_f32_16x16x32_bf16 v[26:29], v[202:205], v[210:213], v[26:29]
	v_mfma_f32_16x16x32_bf16 v[22:25], v[194:197], v[218:221], v[22:25]
	v_mfma_f32_16x16x32_bf16 v[18:21], v[202:205], v[218:221], v[18:21]
	v_mfma_f32_16x16x32_bf16 v[14:17], v[194:197], v[226:229], v[14:17]
	v_mfma_f32_16x16x32_bf16 v[10:13], v[202:205], v[226:229], v[10:13]
	v_mfma_f32_16x16x32_bf16 v[6:9], v[194:197], v[234:237], v[6:9]
	v_mfma_f32_16x16x32_bf16 v[0:3], v[202:205], v[234:237], v[0:3]
	s_barrier
	s_branch .Lpeelmid_852
.LBB0_852:
	s_add_u32 s0, s22, 0xfff80080
	s_addc_u32 s1, s23, -1
	s_add_i32 s3, 0, 0x10000
	s_cmp_eq_u32 s28, 28
	s_cselect_b32 s15, s2, s1
	s_cselect_b32 s14, s8, s0
	v_add_u32_e32 v167, s3, v163
	s_cselect_b32 s1, s10, s25
	s_cselect_b32 s0, s24, s9
	s_add_i32 s6, 0, 0x14000
	ds_read_b128 v[140:143], v167
	ds_read_b128 v[144:147], v167 offset:1024
	ds_read_b128 v[148:151], v167 offset:2048
	ds_read_b128 v[172:175], v167 offset:3072
	v_add_u32_e32 v167, s6, v163
	ds_read_b128 v[190:193], v167
	ds_read_b128 v[194:197], v167 offset:1024
	ds_read_b128 v[198:201], v167 offset:2048
	ds_read_b128 v[202:205], v167 offset:3072
	s_add_i32 m0, s26, 0xc000
	ds_read_b128 v[206:209], v166
	ds_read_b128 v[210:213], v166 offset:1024
	ds_read_b128 v[214:217], v166 offset:2048
	ds_read_b128 v[218:221], v166 offset:3072
	ds_read_b128 v[222:225], v166 offset:4096
	ds_read_b128 v[226:229], v166 offset:5120
	ds_read_b128 v[230:233], v166 offset:6144
	ds_read_b128 v[234:237], v166 offset:7168
	global_load_lds_dwordx4 v136, s[22:23]
	s_add_i32 m0, s26, 0xe000
	s_nop 0
	global_load_lds_dwordx4 v138, s[22:23]
	s_waitcnt vmcnt(8)
	s_waitcnt lgkmcnt(0)
	s_barrier
	s_waitcnt lgkmcnt(0)
	v_mfma_f32_16x16x32_bf16 v[126:129], v[140:143], v[206:209], v[126:129]
	v_mfma_f32_16x16x32_bf16 v[122:125], v[148:151], v[206:209], v[122:125]
	v_mfma_f32_16x16x32_bf16 v[118:121], v[140:143], v[214:217], v[118:121]
	v_mfma_f32_16x16x32_bf16 v[114:117], v[148:151], v[214:217], v[114:117]
	v_mfma_f32_16x16x32_bf16 v[110:113], v[140:143], v[222:225], v[110:113]
	v_mfma_f32_16x16x32_bf16 v[106:109], v[148:151], v[222:225], v[106:109]
	v_mfma_f32_16x16x32_bf16 v[102:105], v[140:143], v[230:233], v[102:105]
	v_mfma_f32_16x16x32_bf16 v[98:101], v[148:151], v[230:233], v[98:101]
	v_mfma_f32_16x16x32_bf16 v[126:129], v[144:147], v[210:213], v[126:129]
	v_mfma_f32_16x16x32_bf16 v[122:125], v[172:175], v[210:213], v[122:125]
	v_mfma_f32_16x16x32_bf16 v[118:121], v[144:147], v[218:221], v[118:121]
	v_mfma_f32_16x16x32_bf16 v[114:117], v[172:175], v[218:221], v[114:117]
	v_mfma_f32_16x16x32_bf16 v[110:113], v[144:147], v[226:229], v[110:113]
	v_mfma_f32_16x16x32_bf16 v[106:109], v[172:175], v[226:229], v[106:109]
	v_mfma_f32_16x16x32_bf16 v[102:105], v[144:147], v[234:237], v[102:105]
	v_mfma_f32_16x16x32_bf16 v[98:101], v[172:175], v[234:237], v[98:101]
	v_mfma_f32_16x16x32_bf16 v[62:65], v[190:193], v[206:209], v[62:65]
	v_mfma_f32_16x16x32_bf16 v[58:61], v[198:201], v[206:209], v[58:61]
	v_mfma_f32_16x16x32_bf16 v[54:57], v[190:193], v[214:217], v[54:57]
	v_mfma_f32_16x16x32_bf16 v[50:53], v[198:201], v[214:217], v[50:53]
	v_mfma_f32_16x16x32_bf16 v[46:49], v[190:193], v[222:225], v[46:49]
	v_mfma_f32_16x16x32_bf16 v[42:45], v[198:201], v[222:225], v[42:45]
	v_mfma_f32_16x16x32_bf16 v[38:41], v[190:193], v[230:233], v[38:41]
	v_mfma_f32_16x16x32_bf16 v[34:37], v[198:201], v[230:233], v[34:37]
	v_mfma_f32_16x16x32_bf16 v[62:65], v[194:197], v[210:213], v[62:65]
	v_mfma_f32_16x16x32_bf16 v[58:61], v[202:205], v[210:213], v[58:61]
	v_mfma_f32_16x16x32_bf16 v[54:57], v[194:197], v[218:221], v[54:57]
	v_mfma_f32_16x16x32_bf16 v[50:53], v[202:205], v[218:221], v[50:53]
	v_mfma_f32_16x16x32_bf16 v[46:49], v[194:197], v[226:229], v[46:49]
	v_mfma_f32_16x16x32_bf16 v[42:45], v[202:205], v[226:229], v[42:45]
	v_mfma_f32_16x16x32_bf16 v[38:41], v[194:197], v[234:237], v[38:41]
	v_mfma_f32_16x16x32_bf16 v[34:37], v[202:205], v[234:237], v[34:37]
	s_barrier
	s_add_i32 s3, s3, s11
	v_lshl_add_u64 v[176:177], s[0:1], 0, v[4:5]
	s_mov_b32 m0, s3
	ds_read_b128 v[206:209], v166 offset:16384
	ds_read_b128 v[210:213], v166 offset:17408
	ds_read_b128 v[214:217], v166 offset:18432
	ds_read_b128 v[218:221], v166 offset:19456
	ds_read_b128 v[222:225], v166 offset:20480
	ds_read_b128 v[226:229], v166 offset:21504
	ds_read_b128 v[230:233], v166 offset:22528
	ds_read_b128 v[234:237], v166 offset:23552
	global_load_lds_dwordx4 v4, s[0:1]
	s_add_i32 m0, s3, 0x2000
	s_add_u32 s4, s0, 0x80000
	v_lshl_add_u64 v[238:239], s[0:1], 0, v[134:135]
	s_addc_u32 s5, s1, 0
	s_add_i32 s3, s6, s11
	global_load_lds_dwordx4 v134, s[0:1]
	s_mov_b32 m0, s3
	v_lshl_add_u64 v[242:243], s[14:15], 0, v[132:133]
	global_load_lds_dwordx4 v4, s[4:5]
	s_add_i32 m0, s3, 0x2000
	s_nop 0
	global_load_lds_dwordx4 v134, s[4:5]
	v_lshl_add_u64 v[240:241], s[14:15], 0, v[130:131]
	s_mov_b32 m0, s26
	s_nop 0
	global_load_lds_dwordx4 v130, s[14:15]
	s_mov_b32 m0, s27
	s_nop 0
	global_load_lds_dwordx4 v132, s[14:15]
	s_waitcnt vmcnt(8)
	s_waitcnt lgkmcnt(0)
	s_barrier
	s_waitcnt lgkmcnt(0)
	v_mfma_f32_16x16x32_bf16 v[94:97], v[140:143], v[206:209], v[94:97]
	v_mfma_f32_16x16x32_bf16 v[90:93], v[148:151], v[206:209], v[90:93]
	v_mfma_f32_16x16x32_bf16 v[86:89], v[140:143], v[214:217], v[86:89]
	v_mfma_f32_16x16x32_bf16 v[82:85], v[148:151], v[214:217], v[82:85]
	v_mfma_f32_16x16x32_bf16 v[78:81], v[140:143], v[222:225], v[78:81]
	v_mfma_f32_16x16x32_bf16 v[74:77], v[148:151], v[222:225], v[74:77]
	v_mfma_f32_16x16x32_bf16 v[70:73], v[140:143], v[230:233], v[70:73]
	v_mfma_f32_16x16x32_bf16 v[66:69], v[148:151], v[230:233], v[66:69]
	v_mfma_f32_16x16x32_bf16 v[94:97], v[144:147], v[210:213], v[94:97]
	v_mfma_f32_16x16x32_bf16 v[90:93], v[172:175], v[210:213], v[90:93]
	v_mfma_f32_16x16x32_bf16 v[86:89], v[144:147], v[218:221], v[86:89]
	v_mfma_f32_16x16x32_bf16 v[82:85], v[172:175], v[218:221], v[82:85]
	v_mfma_f32_16x16x32_bf16 v[78:81], v[144:147], v[226:229], v[78:81]
	v_mfma_f32_16x16x32_bf16 v[74:77], v[172:175], v[226:229], v[74:77]
	v_mfma_f32_16x16x32_bf16 v[70:73], v[144:147], v[234:237], v[70:73]
	v_mfma_f32_16x16x32_bf16 v[66:69], v[172:175], v[234:237], v[66:69]
	v_mfma_f32_16x16x32_bf16 v[30:33], v[190:193], v[206:209], v[30:33]
	v_mfma_f32_16x16x32_bf16 v[26:29], v[198:201], v[206:209], v[26:29]
	v_mfma_f32_16x16x32_bf16 v[22:25], v[190:193], v[214:217], v[22:25]
	v_mfma_f32_16x16x32_bf16 v[18:21], v[198:201], v[214:217], v[18:21]
	v_mfma_f32_16x16x32_bf16 v[14:17], v[190:193], v[222:225], v[14:17]
	v_mfma_f32_16x16x32_bf16 v[10:13], v[198:201], v[222:225], v[10:13]
	v_mfma_f32_16x16x32_bf16 v[6:9], v[190:193], v[230:233], v[6:9]
	v_mfma_f32_16x16x32_bf16 v[0:3], v[198:201], v[230:233], v[0:3]
	v_mfma_f32_16x16x32_bf16 v[30:33], v[194:197], v[210:213], v[30:33]
	v_mfma_f32_16x16x32_bf16 v[26:29], v[202:205], v[210:213], v[26:29]
	v_mfma_f32_16x16x32_bf16 v[22:25], v[194:197], v[218:221], v[22:25]
	v_mfma_f32_16x16x32_bf16 v[18:21], v[202:205], v[218:221], v[18:21]
	v_mfma_f32_16x16x32_bf16 v[14:17], v[194:197], v[226:229], v[14:17]
	v_mfma_f32_16x16x32_bf16 v[10:13], v[202:205], v[226:229], v[10:13]
	v_mfma_f32_16x16x32_bf16 v[6:9], v[194:197], v[234:237], v[6:9]
	v_mfma_f32_16x16x32_bf16 v[0:3], v[202:205], v[234:237], v[0:3]
	s_barrier
.Lpeelmid_852:
	s_add_i32 s3, 0, 0x18000
	v_add_u32_e32 v167, s3, v163
	s_add_i32 s6, 0, 0x1c000
	ds_read_b128 v[140:143], v167
	ds_read_b128 v[144:147], v167 offset:1024
	ds_read_b128 v[148:151], v167 offset:2048
	ds_read_b128 v[172:175], v167 offset:3072
	v_add_u32_e32 v167, s6, v163
	ds_read_b128 v[190:193], v167
	ds_read_b128 v[194:197], v167 offset:1024
	ds_read_b128 v[198:201], v167 offset:2048
	ds_read_b128 v[202:205], v167 offset:3072
	s_add_u32 s4, s14, 0x80000
	s_addc_u32 s5, s15, 0
	s_mov_b32 m0, s30
	ds_read_b128 v[206:209], v166 offset:32768
	ds_read_b128 v[210:213], v166 offset:33792
	ds_read_b128 v[214:217], v166 offset:34816
	ds_read_b128 v[218:221], v166 offset:35840
	ds_read_b128 v[222:225], v166 offset:36864
	ds_read_b128 v[226:229], v166 offset:37888
	ds_read_b128 v[230:233], v166 offset:38912
	ds_read_b128 v[234:237], v166 offset:39936
	global_load_lds_dwordx4 v130, s[4:5]
	v_lshl_add_u64 v[244:245], s[4:5], 0, v[132:133]
	s_mov_b32 m0, s31
	s_nop 0
	global_load_lds_dwordx4 v132, s[4:5]
	s_waitcnt vmcnt(8)
	s_waitcnt lgkmcnt(0)
	s_barrier
	s_waitcnt lgkmcnt(0)
	v_mfma_f32_16x16x32_bf16 v[126:129], v[140:143], v[206:209], v[126:129]
	v_mfma_f32_16x16x32_bf16 v[122:125], v[148:151], v[206:209], v[122:125]
	v_mfma_f32_16x16x32_bf16 v[118:121], v[140:143], v[214:217], v[118:121]
	v_mfma_f32_16x16x32_bf16 v[114:117], v[148:151], v[214:217], v[114:117]
	v_mfma_f32_16x16x32_bf16 v[110:113], v[140:143], v[222:225], v[110:113]
	v_mfma_f32_16x16x32_bf16 v[106:109], v[148:151], v[222:225], v[106:109]
	v_mfma_f32_16x16x32_bf16 v[102:105], v[140:143], v[230:233], v[102:105]
	v_mfma_f32_16x16x32_bf16 v[98:101], v[148:151], v[230:233], v[98:101]
	v_mfma_f32_16x16x32_bf16 v[126:129], v[144:147], v[210:213], v[126:129]
	v_mfma_f32_16x16x32_bf16 v[122:125], v[172:175], v[210:213], v[122:125]
	v_mfma_f32_16x16x32_bf16 v[118:121], v[144:147], v[218:221], v[118:121]
	v_mfma_f32_16x16x32_bf16 v[114:117], v[172:175], v[218:221], v[114:117]
	v_mfma_f32_16x16x32_bf16 v[110:113], v[144:147], v[226:229], v[110:113]
	v_mfma_f32_16x16x32_bf16 v[106:109], v[172:175], v[226:229], v[106:109]
	v_mfma_f32_16x16x32_bf16 v[102:105], v[144:147], v[234:237], v[102:105]
	v_mfma_f32_16x16x32_bf16 v[98:101], v[172:175], v[234:237], v[98:101]
	v_mfma_f32_16x16x32_bf16 v[62:65], v[190:193], v[206:209], v[62:65]
	v_mfma_f32_16x16x32_bf16 v[58:61], v[198:201], v[206:209], v[58:61]
	v_mfma_f32_16x16x32_bf16 v[54:57], v[190:193], v[214:217], v[54:57]
	v_mfma_f32_16x16x32_bf16 v[50:53], v[198:201], v[214:217], v[50:53]
	v_mfma_f32_16x16x32_bf16 v[46:49], v[190:193], v[222:225], v[46:49]
	v_mfma_f32_16x16x32_bf16 v[42:45], v[198:201], v[222:225], v[42:45]
	v_mfma_f32_16x16x32_bf16 v[38:41], v[190:193], v[230:233], v[38:41]
	v_mfma_f32_16x16x32_bf16 v[34:37], v[198:201], v[230:233], v[34:37]
	v_mfma_f32_16x16x32_bf16 v[62:65], v[194:197], v[210:213], v[62:65]
	v_mfma_f32_16x16x32_bf16 v[58:61], v[202:205], v[210:213], v[58:61]
	v_mfma_f32_16x16x32_bf16 v[54:57], v[194:197], v[218:221], v[54:57]
	v_mfma_f32_16x16x32_bf16 v[50:53], v[202:205], v[218:221], v[50:53]
	v_mfma_f32_16x16x32_bf16 v[46:49], v[194:197], v[226:229], v[46:49]
	v_mfma_f32_16x16x32_bf16 v[42:45], v[202:205], v[226:229], v[42:45]
	v_mfma_f32_16x16x32_bf16 v[38:41], v[194:197], v[234:237], v[38:41]
	v_mfma_f32_16x16x32_bf16 v[34:37], v[202:205], v[234:237], v[34:37]
	s_barrier
	s_add_i32 s3, s3, s11
	v_lshl_add_u64 v[176:177], v[176:177], 0, s[70:71]
	s_mov_b32 m0, s3
	ds_read_b128 v[206:209], v166 offset:49152
	ds_read_b128 v[210:213], v166 offset:50176
	ds_read_b128 v[214:217], v166 offset:51200
	ds_read_b128 v[218:221], v166 offset:52224
	ds_read_b128 v[222:225], v166 offset:53248
	ds_read_b128 v[226:229], v166 offset:54272
	ds_read_b128 v[230:233], v166 offset:55296
	ds_read_b128 v[234:237], v166 offset:56320
	global_load_lds_dwordx4 v[176:177], off
	s_add_i32 m0, s3, 0x2000
	s_add_u32 s0, s0, 0x80080
	v_lshl_add_u64 v[176:177], v[238:239], 0, s[70:71]
	s_addc_u32 s1, s1, 0
	s_add_i32 s3, s6, s11
	global_load_lds_dwordx4 v[176:177], off
	s_mov_b32 m0, s3
	s_nop 0
	global_load_lds_dwordx4 v4, s[0:1]
	s_add_i32 m0, s3, 0x2000
	s_nop 0
	global_load_lds_dwordx4 v134, s[0:1]
	v_lshl_add_u64 v[176:177], v[240:241], 0, s[70:71]
	s_mov_b32 m0, s34
	s_nop 0
	global_load_lds_dwordx4 v[176:177], off
	v_lshl_add_u64 v[176:177], v[242:243], 0, s[70:71]
	s_mov_b32 m0, s35
	s_nop 0
	global_load_lds_dwordx4 v[176:177], off
	s_waitcnt vmcnt(8)
	s_waitcnt lgkmcnt(0)
	s_barrier
	s_waitcnt lgkmcnt(0)
	v_mfma_f32_16x16x32_bf16 v[94:97], v[140:143], v[206:209], v[94:97]
	v_mfma_f32_16x16x32_bf16 v[90:93], v[148:151], v[206:209], v[90:93]
	v_mfma_f32_16x16x32_bf16 v[86:89], v[140:143], v[214:217], v[86:89]
	v_mfma_f32_16x16x32_bf16 v[82:85], v[148:151], v[214:217], v[82:85]
	v_mfma_f32_16x16x32_bf16 v[78:81], v[140:143], v[222:225], v[78:81]
	v_mfma_f32_16x16x32_bf16 v[74:77], v[148:151], v[222:225], v[74:77]
	v_mfma_f32_16x16x32_bf16 v[70:73], v[140:143], v[230:233], v[70:73]
	v_mfma_f32_16x16x32_bf16 v[66:69], v[148:151], v[230:233], v[66:69]
	v_mfma_f32_16x16x32_bf16 v[94:97], v[144:147], v[210:213], v[94:97]
	v_mfma_f32_16x16x32_bf16 v[90:93], v[172:175], v[210:213], v[90:93]
	v_mfma_f32_16x16x32_bf16 v[86:89], v[144:147], v[218:221], v[86:89]
	v_mfma_f32_16x16x32_bf16 v[82:85], v[172:175], v[218:221], v[82:85]
	v_mfma_f32_16x16x32_bf16 v[78:81], v[144:147], v[226:229], v[78:81]
	v_mfma_f32_16x16x32_bf16 v[74:77], v[172:175], v[226:229], v[74:77]
	v_mfma_f32_16x16x32_bf16 v[70:73], v[144:147], v[234:237], v[70:73]
	v_mfma_f32_16x16x32_bf16 v[66:69], v[172:175], v[234:237], v[66:69]
	v_mfma_f32_16x16x32_bf16 v[30:33], v[190:193], v[206:209], v[30:33]
	v_mfma_f32_16x16x32_bf16 v[26:29], v[198:201], v[206:209], v[26:29]
	v_mfma_f32_16x16x32_bf16 v[22:25], v[190:193], v[214:217], v[22:25]
	v_mfma_f32_16x16x32_bf16 v[18:21], v[198:201], v[214:217], v[18:21]
	v_mfma_f32_16x16x32_bf16 v[14:17], v[190:193], v[222:225], v[14:17]
	v_mfma_f32_16x16x32_bf16 v[10:13], v[198:201], v[222:225], v[10:13]
	v_mfma_f32_16x16x32_bf16 v[6:9], v[190:193], v[230:233], v[6:9]
	v_mfma_f32_16x16x32_bf16 v[0:3], v[198:201], v[230:233], v[0:3]
	v_mfma_f32_16x16x32_bf16 v[30:33], v[194:197], v[210:213], v[30:33]
	v_mfma_f32_16x16x32_bf16 v[26:29], v[202:205], v[210:213], v[26:29]
	v_mfma_f32_16x16x32_bf16 v[22:25], v[194:197], v[218:221], v[22:25]
	v_mfma_f32_16x16x32_bf16 v[18:21], v[202:205], v[218:221], v[18:21]
	v_mfma_f32_16x16x32_bf16 v[14:17], v[194:197], v[226:229], v[14:17]
	v_mfma_f32_16x16x32_bf16 v[10:13], v[202:205], v[226:229], v[10:13]
	v_mfma_f32_16x16x32_bf16 v[6:9], v[194:197], v[234:237], v[6:9]
	v_mfma_f32_16x16x32_bf16 v[0:3], v[202:205], v[234:237], v[0:3]
	s_barrier
	s_add_i32 s28, s28, 2
	s_add_u32 s22, s22, 0x100
	s_addc_u32 s23, s23, 0
	s_add_u32 s9, s9, 0x100
	s_addc_u32 s25, s25, 0
	s_cmp_gt_u32 s28, 29
	s_cbranch_scc0 .LBB0_852
	s_and_b64 vcc, exec, s[48:49]
	s_cbranch_vccz .LBB0_855
	s_barrier
